# GEMM K-loops (all 8): B(0,1) LDS-DMA refill pair moved from phase 1 (6 DMA + 8 ds_read) to phase 2 (2 DMA + 16 ds_read), phase-1 wait vmcnt(8)->(6): balances load-segment issue cost against the partne
# baseline (speedup 1.0000x reference)
; #define PG8_STAGE(bufoff, gbase, voff) do { _Pragma("unroll") for (int _i = 0; _i < 2; ++_i) \
;         __builtin_amdgcn_global_load_lds((const unsigned*)((const char*)(gbase) + (voff)[_i]), (LAS unsigned*)(lds + (bufoff) + ldsw + _i * 8192), 16, 0, 0); } while (0)
; #define PG8_LDA(dst, b, h) do { _Pragma("unroll") for (int m = 0; m < 4; ++m) _Pragma("unroll") for (int k = 0; k < 2; ++k) dst[m][k] = *(const LAS bf16x8*)(lds + PG8_SA(b, h) + aoff + m * 2048 + k * 1024); } while (0)
; #define PG8_LDB(dst, b, h) do { _Pragma("unroll") for (int n = 0; n < 2; ++n) _Pragma("unroll") for (int k = 0; k < 2; ++k) dst[n][k] = *(const LAS bf16x8*)(lds + PG8_SB(b, h) + boff + n * 2048 + k * 1024); } while (0)
; #define PG8_MMA(ai, bj, At, Bt) do { __builtin_amdgcn_s_setprio(1); _Pragma("unroll") for (int m = 0; m < 4; ++m) _Pragma("unroll") for (int n = 0; n < 2; ++n) _Pragma("unroll") for (int k = 0; k < 2; ++k) \
;         acc[ai][bj][m][n] = __builtin_amdgcn_mfma_f32_16x16x32_bf16(Bt[n][k], At[m][k], acc[ai][bj][m][n], 0, 0, 0); __builtin_amdgcn_s_setprio(0); } while (0)
; #define PG8_WAIT_V(n) asm volatile("s_waitcnt vmcnt(" #n ")" ::: "memory")
; #define PG8_WAIT_L(n) asm volatile("s_waitcnt lgkmcnt(" #n ")" ::: "memory")
; #define PG8_BAR __builtin_amdgcn_s_barrier()
; #define PG8_SCHED __builtin_amdgcn_sched_barrier(0)
; template <class Epi>
; __device__ __forceinline__ void gemm_phase(LAS unsigned char* lds, const int tid, const Gemm g, const StaticOrder& S, const Epi& E) {
;     ...
;         for (int t = 0; t < nt; t += 2) {
;             const bool last = (t == nt - 2);
;             const char* a1 = cA + (size_t)(t + 1) * kstep;
;             const char* a2 = last ? nA : cA + (size_t)(t + 2) * kstep; const char* b2 = last ? nB : cB + (size_t)(t + 2) * kstep;
;             const char* a3 = a2 + kstep; const char* b3 = b2 + kstep;
;             PG8_LDB(B0, 0, 0); PG8_LDB(B1, 0, 1); PG8_SCHED; PG8_LDA(At, 0, 0); PG8_STAGE(PG8_SA(1, 1), a1 + hstepA, voffA);
;             PG8_WAIT_V(8); PG8_WAIT_L(0); PG8_BAR; PG8_MMA(0, 0, At, B0); PG8_MMA(0, 1, At, B1); PG8_BAR; PG8_SCHED;
;             PG8_LDA(At, 0, 1); PG8_STAGE(PG8_SB(0, 0), b2, voffB); PG8_STAGE(PG8_SB(0, 1), b2 + hstepB, voffB); PG8_STAGE(PG8_SA(0, 0), a2, voffA);
;             PG8_WAIT_V(8); PG8_WAIT_L(0); PG8_BAR; PG8_MMA(1, 0, At, B0); PG8_MMA(1, 1, At, B1); PG8_BAR; PG8_SCHED;
.LBB0_414:
	s_add_u32 s10, s68, 0xfffc0080
	s_addc_u32 s11, s69, -1
	s_add_i32 s17, 0, 0x10000
	s_cmp_eq_u32 s16, 12
	s_cselect_b32 s73, s7, s11
	s_cselect_b32 s72, s67, s10
	s_cselect_b32 s71, s5, s76
	s_cselect_b32 s70, vcc_lo, vcc_hi
	s_add_i32 s0, 0, 0x14000
	v_add_u32_e32 v70, s17, v202
	v_add_u32_e32 v160, s0, v202
	ds_read_b128 v[50:53], v70
	ds_read_b128 v[54:57], v70 offset:1024
	ds_read_b128 v[66:69], v70 offset:2048
	ds_read_b128 v[70:73], v70 offset:3072
	ds_read_b128 v[156:159], v160
	ds_read_b128 v[170:173], v160 offset:1024
	ds_read_b128 v[174:177], v160 offset:2048
	ds_read_b128 v[178:181], v160 offset:3072
	v_lshl_add_u64 v[160:161], s[68:69], 0, v[152:153]
	s_add_i32 m0, s83, 0xc000
	ds_read_b128 v[216:219], v215
	ds_read_b128 v[220:223], v215 offset:1024
	ds_read_b128 v[224:227], v215 offset:2048
	ds_read_b128 v[228:231], v215 offset:3072
	ds_read_b128 v[232:235], v215 offset:4096
	ds_read_b128 v[236:239], v215 offset:5120
	ds_read_b128 v[240:243], v215 offset:6144
	ds_read_b128 v[244:247], v215 offset:7168
	global_load_lds_dwordx4 v[160:161], off
	v_lshl_add_u64 v[160:161], s[68:69], 0, v[154:155]
	s_add_i32 m0, s83, 0xe000
	s_nop 0
	global_load_lds_dwordx4 v[160:161], off
	s_waitcnt vmcnt(8)
	s_waitcnt lgkmcnt(0)
	s_barrier
	s_setprio 1
	s_waitcnt lgkmcnt(0)
	v_mfma_f32_16x16x32_bf16 v[142:145], v[50:53], v[216:219], v[142:145]
	v_mfma_f32_16x16x32_bf16 v[138:141], v[66:69], v[216:219], v[138:141]
	v_mfma_f32_16x16x32_bf16 v[126:129], v[50:53], v[224:227], v[126:129]
	v_mfma_f32_16x16x32_bf16 v[122:125], v[66:69], v[224:227], v[122:125]
	v_mfma_f32_16x16x32_bf16 v[110:113], v[50:53], v[232:235], v[110:113]
	v_mfma_f32_16x16x32_bf16 v[106:109], v[66:69], v[232:235], v[106:109]
	v_mfma_f32_16x16x32_bf16 v[94:97], v[50:53], v[240:243], v[94:97]
	v_mfma_f32_16x16x32_bf16 v[90:93], v[66:69], v[240:243], v[90:93]
	v_mfma_f32_16x16x32_bf16 v[142:145], v[54:57], v[220:223], v[142:145]
	v_mfma_f32_16x16x32_bf16 v[138:141], v[70:73], v[220:223], v[138:141]
	v_mfma_f32_16x16x32_bf16 v[126:129], v[54:57], v[228:231], v[126:129]
	v_mfma_f32_16x16x32_bf16 v[122:125], v[70:73], v[228:231], v[122:125]
	v_mfma_f32_16x16x32_bf16 v[110:113], v[54:57], v[236:239], v[110:113]
	v_mfma_f32_16x16x32_bf16 v[106:109], v[70:73], v[236:239], v[106:109]
	v_mfma_f32_16x16x32_bf16 v[94:97], v[54:57], v[244:247], v[94:97]
	v_mfma_f32_16x16x32_bf16 v[90:93], v[70:73], v[244:247], v[90:93]
	s_setprio 0
	s_setprio 1
	v_mfma_f32_16x16x32_bf16 v[134:137], v[156:159], v[216:219], v[134:137]
	v_mfma_f32_16x16x32_bf16 v[130:133], v[174:177], v[216:219], v[130:133]
	v_mfma_f32_16x16x32_bf16 v[118:121], v[156:159], v[224:227], v[118:121]
	v_mfma_f32_16x16x32_bf16 v[114:117], v[174:177], v[224:227], v[114:117]
	v_mfma_f32_16x16x32_bf16 v[102:105], v[156:159], v[232:235], v[102:105]
	v_mfma_f32_16x16x32_bf16 v[98:101], v[174:177], v[232:235], v[98:101]
	v_mfma_f32_16x16x32_bf16 v[86:89], v[156:159], v[240:243], v[86:89]
	v_mfma_f32_16x16x32_bf16 v[82:85], v[174:177], v[240:243], v[82:85]
	v_mfma_f32_16x16x32_bf16 v[134:137], v[170:173], v[220:223], v[134:137]
	v_mfma_f32_16x16x32_bf16 v[130:133], v[178:181], v[220:223], v[130:133]
	v_mfma_f32_16x16x32_bf16 v[118:121], v[170:173], v[228:231], v[118:121]
	v_mfma_f32_16x16x32_bf16 v[114:117], v[178:181], v[228:231], v[114:117]
	v_mfma_f32_16x16x32_bf16 v[102:105], v[170:173], v[236:239], v[102:105]
	v_mfma_f32_16x16x32_bf16 v[98:101], v[178:181], v[236:239], v[98:101]
	v_mfma_f32_16x16x32_bf16 v[86:89], v[170:173], v[244:247], v[86:89]
	v_mfma_f32_16x16x32_bf16 v[82:85], v[178:181], v[244:247], v[82:85]
	s_setprio 0
	s_barrier
	s_add_i32 s1, s17, s82
	v_lshl_add_u64 v[160:161], s[70:71], 0, v[0:1]
	s_mov_b32 m0, s1
	ds_read_b128 v[216:219], v215 offset:16384
	ds_read_b128 v[220:223], v215 offset:17408
	ds_read_b128 v[224:227], v215 offset:18432
	ds_read_b128 v[228:231], v215 offset:19456
	ds_read_b128 v[232:235], v215 offset:20480
	ds_read_b128 v[236:239], v215 offset:21504
	ds_read_b128 v[240:243], v215 offset:22528
	ds_read_b128 v[244:247], v215 offset:23552
	global_load_lds_dwordx4 v[160:161], off
	s_add_i32 m0, s1, 0x2000
	s_add_u32 s10, s70, 0x40000
	v_lshl_add_u64 v[182:183], s[70:71], 0, v[146:147]
	s_addc_u32 s11, s71, 0
	s_add_i32 s0, s0, s82
	global_load_lds_dwordx4 v[182:183], off
	v_lshl_add_u64 v[162:163], s[10:11], 0, v[0:1]
	s_mov_b32 m0, s0
	v_lshl_add_u64 v[164:165], s[72:73], 0, v[150:151]
	v_lshl_add_u64 v[162:163], s[10:11], 0, v[146:147]
	s_add_i32 m0, s0, 0x2000
	s_nop 0
	v_lshl_add_u64 v[162:163], s[72:73], 0, v[148:149]
	s_mov_b32 m0, s83
	s_nop 0
	global_load_lds_dwordx4 v[162:163], off
	s_mov_b32 m0, s88
	s_nop 0
	global_load_lds_dwordx4 v[164:165], off
	s_waitcnt vmcnt(6)
	s_waitcnt lgkmcnt(0)
	s_barrier
; #define PG8_STAGE(bufoff, gbase, voff) do { _Pragma("unroll") for (int _i = 0; _i < 2; ++_i) \
;         __builtin_amdgcn_global_load_lds((const unsigned*)((const char*)(gbase) + (voff)[_i]), (LAS unsigned*)(lds + (bufoff) + ldsw + _i * 8192), 16, 0, 0); } while (0)
; #define PG8_LDA(dst, b, h) do { _Pragma("unroll") for (int m = 0; m < 4; ++m) _Pragma("unroll") for (int k = 0; k < 2; ++k) dst[m][k] = *(const LAS bf16x8*)(lds + PG8_SA(b, h) + aoff + m * 2048 + k * 1024); } while (0)
; #define PG8_LDB(dst, b, h) do { _Pragma("unroll") for (int n = 0; n < 2; ++n) _Pragma("unroll") for (int k = 0; k < 2; ++k) dst[n][k] = *(const LAS bf16x8*)(lds + PG8_SB(b, h) + boff + n * 2048 + k * 1024); } while (0)
; #define PG8_MMA(ai, bj, At, Bt) do { __builtin_amdgcn_s_setprio(1); _Pragma("unroll") for (int m = 0; m < 4; ++m) _Pragma("unroll") for (int n = 0; n < 2; ++n) _Pragma("unroll") for (int k = 0; k < 2; ++k) \
;         acc[ai][bj][m][n] = __builtin_amdgcn_mfma_f32_16x16x32_bf16(Bt[n][k], At[m][k], acc[ai][bj][m][n], 0, 0, 0); __builtin_amdgcn_s_setprio(0); } while (0)
; #define PG8_WAIT_V(n) asm volatile("s_waitcnt vmcnt(" #n ")" ::: "memory")
; #define PG8_WAIT_L(n) asm volatile("s_waitcnt lgkmcnt(" #n ")" ::: "memory")
; #define PG8_BAR __builtin_amdgcn_s_barrier()
; #define PG8_SCHED __builtin_amdgcn_sched_barrier(0)
; template <class Epi>
; __device__ __forceinline__ void gemm_phase(LAS unsigned char* lds, const int tid, const Gemm g, const StaticOrder& S, const Epi& E) {
;     ...
;             PG8_WAIT_V(8); PG8_WAIT_L(0); PG8_BAR; PG8_MMA(1, 0, At, B0); PG8_MMA(1, 1, At, B1); PG8_BAR; PG8_SCHED;
;             PG8_LDB(B0, 1, 0); PG8_LDB(B1, 1, 1); PG8_SCHED; PG8_LDA(At, 1, 0); PG8_STAGE(PG8_SA(0, 1), a2 + hstepA, voffA);
;             PG8_WAIT_V(8); PG8_WAIT_L(0); PG8_BAR; PG8_MMA(0, 0, At, B0); PG8_MMA(0, 1, At, B1); PG8_BAR; PG8_SCHED;
	s_setprio 1
	s_waitcnt lgkmcnt(0)
	v_mfma_f32_16x16x32_bf16 v[78:81], v[50:53], v[216:219], v[78:81]
	v_mfma_f32_16x16x32_bf16 v[74:77], v[66:69], v[216:219], v[74:77]
	v_mfma_f32_16x16x32_bf16 v[46:49], v[50:53], v[224:227], v[46:49]
	v_mfma_f32_16x16x32_bf16 v[42:45], v[66:69], v[224:227], v[42:45]
	v_mfma_f32_16x16x32_bf16 v[30:33], v[50:53], v[232:235], v[30:33]
	v_mfma_f32_16x16x32_bf16 v[26:29], v[66:69], v[232:235], v[26:29]
	v_mfma_f32_16x16x32_bf16 v[14:17], v[50:53], v[240:243], v[14:17]
	v_mfma_f32_16x16x32_bf16 v[10:13], v[66:69], v[240:243], v[10:13]
	v_mfma_f32_16x16x32_bf16 v[78:81], v[54:57], v[220:223], v[78:81]
	v_mfma_f32_16x16x32_bf16 v[74:77], v[70:73], v[220:223], v[74:77]
	v_mfma_f32_16x16x32_bf16 v[46:49], v[54:57], v[228:231], v[46:49]
	v_mfma_f32_16x16x32_bf16 v[42:45], v[70:73], v[228:231], v[42:45]
	v_mfma_f32_16x16x32_bf16 v[30:33], v[54:57], v[236:239], v[30:33]
	v_mfma_f32_16x16x32_bf16 v[26:29], v[70:73], v[236:239], v[26:29]
	v_mfma_f32_16x16x32_bf16 v[14:17], v[54:57], v[244:247], v[14:17]
	v_mfma_f32_16x16x32_bf16 v[10:13], v[70:73], v[244:247], v[10:13]
	s_setprio 0
	s_setprio 1
	v_mfma_f32_16x16x32_bf16 v[38:41], v[156:159], v[224:227], v[38:41]
	v_mfma_f32_16x16x32_bf16 v[34:37], v[174:177], v[224:227], v[34:37]
	v_mfma_f32_16x16x32_bf16 v[22:25], v[156:159], v[232:235], v[22:25]
	v_mfma_f32_16x16x32_bf16 v[18:21], v[174:177], v[232:235], v[18:21]
	v_mfma_f32_16x16x32_bf16 v[6:9], v[156:159], v[240:243], v[6:9]
	v_mfma_f32_16x16x32_bf16 v[2:5], v[174:177], v[240:243], v[2:5]
	v_mfma_f32_16x16x32_bf16 v[50:53], v[156:159], v[216:219], v[62:65]
	v_mfma_f32_16x16x32_bf16 v[54:57], v[174:177], v[216:219], v[58:61]
	v_mfma_f32_16x16x32_bf16 v[38:41], v[170:173], v[228:231], v[38:41]
	v_mfma_f32_16x16x32_bf16 v[34:37], v[178:181], v[228:231], v[34:37]
	v_mfma_f32_16x16x32_bf16 v[22:25], v[170:173], v[236:239], v[22:25]
	v_mfma_f32_16x16x32_bf16 v[18:21], v[178:181], v[236:239], v[18:21]
	v_mfma_f32_16x16x32_bf16 v[6:9], v[170:173], v[244:247], v[6:9]
	v_mfma_f32_16x16x32_bf16 v[2:5], v[178:181], v[244:247], v[2:5]
	v_mfma_f32_16x16x32_bf16 v[50:53], v[170:173], v[220:223], v[50:53]
	v_mfma_f32_16x16x32_bf16 v[54:57], v[178:181], v[220:223], v[54:57]
	s_setprio 0
	s_barrier
	s_add_i32 s0, 0, 0x18000
	s_add_i32 s1, 0, 0x1c000
	v_add_u32_e32 v70, s0, v202
	v_add_u32_e32 v178, s1, v202
	ds_read_b128 v[58:61], v70
	ds_read_b128 v[62:65], v70 offset:1024
	ds_read_b128 v[66:69], v70 offset:2048
	ds_read_b128 v[70:73], v70 offset:3072
	ds_read_b128 v[156:159], v178
	ds_read_b128 v[170:173], v178 offset:1024
	ds_read_b128 v[174:177], v178 offset:2048
	ds_read_b128 v[178:181], v178 offset:3072
	s_add_u32 s100, s70, 0x40000
	s_addc_u32 s101, s71, 0
	v_lshl_add_u64 v[206:207], s[100:101], 0, v[0:1]
	s_add_i32 m0, s82, 0x14000
	s_nop 0
	global_load_lds_dwordx4 v[206:207], off
	v_lshl_add_u64 v[206:207], s[100:101], 0, v[146:147]
	s_add_i32 m0, s82, 0x16000
	s_nop 0
	global_load_lds_dwordx4 v[206:207], off
	s_add_u32 s10, s72, 0x40000
	s_addc_u32 s11, s73, 0
	s_mov_b32 m0, s89
	v_lshl_add_u64 v[206:207], s[10:11], 0, v[148:149]
	ds_read_b128 v[216:219], v215 offset:32768
	ds_read_b128 v[220:223], v215 offset:33792
	ds_read_b128 v[224:227], v215 offset:34816
	ds_read_b128 v[228:231], v215 offset:35840
	ds_read_b128 v[232:235], v215 offset:36864
	ds_read_b128 v[236:239], v215 offset:37888
	ds_read_b128 v[240:243], v215 offset:38912
	ds_read_b128 v[244:247], v215 offset:39936
	global_load_lds_dwordx4 v[206:207], off
	v_lshl_add_u64 v[206:207], s[10:11], 0, v[150:151]
	s_mov_b32 m0, s92
	s_nop 0
	global_load_lds_dwordx4 v[206:207], off
	s_waitcnt vmcnt(8)
	s_waitcnt lgkmcnt(0)
	s_barrier
	s_setprio 1
	s_waitcnt lgkmcnt(0)
	v_mfma_f32_16x16x32_bf16 v[142:145], v[58:61], v[216:219], v[142:145]
	v_mfma_f32_16x16x32_bf16 v[138:141], v[66:69], v[216:219], v[138:141]
	v_mfma_f32_16x16x32_bf16 v[126:129], v[58:61], v[224:227], v[126:129]
	v_mfma_f32_16x16x32_bf16 v[122:125], v[66:69], v[224:227], v[122:125]
	v_mfma_f32_16x16x32_bf16 v[110:113], v[58:61], v[232:235], v[110:113]
	v_mfma_f32_16x16x32_bf16 v[106:109], v[66:69], v[232:235], v[106:109]
	v_mfma_f32_16x16x32_bf16 v[94:97], v[58:61], v[240:243], v[94:97]
	v_mfma_f32_16x16x32_bf16 v[90:93], v[66:69], v[240:243], v[90:93]
	v_mfma_f32_16x16x32_bf16 v[142:145], v[62:65], v[220:223], v[142:145]
	v_mfma_f32_16x16x32_bf16 v[138:141], v[70:73], v[220:223], v[138:141]
	v_mfma_f32_16x16x32_bf16 v[126:129], v[62:65], v[228:231], v[126:129]
	v_mfma_f32_16x16x32_bf16 v[122:125], v[70:73], v[228:231], v[122:125]
	v_mfma_f32_16x16x32_bf16 v[110:113], v[62:65], v[236:239], v[110:113]
	v_mfma_f32_16x16x32_bf16 v[106:109], v[70:73], v[236:239], v[106:109]
	v_mfma_f32_16x16x32_bf16 v[94:97], v[62:65], v[244:247], v[94:97]
	v_mfma_f32_16x16x32_bf16 v[90:93], v[70:73], v[244:247], v[90:93]
	s_setprio 0
	s_setprio 1
	v_mfma_f32_16x16x32_bf16 v[134:137], v[156:159], v[216:219], v[134:137]
	v_mfma_f32_16x16x32_bf16 v[130:133], v[174:177], v[216:219], v[130:133]
	v_mfma_f32_16x16x32_bf16 v[118:121], v[156:159], v[224:227], v[118:121]
	v_mfma_f32_16x16x32_bf16 v[114:117], v[174:177], v[224:227], v[114:117]
	v_mfma_f32_16x16x32_bf16 v[102:105], v[156:159], v[232:235], v[102:105]
	v_mfma_f32_16x16x32_bf16 v[98:101], v[174:177], v[232:235], v[98:101]
	v_mfma_f32_16x16x32_bf16 v[86:89], v[156:159], v[240:243], v[86:89]
	v_mfma_f32_16x16x32_bf16 v[82:85], v[174:177], v[240:243], v[82:85]
	v_mfma_f32_16x16x32_bf16 v[134:137], v[170:173], v[220:223], v[134:137]
	v_mfma_f32_16x16x32_bf16 v[130:133], v[178:181], v[220:223], v[130:133]
	v_mfma_f32_16x16x32_bf16 v[118:121], v[170:173], v[228:231], v[118:121]
	v_mfma_f32_16x16x32_bf16 v[114:117], v[178:181], v[228:231], v[114:117]
	v_mfma_f32_16x16x32_bf16 v[102:105], v[170:173], v[236:239], v[102:105]
	v_mfma_f32_16x16x32_bf16 v[98:101], v[178:181], v[236:239], v[98:101]
	v_mfma_f32_16x16x32_bf16 v[86:89], v[170:173], v[244:247], v[86:89]
	v_mfma_f32_16x16x32_bf16 v[82:85], v[178:181], v[244:247], v[82:85]
	s_setprio 0
	s_barrier
; #define PG8_STAGE(bufoff, gbase, voff) do { _Pragma("unroll") for (int _i = 0; _i < 2; ++_i) \
;         __builtin_amdgcn_global_load_lds((const unsigned*)((const char*)(gbase) + (voff)[_i]), (LAS unsigned*)(lds + (bufoff) + ldsw + _i * 8192), 16, 0, 0); } while (0)
; #define PG8_LDA(dst, b, h) do { _Pragma("unroll") for (int m = 0; m < 4; ++m) _Pragma("unroll") for (int k = 0; k < 2; ++k) dst[m][k] = *(const LAS bf16x8*)(lds + PG8_SA(b, h) + aoff + m * 2048 + k * 1024); } while (0)
; #define PG8_MMA(ai, bj, At, Bt) do { __builtin_amdgcn_s_setprio(1); _Pragma("unroll") for (int m = 0; m < 4; ++m) _Pragma("unroll") for (int n = 0; n < 2; ++n) _Pragma("unroll") for (int k = 0; k < 2; ++k) \
;         acc[ai][bj][m][n] = __builtin_amdgcn_mfma_f32_16x16x32_bf16(Bt[n][k], At[m][k], acc[ai][bj][m][n], 0, 0, 0); __builtin_amdgcn_s_setprio(0); } while (0)
; #define PG8_WAIT_V(n) asm volatile("s_waitcnt vmcnt(" #n ")" ::: "memory")
; #define PG8_WAIT_L(n) asm volatile("s_waitcnt lgkmcnt(" #n ")" ::: "memory")
; #define PG8_BAR __builtin_amdgcn_s_barrier()
; #define PG8_SCHED __builtin_amdgcn_sched_barrier(0)
; template <class Epi>
; __device__ __forceinline__ void gemm_phase(LAS unsigned char* lds, const int tid, const Gemm g, const StaticOrder& S, const Epi& E) {
;     ...
;             PG8_LDA(At, 1, 1); PG8_STAGE(PG8_SB(1, 0), b3, voffB); PG8_STAGE(PG8_SB(1, 1), b3 + hstepB, voffB); PG8_STAGE(PG8_SA(1, 0), a3, voffA);
;             PG8_WAIT_V(8); PG8_WAIT_L(0); PG8_BAR; PG8_MMA(1, 0, At, B0); PG8_MMA(1, 1, At, B1); PG8_BAR; PG8_SCHED;
;         }
;         if (wr == 0) PG8_BAR;
	s_add_i32 s0, s0, s82
	v_lshl_add_u64 v[160:161], v[160:161], 0, s[36:37]
	s_mov_b32 m0, s0
	ds_read_b128 v[216:219], v215 offset:49152
	ds_read_b128 v[220:223], v215 offset:50176
	ds_read_b128 v[224:227], v215 offset:51200
	ds_read_b128 v[228:231], v215 offset:52224
	ds_read_b128 v[232:235], v215 offset:53248
	ds_read_b128 v[236:239], v215 offset:54272
	ds_read_b128 v[240:243], v215 offset:55296
	ds_read_b128 v[244:247], v215 offset:56320
	global_load_lds_dwordx4 v[160:161], off
	s_add_i32 m0, s0, 0x2000
	s_add_u32 s10, s70, 0x40080
	v_lshl_add_u64 v[160:161], v[182:183], 0, s[36:37]
	s_addc_u32 s11, s71, 0
	s_add_i32 s0, s1, s82
	global_load_lds_dwordx4 v[160:161], off
	v_lshl_add_u64 v[160:161], s[10:11], 0, v[0:1]
	s_mov_b32 m0, s0
	s_nop 0
	global_load_lds_dwordx4 v[160:161], off
	v_lshl_add_u64 v[160:161], s[10:11], 0, v[146:147]
	s_add_i32 m0, s0, 0x2000
	s_nop 0
	global_load_lds_dwordx4 v[160:161], off
	v_lshl_add_u64 v[160:161], v[162:163], 0, s[36:37]
	s_mov_b32 m0, s93
	s_nop 0
	global_load_lds_dwordx4 v[160:161], off
	v_lshl_add_u64 v[160:161], v[164:165], 0, s[36:37]
	s_mov_b32 m0, s74
	s_nop 0
	global_load_lds_dwordx4 v[160:161], off
	s_waitcnt vmcnt(8)
	s_waitcnt lgkmcnt(0)
	s_barrier
	s_setprio 1
	s_waitcnt lgkmcnt(0)
	v_mfma_f32_16x16x32_bf16 v[78:81], v[58:61], v[216:219], v[78:81]
	v_mfma_f32_16x16x32_bf16 v[74:77], v[66:69], v[216:219], v[74:77]
	v_mfma_f32_16x16x32_bf16 v[46:49], v[58:61], v[224:227], v[46:49]
	v_mfma_f32_16x16x32_bf16 v[42:45], v[66:69], v[224:227], v[42:45]
	v_mfma_f32_16x16x32_bf16 v[30:33], v[58:61], v[232:235], v[30:33]
	v_mfma_f32_16x16x32_bf16 v[26:29], v[66:69], v[232:235], v[26:29]
	v_mfma_f32_16x16x32_bf16 v[14:17], v[58:61], v[240:243], v[14:17]
	v_mfma_f32_16x16x32_bf16 v[10:13], v[66:69], v[240:243], v[10:13]
	v_mfma_f32_16x16x32_bf16 v[78:81], v[62:65], v[220:223], v[78:81]
	v_mfma_f32_16x16x32_bf16 v[74:77], v[70:73], v[220:223], v[74:77]
	v_mfma_f32_16x16x32_bf16 v[46:49], v[62:65], v[228:231], v[46:49]
	v_mfma_f32_16x16x32_bf16 v[42:45], v[70:73], v[228:231], v[42:45]
	v_mfma_f32_16x16x32_bf16 v[30:33], v[62:65], v[236:239], v[30:33]
	v_mfma_f32_16x16x32_bf16 v[26:29], v[70:73], v[236:239], v[26:29]
	v_mfma_f32_16x16x32_bf16 v[14:17], v[62:65], v[244:247], v[14:17]
	v_mfma_f32_16x16x32_bf16 v[10:13], v[70:73], v[244:247], v[10:13]
	s_setprio 0
	s_setprio 1
	v_mfma_f32_16x16x32_bf16 v[50:53], v[156:159], v[216:219], v[50:53]
	v_mfma_f32_16x16x32_bf16 v[62:65], v[170:173], v[220:223], v[50:53]
	v_mfma_f32_16x16x32_bf16 v[50:53], v[174:177], v[216:219], v[54:57]
	v_mfma_f32_16x16x32_bf16 v[38:41], v[156:159], v[224:227], v[38:41]
	v_mfma_f32_16x16x32_bf16 v[34:37], v[174:177], v[224:227], v[34:37]
	v_mfma_f32_16x16x32_bf16 v[22:25], v[156:159], v[232:235], v[22:25]
	v_mfma_f32_16x16x32_bf16 v[18:21], v[174:177], v[232:235], v[18:21]
	v_mfma_f32_16x16x32_bf16 v[6:9], v[156:159], v[240:243], v[6:9]
	v_mfma_f32_16x16x32_bf16 v[2:5], v[174:177], v[240:243], v[2:5]
	v_mfma_f32_16x16x32_bf16 v[58:61], v[178:181], v[220:223], v[50:53]
	v_mfma_f32_16x16x32_bf16 v[38:41], v[170:173], v[228:231], v[38:41]
	v_mfma_f32_16x16x32_bf16 v[34:37], v[178:181], v[228:231], v[34:37]
	v_mfma_f32_16x16x32_bf16 v[22:25], v[170:173], v[236:239], v[22:25]
	v_mfma_f32_16x16x32_bf16 v[18:21], v[178:181], v[236:239], v[18:21]
	v_mfma_f32_16x16x32_bf16 v[6:9], v[170:173], v[244:247], v[6:9]
	v_mfma_f32_16x16x32_bf16 v[2:5], v[178:181], v[244:247], v[2:5]
	s_setprio 0
	s_barrier
	s_add_i32 s16, s16, 2
	s_add_u32 s68, s68, 0x100
	s_addc_u32 s69, s69, 0
	s_add_u32 vcc_hi, vcc_hi, 0x100
	s_addc_u32 s76, s76, 0
	s_cmp_gt_u32 s16, 13
	s_cbranch_scc0 .LBB0_414
	s_and_b64 vcc, exec, s[2:3]
	s_cbranch_vccz .LBB0_417
	s_barrier

; #define PG8_STAGE(bufoff, gbase, voff) do { _Pragma("unroll") for (int _i = 0; _i < 2; ++_i) \
;         __builtin_amdgcn_global_load_lds((const unsigned*)((const char*)(gbase) + (voff)[_i]), (LAS unsigned*)(lds + (bufoff) + ldsw + _i * 8192), 16, 0, 0); } while (0)
; #define PG8_LDA(dst, b, h) do { _Pragma("unroll") for (int m = 0; m < 4; ++m) _Pragma("unroll") for (int k = 0; k < 2; ++k) dst[m][k] = *(const LAS bf16x8*)(lds + PG8_SA(b, h) + aoff + m * 2048 + k * 1024); } while (0)
; #define PG8_LDB(dst, b, h) do { _Pragma("unroll") for (int n = 0; n < 2; ++n) _Pragma("unroll") for (int k = 0; k < 2; ++k) dst[n][k] = *(const LAS bf16x8*)(lds + PG8_SB(b, h) + boff + n * 2048 + k * 1024); } while (0)
; #define PG8_MMA(ai, bj, At, Bt) do { __builtin_amdgcn_s_setprio(1); _Pragma("unroll") for (int m = 0; m < 4; ++m) _Pragma("unroll") for (int n = 0; n < 2; ++n) _Pragma("unroll") for (int k = 0; k < 2; ++k) \
;         acc[ai][bj][m][n] = __builtin_amdgcn_mfma_f32_16x16x32_bf16(Bt[n][k], At[m][k], acc[ai][bj][m][n], 0, 0, 0); __builtin_amdgcn_s_setprio(0); } while (0)
; #define PG8_WAIT_V(n) asm volatile("s_waitcnt vmcnt(" #n ")" ::: "memory")
; #define PG8_WAIT_L(n) asm volatile("s_waitcnt lgkmcnt(" #n ")" ::: "memory")
; #define PG8_BAR __builtin_amdgcn_s_barrier()
; #define PG8_SCHED __builtin_amdgcn_sched_barrier(0)
; template <class Epi>
; __device__ __forceinline__ void gemm_phase(LAS unsigned char* lds, const int tid, const Gemm g, const StaticOrder& S, const Epi& E) {
;     ...
;         for (int t = 0; t < nt; t += 2) {
;             const bool last = (t == nt - 2);
;             const char* a1 = cA + (size_t)(t + 1) * kstep;
;             const char* a2 = last ? nA : cA + (size_t)(t + 2) * kstep; const char* b2 = last ? nB : cB + (size_t)(t + 2) * kstep;
;             const char* a3 = a2 + kstep; const char* b3 = b2 + kstep;
;             PG8_LDB(B0, 0, 0); PG8_LDB(B1, 0, 1); PG8_SCHED; PG8_LDA(At, 0, 0); PG8_STAGE(PG8_SA(1, 1), a1 + hstepA, voffA);
;             PG8_WAIT_V(8); PG8_WAIT_L(0); PG8_BAR; PG8_MMA(0, 0, At, B0); PG8_MMA(0, 1, At, B1); PG8_BAR; PG8_SCHED;
;             PG8_LDA(At, 0, 1); PG8_STAGE(PG8_SB(0, 0), b2, voffB); PG8_STAGE(PG8_SB(0, 1), b2 + hstepB, voffB); PG8_STAGE(PG8_SA(0, 0), a2, voffA);
;             PG8_WAIT_V(8); PG8_WAIT_L(0); PG8_BAR; PG8_MMA(1, 0, At, B0); PG8_MMA(1, 1, At, B1); PG8_BAR; PG8_SCHED;
.LBB0_945:
	s_add_u32 s30, s72, 0xfffc0080
	s_addc_u32 s31, s73, -1
	s_add_i32 s76, 0, 0x10000
	s_cmp_eq_u32 vcc_hi, 12
	s_cselect_b32 s75, s9, s31
	s_cselect_b32 s74, s27, s30
	v_add_u32_e32 v0, s76, v178
	s_cselect_b32 s31, s7, vcc_lo
	s_cselect_b32 s30, s28, s65
	s_add_i32 s0, 0, 0x14000
	ds_read_b128 v[18:21], v0
	ds_read_b128 v[22:25], v0 offset:1024
	ds_read_b128 v[26:29], v0 offset:2048
	ds_read_b128 v[30:33], v0 offset:3072
	v_add_u32_e32 v0, s0, v178
	ds_read_b128 v[170:173], v0
	ds_read_b128 v[174:177], v0 offset:1024
	ds_read_b128 v[190:193], v0 offset:2048
	ds_read_b128 v[194:197], v0 offset:3072
	v_lshl_add_u64 v[162:163], s[72:73], 0, v[158:159]
	s_add_i32 m0, s71, 0xc000
	ds_read_b128 v[198:201], v189
	ds_read_b128 v[210:213], v189 offset:1024
	ds_read_b128 v[214:217], v189 offset:2048
	ds_read_b128 v[218:221], v189 offset:3072
	ds_read_b128 v[222:225], v189 offset:4096
	ds_read_b128 v[226:229], v189 offset:5120
	ds_read_b128 v[230:233], v189 offset:6144
	ds_read_b128 v[234:237], v189 offset:7168
	global_load_lds_dwordx4 v[162:163], off
	v_lshl_add_u64 v[162:163], s[72:73], 0, v[160:161]
	s_add_i32 m0, s71, 0xe000
	s_nop 0
	global_load_lds_dwordx4 v[162:163], off
	s_waitcnt vmcnt(8)
	s_waitcnt lgkmcnt(0)
	s_barrier
	s_setprio 1
	s_waitcnt lgkmcnt(0)
	v_mfma_f32_16x16x32_bf16 v[142:145], v[18:21], v[198:201], v[142:145]
	v_mfma_f32_16x16x32_bf16 v[138:141], v[26:29], v[198:201], v[138:141]
	v_mfma_f32_16x16x32_bf16 v[126:129], v[18:21], v[214:217], v[126:129]
	v_mfma_f32_16x16x32_bf16 v[122:125], v[26:29], v[214:217], v[122:125]
	v_mfma_f32_16x16x32_bf16 v[110:113], v[18:21], v[222:225], v[110:113]
	v_mfma_f32_16x16x32_bf16 v[106:109], v[26:29], v[222:225], v[106:109]
	v_mfma_f32_16x16x32_bf16 v[94:97], v[18:21], v[230:233], v[94:97]
	v_mfma_f32_16x16x32_bf16 v[90:93], v[26:29], v[230:233], v[90:93]
	v_mfma_f32_16x16x32_bf16 v[142:145], v[22:25], v[210:213], v[142:145]
	v_mfma_f32_16x16x32_bf16 v[138:141], v[30:33], v[210:213], v[138:141]
	v_mfma_f32_16x16x32_bf16 v[126:129], v[22:25], v[218:221], v[126:129]
	v_mfma_f32_16x16x32_bf16 v[122:125], v[30:33], v[218:221], v[122:125]
	v_mfma_f32_16x16x32_bf16 v[110:113], v[22:25], v[226:229], v[110:113]
	v_mfma_f32_16x16x32_bf16 v[106:109], v[30:33], v[226:229], v[106:109]
	v_mfma_f32_16x16x32_bf16 v[94:97], v[22:25], v[234:237], v[94:97]
	v_mfma_f32_16x16x32_bf16 v[90:93], v[30:33], v[234:237], v[90:93]
	s_setprio 0
	s_setprio 1
	v_mfma_f32_16x16x32_bf16 v[134:137], v[170:173], v[198:201], v[134:137]
	v_mfma_f32_16x16x32_bf16 v[130:133], v[190:193], v[198:201], v[130:133]
	v_mfma_f32_16x16x32_bf16 v[118:121], v[170:173], v[214:217], v[118:121]
	v_mfma_f32_16x16x32_bf16 v[114:117], v[190:193], v[214:217], v[114:117]
	v_mfma_f32_16x16x32_bf16 v[102:105], v[170:173], v[222:225], v[102:105]
	v_mfma_f32_16x16x32_bf16 v[98:101], v[190:193], v[222:225], v[98:101]
	v_mfma_f32_16x16x32_bf16 v[86:89], v[170:173], v[230:233], v[86:89]
	v_mfma_f32_16x16x32_bf16 v[82:85], v[190:193], v[230:233], v[82:85]
	v_mfma_f32_16x16x32_bf16 v[134:137], v[174:177], v[210:213], v[134:137]
	v_mfma_f32_16x16x32_bf16 v[130:133], v[194:197], v[210:213], v[130:133]
	v_mfma_f32_16x16x32_bf16 v[118:121], v[174:177], v[218:221], v[118:121]
	v_mfma_f32_16x16x32_bf16 v[114:117], v[194:197], v[218:221], v[114:117]
	v_mfma_f32_16x16x32_bf16 v[102:105], v[174:177], v[226:229], v[102:105]
	v_mfma_f32_16x16x32_bf16 v[98:101], v[194:197], v[226:229], v[98:101]
	v_mfma_f32_16x16x32_bf16 v[86:89], v[174:177], v[234:237], v[86:89]
	v_mfma_f32_16x16x32_bf16 v[82:85], v[194:197], v[234:237], v[82:85]
	s_setprio 0
	s_barrier
	s_add_i32 s1, s76, s93
	v_lshl_add_u64 v[162:163], s[30:31], 0, v[150:151]
	s_mov_b32 m0, s1
	ds_read_b128 v[198:201], v189 offset:16384
	ds_read_b128 v[210:213], v189 offset:17408
	ds_read_b128 v[214:217], v189 offset:18432
	ds_read_b128 v[218:221], v189 offset:19456
	ds_read_b128 v[222:225], v189 offset:20480
	ds_read_b128 v[226:229], v189 offset:21504
	ds_read_b128 v[230:233], v189 offset:22528
	ds_read_b128 v[234:237], v189 offset:23552
	global_load_lds_dwordx4 v[162:163], off
	s_add_i32 m0, s1, 0x2000
	s_add_u32 s76, s30, 0x40000
	v_lshl_add_u64 v[164:165], s[30:31], 0, v[154:155]
	s_addc_u32 s77, s31, 0
	s_add_i32 s0, s0, s93
	global_load_lds_dwordx4 v[164:165], off
	v_lshl_add_u64 v[202:203], s[76:77], 0, v[150:151]
	s_mov_b32 m0, s0
	v_lshl_add_u64 v[206:207], s[74:75], 0, v[152:153]
	v_lshl_add_u64 v[202:203], s[76:77], 0, v[154:155]
	s_add_i32 m0, s0, 0x2000
	s_nop 0
	v_lshl_add_u64 v[202:203], s[74:75], 0, v[148:149]
	s_mov_b32 m0, s71
	s_nop 0
	global_load_lds_dwordx4 v[202:203], off
	s_mov_b32 m0, s88
	s_nop 0
	global_load_lds_dwordx4 v[206:207], off
	s_waitcnt vmcnt(6)
	s_waitcnt lgkmcnt(0)
	s_barrier
; #define PG8_STAGE(bufoff, gbase, voff) do { _Pragma("unroll") for (int _i = 0; _i < 2; ++_i) \
;         __builtin_amdgcn_global_load_lds((const unsigned*)((const char*)(gbase) + (voff)[_i]), (LAS unsigned*)(lds + (bufoff) + ldsw + _i * 8192), 16, 0, 0); } while (0)
; #define PG8_LDA(dst, b, h) do { _Pragma("unroll") for (int m = 0; m < 4; ++m) _Pragma("unroll") for (int k = 0; k < 2; ++k) dst[m][k] = *(const LAS bf16x8*)(lds + PG8_SA(b, h) + aoff + m * 2048 + k * 1024); } while (0)
; #define PG8_LDB(dst, b, h) do { _Pragma("unroll") for (int n = 0; n < 2; ++n) _Pragma("unroll") for (int k = 0; k < 2; ++k) dst[n][k] = *(const LAS bf16x8*)(lds + PG8_SB(b, h) + boff + n * 2048 + k * 1024); } while (0)
; #define PG8_MMA(ai, bj, At, Bt) do { __builtin_amdgcn_s_setprio(1); _Pragma("unroll") for (int m = 0; m < 4; ++m) _Pragma("unroll") for (int n = 0; n < 2; ++n) _Pragma("unroll") for (int k = 0; k < 2; ++k) \
;         acc[ai][bj][m][n] = __builtin_amdgcn_mfma_f32_16x16x32_bf16(Bt[n][k], At[m][k], acc[ai][bj][m][n], 0, 0, 0); __builtin_amdgcn_s_setprio(0); } while (0)
; #define PG8_WAIT_V(n) asm volatile("s_waitcnt vmcnt(" #n ")" ::: "memory")
; #define PG8_WAIT_L(n) asm volatile("s_waitcnt lgkmcnt(" #n ")" ::: "memory")
; #define PG8_BAR __builtin_amdgcn_s_barrier()
; #define PG8_SCHED __builtin_amdgcn_sched_barrier(0)
; template <class Epi>
; __device__ __forceinline__ void gemm_phase(LAS unsigned char* lds, const int tid, const Gemm g, const StaticOrder& S, const Epi& E) {
;     ...
;             PG8_WAIT_V(8); PG8_WAIT_L(0); PG8_BAR; PG8_MMA(1, 0, At, B0); PG8_MMA(1, 1, At, B1); PG8_BAR; PG8_SCHED;
;             PG8_LDB(B0, 1, 0); PG8_LDB(B1, 1, 1); PG8_SCHED; PG8_LDA(At, 1, 0); PG8_STAGE(PG8_SA(0, 1), a2 + hstepA, voffA);
;             PG8_WAIT_V(8); PG8_WAIT_L(0); PG8_BAR; PG8_MMA(0, 0, At, B0); PG8_MMA(0, 1, At, B1); PG8_BAR; PG8_SCHED;
	s_setprio 1
	s_waitcnt lgkmcnt(0)
	v_mfma_f32_16x16x32_bf16 v[78:81], v[18:21], v[198:201], v[78:81]
	v_mfma_f32_16x16x32_bf16 v[74:77], v[26:29], v[198:201], v[74:77]
	v_mfma_f32_16x16x32_bf16 v[62:65], v[18:21], v[214:217], v[62:65]
	v_mfma_f32_16x16x32_bf16 v[58:61], v[26:29], v[214:217], v[58:61]
	v_mfma_f32_16x16x32_bf16 v[46:49], v[18:21], v[222:225], v[46:49]
	v_mfma_f32_16x16x32_bf16 v[42:45], v[26:29], v[222:225], v[42:45]
	v_mfma_f32_16x16x32_bf16 v[14:17], v[18:21], v[230:233], v[14:17]
	v_mfma_f32_16x16x32_bf16 v[10:13], v[26:29], v[230:233], v[10:13]
	v_mfma_f32_16x16x32_bf16 v[78:81], v[22:25], v[210:213], v[78:81]
	v_mfma_f32_16x16x32_bf16 v[74:77], v[30:33], v[210:213], v[74:77]
	v_mfma_f32_16x16x32_bf16 v[62:65], v[22:25], v[218:221], v[62:65]
	v_mfma_f32_16x16x32_bf16 v[58:61], v[30:33], v[218:221], v[58:61]
	v_mfma_f32_16x16x32_bf16 v[46:49], v[22:25], v[226:229], v[46:49]
	v_mfma_f32_16x16x32_bf16 v[42:45], v[30:33], v[226:229], v[42:45]
	v_mfma_f32_16x16x32_bf16 v[14:17], v[22:25], v[234:237], v[14:17]
	v_mfma_f32_16x16x32_bf16 v[10:13], v[30:33], v[234:237], v[10:13]
	s_setprio 0
	s_setprio 1
	v_mfma_f32_16x16x32_bf16 v[38:41], v[170:173], v[222:225], v[38:41]
	v_mfma_f32_16x16x32_bf16 v[34:37], v[190:193], v[222:225], v[34:37]
	v_mfma_f32_16x16x32_bf16 v[6:9], v[170:173], v[230:233], v[6:9]
	v_mfma_f32_16x16x32_bf16 v[2:5], v[190:193], v[230:233], v[2:5]
	v_mfma_f32_16x16x32_bf16 v[18:21], v[170:173], v[198:201], v[70:73]
	v_mfma_f32_16x16x32_bf16 v[22:25], v[190:193], v[198:201], v[66:69]
	v_mfma_f32_16x16x32_bf16 v[26:29], v[170:173], v[214:217], v[54:57]
	v_mfma_f32_16x16x32_bf16 v[30:33], v[190:193], v[214:217], v[50:53]
	v_mfma_f32_16x16x32_bf16 v[38:41], v[174:177], v[226:229], v[38:41]
	v_mfma_f32_16x16x32_bf16 v[34:37], v[194:197], v[226:229], v[34:37]
	v_mfma_f32_16x16x32_bf16 v[6:9], v[174:177], v[234:237], v[6:9]
	v_mfma_f32_16x16x32_bf16 v[2:5], v[194:197], v[234:237], v[2:5]
	v_mfma_f32_16x16x32_bf16 v[18:21], v[174:177], v[210:213], v[18:21]
	v_mfma_f32_16x16x32_bf16 v[22:25], v[194:197], v[210:213], v[22:25]
	v_mfma_f32_16x16x32_bf16 v[26:29], v[174:177], v[218:221], v[26:29]
	v_mfma_f32_16x16x32_bf16 v[30:33], v[194:197], v[218:221], v[30:33]
	s_setprio 0
	s_barrier
	s_add_i32 s0, 0, 0x18000
	v_add_u32_e32 v0, s0, v178
	s_add_i32 s1, 0, 0x1c000
	ds_read_b128 v[50:53], v0
	ds_read_b128 v[54:57], v0 offset:1024
	ds_read_b128 v[66:69], v0 offset:2048
	ds_read_b128 v[70:73], v0 offset:3072
	v_add_u32_e32 v0, s1, v178
	ds_read_b128 v[170:173], v0
	ds_read_b128 v[174:177], v0 offset:1024
	ds_read_b128 v[190:193], v0 offset:2048
	ds_read_b128 v[194:197], v0 offset:3072
	s_add_u32 s100, s30, 0x40000
	s_addc_u32 s101, s31, 0
	v_lshl_add_u64 v[238:239], s[100:101], 0, v[150:151]
	s_add_i32 m0, s93, 0x14000
	s_nop 0
	global_load_lds_dwordx4 v[238:239], off
	v_lshl_add_u64 v[238:239], s[100:101], 0, v[154:155]
	s_add_i32 m0, s93, 0x16000
	s_nop 0
	global_load_lds_dwordx4 v[238:239], off
	s_add_u32 s74, s74, 0x40000
	s_addc_u32 s75, s75, 0
	s_mov_b32 m0, s83
	v_lshl_add_u64 v[238:239], s[74:75], 0, v[148:149]
	ds_read_b128 v[198:201], v189 offset:32768
	ds_read_b128 v[210:213], v189 offset:33792
	ds_read_b128 v[214:217], v189 offset:34816
	ds_read_b128 v[218:221], v189 offset:35840
	ds_read_b128 v[222:225], v189 offset:36864
	ds_read_b128 v[226:229], v189 offset:37888
	ds_read_b128 v[230:233], v189 offset:38912
	ds_read_b128 v[234:237], v189 offset:39936
	global_load_lds_dwordx4 v[238:239], off
	v_lshl_add_u64 v[238:239], s[74:75], 0, v[152:153]
	s_mov_b32 m0, s16
	s_nop 0
	global_load_lds_dwordx4 v[238:239], off
	s_waitcnt vmcnt(8)
	s_waitcnt lgkmcnt(0)
	s_barrier
	s_setprio 1
	s_waitcnt lgkmcnt(0)
	v_mfma_f32_16x16x32_bf16 v[142:145], v[50:53], v[198:201], v[142:145]
	v_mfma_f32_16x16x32_bf16 v[138:141], v[66:69], v[198:201], v[138:141]
	v_mfma_f32_16x16x32_bf16 v[126:129], v[50:53], v[214:217], v[126:129]
	v_mfma_f32_16x16x32_bf16 v[122:125], v[66:69], v[214:217], v[122:125]
	v_mfma_f32_16x16x32_bf16 v[110:113], v[50:53], v[222:225], v[110:113]
	v_mfma_f32_16x16x32_bf16 v[106:109], v[66:69], v[222:225], v[106:109]
	v_mfma_f32_16x16x32_bf16 v[94:97], v[50:53], v[230:233], v[94:97]
	v_mfma_f32_16x16x32_bf16 v[90:93], v[66:69], v[230:233], v[90:93]
	v_mfma_f32_16x16x32_bf16 v[142:145], v[54:57], v[210:213], v[142:145]
	v_mfma_f32_16x16x32_bf16 v[138:141], v[70:73], v[210:213], v[138:141]
	v_mfma_f32_16x16x32_bf16 v[126:129], v[54:57], v[218:221], v[126:129]
	v_mfma_f32_16x16x32_bf16 v[122:125], v[70:73], v[218:221], v[122:125]
	v_mfma_f32_16x16x32_bf16 v[110:113], v[54:57], v[226:229], v[110:113]
	v_mfma_f32_16x16x32_bf16 v[106:109], v[70:73], v[226:229], v[106:109]
	v_mfma_f32_16x16x32_bf16 v[94:97], v[54:57], v[234:237], v[94:97]
	v_mfma_f32_16x16x32_bf16 v[90:93], v[70:73], v[234:237], v[90:93]
	s_setprio 0
	s_setprio 1
	v_mfma_f32_16x16x32_bf16 v[134:137], v[170:173], v[198:201], v[134:137]
	v_mfma_f32_16x16x32_bf16 v[130:133], v[190:193], v[198:201], v[130:133]
	v_mfma_f32_16x16x32_bf16 v[118:121], v[170:173], v[214:217], v[118:121]
	v_mfma_f32_16x16x32_bf16 v[114:117], v[190:193], v[214:217], v[114:117]
	v_mfma_f32_16x16x32_bf16 v[102:105], v[170:173], v[222:225], v[102:105]
	v_mfma_f32_16x16x32_bf16 v[98:101], v[190:193], v[222:225], v[98:101]
	v_mfma_f32_16x16x32_bf16 v[86:89], v[170:173], v[230:233], v[86:89]
	v_mfma_f32_16x16x32_bf16 v[82:85], v[190:193], v[230:233], v[82:85]
	v_mfma_f32_16x16x32_bf16 v[134:137], v[174:177], v[210:213], v[134:137]
	v_mfma_f32_16x16x32_bf16 v[130:133], v[194:197], v[210:213], v[130:133]
	v_mfma_f32_16x16x32_bf16 v[118:121], v[174:177], v[218:221], v[118:121]
	v_mfma_f32_16x16x32_bf16 v[114:117], v[194:197], v[218:221], v[114:117]
	v_mfma_f32_16x16x32_bf16 v[102:105], v[174:177], v[226:229], v[102:105]
	v_mfma_f32_16x16x32_bf16 v[98:101], v[194:197], v[226:229], v[98:101]
	v_mfma_f32_16x16x32_bf16 v[86:89], v[174:177], v[234:237], v[86:89]
	v_mfma_f32_16x16x32_bf16 v[82:85], v[194:197], v[234:237], v[82:85]
	s_setprio 0
	s_barrier
; #define PG8_STAGE(bufoff, gbase, voff) do { _Pragma("unroll") for (int _i = 0; _i < 2; ++_i) \
;         __builtin_amdgcn_global_load_lds((const unsigned*)((const char*)(gbase) + (voff)[_i]), (LAS unsigned*)(lds + (bufoff) + ldsw + _i * 8192), 16, 0, 0); } while (0)
; #define PG8_LDA(dst, b, h) do { _Pragma("unroll") for (int m = 0; m < 4; ++m) _Pragma("unroll") for (int k = 0; k < 2; ++k) dst[m][k] = *(const LAS bf16x8*)(lds + PG8_SA(b, h) + aoff + m * 2048 + k * 1024); } while (0)
; #define PG8_MMA(ai, bj, At, Bt) do { __builtin_amdgcn_s_setprio(1); _Pragma("unroll") for (int m = 0; m < 4; ++m) _Pragma("unroll") for (int n = 0; n < 2; ++n) _Pragma("unroll") for (int k = 0; k < 2; ++k) \
;         acc[ai][bj][m][n] = __builtin_amdgcn_mfma_f32_16x16x32_bf16(Bt[n][k], At[m][k], acc[ai][bj][m][n], 0, 0, 0); __builtin_amdgcn_s_setprio(0); } while (0)
; #define PG8_WAIT_V(n) asm volatile("s_waitcnt vmcnt(" #n ")" ::: "memory")
; #define PG8_WAIT_L(n) asm volatile("s_waitcnt lgkmcnt(" #n ")" ::: "memory")
; #define PG8_BAR __builtin_amdgcn_s_barrier()
; #define PG8_SCHED __builtin_amdgcn_sched_barrier(0)
; template <class Epi>
; __device__ __forceinline__ void gemm_phase(LAS unsigned char* lds, const int tid, const Gemm g, const StaticOrder& S, const Epi& E) {
;     ...
;             PG8_LDA(At, 1, 1); PG8_STAGE(PG8_SB(1, 0), b3, voffB); PG8_STAGE(PG8_SB(1, 1), b3 + hstepB, voffB); PG8_STAGE(PG8_SA(1, 0), a3, voffA);
;             PG8_WAIT_V(8); PG8_WAIT_L(0); PG8_BAR; PG8_MMA(1, 0, At, B0); PG8_MMA(1, 1, At, B1); PG8_BAR; PG8_SCHED;
;         }
;         if (wr == 0) PG8_BAR;
	s_add_i32 s0, s0, s93
	v_lshl_add_u64 v[162:163], v[162:163], 0, s[36:37]
	s_mov_b32 m0, s0
	ds_read_b128 v[198:201], v189 offset:49152
	ds_read_b128 v[210:213], v189 offset:50176
	ds_read_b128 v[214:217], v189 offset:51200
	ds_read_b128 v[218:221], v189 offset:52224
	ds_read_b128 v[222:225], v189 offset:53248
	ds_read_b128 v[226:229], v189 offset:54272
	ds_read_b128 v[230:233], v189 offset:55296
	ds_read_b128 v[234:237], v189 offset:56320
	global_load_lds_dwordx4 v[162:163], off
	s_add_i32 m0, s0, 0x2000
	s_add_u32 s30, s30, 0x40080
	v_lshl_add_u64 v[162:163], v[164:165], 0, s[36:37]
	s_addc_u32 s31, s31, 0
	s_add_i32 s0, s1, s93
	global_load_lds_dwordx4 v[162:163], off
	v_lshl_add_u64 v[162:163], s[30:31], 0, v[150:151]
	s_mov_b32 m0, s0
	s_nop 0
	global_load_lds_dwordx4 v[162:163], off
	v_lshl_add_u64 v[162:163], s[30:31], 0, v[154:155]
	s_add_i32 m0, s0, 0x2000
	s_nop 0
	global_load_lds_dwordx4 v[162:163], off
	v_lshl_add_u64 v[162:163], v[202:203], 0, s[36:37]
	s_mov_b32 m0, s92
	s_nop 0
	global_load_lds_dwordx4 v[162:163], off
	v_lshl_add_u64 v[162:163], v[206:207], 0, s[36:37]
	s_mov_b32 m0, s89
	s_nop 0
	global_load_lds_dwordx4 v[162:163], off
	s_waitcnt vmcnt(8)
	s_waitcnt lgkmcnt(0)
	s_barrier
	s_setprio 1
	s_waitcnt lgkmcnt(0)
	v_mfma_f32_16x16x32_bf16 v[78:81], v[50:53], v[198:201], v[78:81]
	v_mfma_f32_16x16x32_bf16 v[74:77], v[66:69], v[198:201], v[74:77]
	v_mfma_f32_16x16x32_bf16 v[62:65], v[50:53], v[214:217], v[62:65]
	v_mfma_f32_16x16x32_bf16 v[58:61], v[66:69], v[214:217], v[58:61]
	v_mfma_f32_16x16x32_bf16 v[46:49], v[50:53], v[222:225], v[46:49]
	v_mfma_f32_16x16x32_bf16 v[42:45], v[66:69], v[222:225], v[42:45]
	v_mfma_f32_16x16x32_bf16 v[14:17], v[50:53], v[230:233], v[14:17]
	v_mfma_f32_16x16x32_bf16 v[10:13], v[66:69], v[230:233], v[10:13]
	v_mfma_f32_16x16x32_bf16 v[78:81], v[54:57], v[210:213], v[78:81]
	v_mfma_f32_16x16x32_bf16 v[74:77], v[70:73], v[210:213], v[74:77]
	v_mfma_f32_16x16x32_bf16 v[62:65], v[54:57], v[218:221], v[62:65]
	v_mfma_f32_16x16x32_bf16 v[58:61], v[70:73], v[218:221], v[58:61]
	v_mfma_f32_16x16x32_bf16 v[46:49], v[54:57], v[226:229], v[46:49]
	v_mfma_f32_16x16x32_bf16 v[42:45], v[70:73], v[226:229], v[42:45]
	v_mfma_f32_16x16x32_bf16 v[14:17], v[54:57], v[234:237], v[14:17]
	v_mfma_f32_16x16x32_bf16 v[10:13], v[70:73], v[234:237], v[10:13]
	s_setprio 0
	s_setprio 1
	v_mfma_f32_16x16x32_bf16 v[18:21], v[170:173], v[198:201], v[18:21]
	v_mfma_f32_16x16x32_bf16 v[70:73], v[174:177], v[210:213], v[18:21]
	v_mfma_f32_16x16x32_bf16 v[18:21], v[190:193], v[198:201], v[22:25]
	v_mfma_f32_16x16x32_bf16 v[66:69], v[194:197], v[210:213], v[18:21]
	v_mfma_f32_16x16x32_bf16 v[18:21], v[170:173], v[214:217], v[26:29]
	v_mfma_f32_16x16x32_bf16 v[54:57], v[174:177], v[218:221], v[18:21]
	v_mfma_f32_16x16x32_bf16 v[18:21], v[190:193], v[214:217], v[30:33]
	v_mfma_f32_16x16x32_bf16 v[50:53], v[194:197], v[218:221], v[18:21]
	v_mfma_f32_16x16x32_bf16 v[18:21], v[170:173], v[222:225], v[38:41]
	v_mfma_f32_16x16x32_bf16 v[38:41], v[174:177], v[226:229], v[18:21]
	v_mfma_f32_16x16x32_bf16 v[18:21], v[190:193], v[222:225], v[34:37]
	v_mfma_f32_16x16x32_bf16 v[6:9], v[170:173], v[230:233], v[6:9]
	v_mfma_f32_16x16x32_bf16 v[2:5], v[190:193], v[230:233], v[2:5]
	v_mfma_f32_16x16x32_bf16 v[34:37], v[194:197], v[226:229], v[18:21]
	v_mfma_f32_16x16x32_bf16 v[6:9], v[174:177], v[234:237], v[6:9]
	v_mfma_f32_16x16x32_bf16 v[2:5], v[194:197], v[234:237], v[2:5]
	s_setprio 0
	s_barrier
	s_add_i32 vcc_hi, vcc_hi, 2
	s_add_u32 s72, s72, 0x100
	s_addc_u32 s73, s73, 0
	s_add_u32 s65, s65, 0x100
	s_addc_u32 vcc_lo, vcc_lo, 0
	s_cmp_gt_u32 vcc_hi, 13
	s_cbranch_scc0 .LBB0_945
	s_and_b64 vcc, exec, s[4:5]
	s_cbranch_vccz .LBB0_948
	s_barrier

; #define PG8_STAGE(bufoff, gbase, voff) do { _Pragma("unroll") for (int _i = 0; _i < 2; ++_i) \
;         __builtin_amdgcn_global_load_lds((const unsigned*)((const char*)(gbase) + (voff)[_i]), (LAS unsigned*)(lds + (bufoff) + ldsw + _i * 8192), 16, 0, 0); } while (0)
; #define PG8_LDA(dst, b, h) do { _Pragma("unroll") for (int m = 0; m < 4; ++m) _Pragma("unroll") for (int k = 0; k < 2; ++k) dst[m][k] = *(const LAS bf16x8*)(lds + PG8_SA(b, h) + aoff + m * 2048 + k * 1024); } while (0)
; #define PG8_LDB(dst, b, h) do { _Pragma("unroll") for (int n = 0; n < 2; ++n) _Pragma("unroll") for (int k = 0; k < 2; ++k) dst[n][k] = *(const LAS bf16x8*)(lds + PG8_SB(b, h) + boff + n * 2048 + k * 1024); } while (0)
; #define PG8_MMA(ai, bj, At, Bt) do { __builtin_amdgcn_s_setprio(1); _Pragma("unroll") for (int m = 0; m < 4; ++m) _Pragma("unroll") for (int n = 0; n < 2; ++n) _Pragma("unroll") for (int k = 0; k < 2; ++k) \
;         acc[ai][bj][m][n] = __builtin_amdgcn_mfma_f32_16x16x32_bf16(Bt[n][k], At[m][k], acc[ai][bj][m][n], 0, 0, 0); __builtin_amdgcn_s_setprio(0); } while (0)
; #define PG8_WAIT_V(n) asm volatile("s_waitcnt vmcnt(" #n ")" ::: "memory")
; #define PG8_WAIT_L(n) asm volatile("s_waitcnt lgkmcnt(" #n ")" ::: "memory")
; #define PG8_BAR __builtin_amdgcn_s_barrier()
; #define PG8_SCHED __builtin_amdgcn_sched_barrier(0)
; template <class Epi>
; __device__ __forceinline__ void gemm_phase(LAS unsigned char* lds, const int tid, const Gemm g, const StaticOrder& S, const Epi& E) {
;     ...
;             const bool last = (t == nt - 2);
;             const char* a1 = cA + (size_t)(t + 1) * kstep;
;             const char* a2 = last ? nA : cA + (size_t)(t + 2) * kstep; const char* b2 = last ? nB : cB + (size_t)(t + 2) * kstep;
;             const char* a3 = a2 + kstep; const char* b3 = b2 + kstep;
;             PG8_LDB(B0, 0, 0); PG8_LDB(B1, 0, 1); PG8_SCHED; PG8_LDA(At, 0, 0); PG8_STAGE(PG8_SA(1, 1), a1 + hstepA, voffA);
;             PG8_WAIT_V(8); PG8_WAIT_L(0); PG8_BAR; PG8_MMA(0, 0, At, B0); PG8_MMA(0, 1, At, B1); PG8_BAR; PG8_SCHED;
;             PG8_LDA(At, 0, 1); PG8_STAGE(PG8_SB(0, 0), b2, voffB); PG8_STAGE(PG8_SB(0, 1), b2 + hstepB, voffB); PG8_STAGE(PG8_SA(0, 0), a2, voffA);
;             PG8_WAIT_V(8); PG8_WAIT_L(0); PG8_BAR; PG8_MMA(1, 0, At, B0); PG8_MMA(1, 1, At, B1); PG8_BAR; PG8_SCHED;
.LBB0_1284:
	s_add_u32 s2, s66, 0xfff80080
	s_addc_u32 s3, s67, -1
	s_add_i32 vcc_hi, 0, 0x10000
	s_cmp_eq_u32 vcc_lo, 12
	s_cselect_b32 s69, s11, s3
	s_cselect_b32 s68, s88, s2
	v_add_u32_e32 v144, vcc_hi, v171
	s_cselect_b32 s31, s9, s93
	s_cselect_b32 s30, s89, s92
	s_add_i32 s0, 0, 0x14000
	ds_read_b128 v[140:143], v144
	ds_read_b128 v[176:179], v144 offset:1024
	ds_read_b128 v[180:183], v144 offset:2048
	ds_read_b128 v[184:187], v144 offset:3072
	v_add_u32_e32 v144, s0, v171
	ds_read_b128 v[188:191], v144
	ds_read_b128 v[192:195], v144 offset:1024
	ds_read_b128 v[196:199], v144 offset:2048
	ds_read_b128 v[200:203], v144 offset:3072
	v_lshl_add_u64 v[144:145], s[66:67], 0, v[136:137]
	s_add_i32 m0, s71, 0xc000
	ds_read_b128 v[210:213], v174
	ds_read_b128 v[214:217], v174 offset:1024
	ds_read_b128 v[218:221], v174 offset:2048
	ds_read_b128 v[222:225], v174 offset:3072
	ds_read_b128 v[226:229], v174 offset:4096
	ds_read_b128 v[230:233], v174 offset:5120
	ds_read_b128 v[234:237], v174 offset:6144
	ds_read_b128 v[238:241], v174 offset:7168
	global_load_lds_dwordx4 v[144:145], off
	v_lshl_add_u64 v[144:145], s[66:67], 0, v[138:139]
	s_add_i32 m0, s71, 0xe000
	s_nop 0
	global_load_lds_dwordx4 v[144:145], off
	s_waitcnt vmcnt(8)
	s_waitcnt lgkmcnt(0)
	s_barrier
	s_setprio 1
	s_waitcnt lgkmcnt(0)
	v_mfma_f32_16x16x32_bf16 v[126:129], v[140:143], v[210:213], v[126:129]
	v_mfma_f32_16x16x32_bf16 v[122:125], v[180:183], v[210:213], v[122:125]
	v_mfma_f32_16x16x32_bf16 v[118:121], v[140:143], v[218:221], v[118:121]
	v_mfma_f32_16x16x32_bf16 v[110:113], v[180:183], v[218:221], v[110:113]
	v_mfma_f32_16x16x32_bf16 v[94:97], v[140:143], v[226:229], v[94:97]
	v_mfma_f32_16x16x32_bf16 v[90:93], v[180:183], v[226:229], v[90:93]
	v_mfma_f32_16x16x32_bf16 v[86:89], v[140:143], v[234:237], v[86:89]
	v_mfma_f32_16x16x32_bf16 v[78:81], v[180:183], v[234:237], v[78:81]
	v_mfma_f32_16x16x32_bf16 v[126:129], v[176:179], v[214:217], v[126:129]
	v_mfma_f32_16x16x32_bf16 v[122:125], v[184:187], v[214:217], v[122:125]
	v_mfma_f32_16x16x32_bf16 v[118:121], v[176:179], v[222:225], v[118:121]
	v_mfma_f32_16x16x32_bf16 v[110:113], v[184:187], v[222:225], v[110:113]
	v_mfma_f32_16x16x32_bf16 v[94:97], v[176:179], v[230:233], v[94:97]
	v_mfma_f32_16x16x32_bf16 v[90:93], v[184:187], v[230:233], v[90:93]
	v_mfma_f32_16x16x32_bf16 v[86:89], v[176:179], v[238:241], v[86:89]
	v_mfma_f32_16x16x32_bf16 v[78:81], v[184:187], v[238:241], v[78:81]
	s_setprio 0
	s_setprio 1
	v_mfma_f32_16x16x32_bf16 v[114:117], v[188:191], v[210:213], v[114:117]
	v_mfma_f32_16x16x32_bf16 v[106:109], v[196:199], v[210:213], v[106:109]
	v_mfma_f32_16x16x32_bf16 v[102:105], v[188:191], v[218:221], v[102:105]
	v_mfma_f32_16x16x32_bf16 v[98:101], v[196:199], v[218:221], v[98:101]
	v_mfma_f32_16x16x32_bf16 v[82:85], v[188:191], v[226:229], v[82:85]
	v_mfma_f32_16x16x32_bf16 v[74:77], v[196:199], v[226:229], v[74:77]
	v_mfma_f32_16x16x32_bf16 v[70:73], v[188:191], v[234:237], v[70:73]
	v_mfma_f32_16x16x32_bf16 v[66:69], v[196:199], v[234:237], v[66:69]
	v_mfma_f32_16x16x32_bf16 v[114:117], v[192:195], v[214:217], v[114:117]
	v_mfma_f32_16x16x32_bf16 v[106:109], v[200:203], v[214:217], v[106:109]
	v_mfma_f32_16x16x32_bf16 v[102:105], v[192:195], v[222:225], v[102:105]
	v_mfma_f32_16x16x32_bf16 v[98:101], v[200:203], v[222:225], v[98:101]
	v_mfma_f32_16x16x32_bf16 v[82:85], v[192:195], v[230:233], v[82:85]
	v_mfma_f32_16x16x32_bf16 v[74:77], v[200:203], v[230:233], v[74:77]
	v_mfma_f32_16x16x32_bf16 v[70:73], v[192:195], v[238:241], v[70:73]
	v_mfma_f32_16x16x32_bf16 v[66:69], v[200:203], v[238:241], v[66:69]
	s_setprio 0
	s_barrier
	s_add_i32 s1, vcc_hi, s28
	v_lshl_add_u64 v[144:145], s[30:31], 0, v[0:1]
	s_mov_b32 m0, s1
	ds_read_b128 v[210:213], v174 offset:16384
	ds_read_b128 v[214:217], v174 offset:17408
	ds_read_b128 v[218:221], v174 offset:18432
	ds_read_b128 v[222:225], v174 offset:19456
	ds_read_b128 v[226:229], v174 offset:20480
	ds_read_b128 v[230:233], v174 offset:21504
	ds_read_b128 v[234:237], v174 offset:22528
	ds_read_b128 v[238:241], v174 offset:23552
	global_load_lds_dwordx4 v[144:145], off
	s_add_i32 m0, s1, 0x2000
	s_add_u32 s2, s30, 0x40000
	v_lshl_add_u64 v[162:163], s[30:31], 0, v[130:131]
	s_addc_u32 s3, s31, 0
	s_add_i32 s0, s0, s28
	global_load_lds_dwordx4 v[162:163], off
	v_lshl_add_u64 v[164:165], s[2:3], 0, v[0:1]
	s_mov_b32 m0, s0
	v_lshl_add_u64 v[206:207], s[68:69], 0, v[132:133]
	v_lshl_add_u64 v[164:165], s[2:3], 0, v[130:131]
	s_add_i32 m0, s0, 0x2000
	s_nop 0
	v_lshl_add_u64 v[164:165], s[68:69], 0, v[134:135]
	s_mov_b32 m0, s71
	s_nop 0
	global_load_lds_dwordx4 v[164:165], off
	s_mov_b32 m0, s72
	s_nop 0
	global_load_lds_dwordx4 v[206:207], off
	s_waitcnt vmcnt(6)
	s_waitcnt lgkmcnt(0)
	s_barrier
; #define PG8_STAGE(bufoff, gbase, voff) do { _Pragma("unroll") for (int _i = 0; _i < 2; ++_i) \
;         __builtin_amdgcn_global_load_lds((const unsigned*)((const char*)(gbase) + (voff)[_i]), (LAS unsigned*)(lds + (bufoff) + ldsw + _i * 8192), 16, 0, 0); } while (0)
; #define PG8_LDA(dst, b, h) do { _Pragma("unroll") for (int m = 0; m < 4; ++m) _Pragma("unroll") for (int k = 0; k < 2; ++k) dst[m][k] = *(const LAS bf16x8*)(lds + PG8_SA(b, h) + aoff + m * 2048 + k * 1024); } while (0)
; #define PG8_LDB(dst, b, h) do { _Pragma("unroll") for (int n = 0; n < 2; ++n) _Pragma("unroll") for (int k = 0; k < 2; ++k) dst[n][k] = *(const LAS bf16x8*)(lds + PG8_SB(b, h) + boff + n * 2048 + k * 1024); } while (0)
; #define PG8_MMA(ai, bj, At, Bt) do { __builtin_amdgcn_s_setprio(1); _Pragma("unroll") for (int m = 0; m < 4; ++m) _Pragma("unroll") for (int n = 0; n < 2; ++n) _Pragma("unroll") for (int k = 0; k < 2; ++k) \
;         acc[ai][bj][m][n] = __builtin_amdgcn_mfma_f32_16x16x32_bf16(Bt[n][k], At[m][k], acc[ai][bj][m][n], 0, 0, 0); __builtin_amdgcn_s_setprio(0); } while (0)
; #define PG8_WAIT_V(n) asm volatile("s_waitcnt vmcnt(" #n ")" ::: "memory")
; #define PG8_WAIT_L(n) asm volatile("s_waitcnt lgkmcnt(" #n ")" ::: "memory")
; #define PG8_BAR __builtin_amdgcn_s_barrier()
; #define PG8_SCHED __builtin_amdgcn_sched_barrier(0)
; template <class Epi>
; __device__ __forceinline__ void gemm_phase(LAS unsigned char* lds, const int tid, const Gemm g, const StaticOrder& S, const Epi& E) {
;     ...
;             PG8_WAIT_V(8); PG8_WAIT_L(0); PG8_BAR; PG8_MMA(1, 0, At, B0); PG8_MMA(1, 1, At, B1); PG8_BAR; PG8_SCHED;
;             PG8_LDB(B0, 1, 0); PG8_LDB(B1, 1, 1); PG8_SCHED; PG8_LDA(At, 1, 0); PG8_STAGE(PG8_SA(0, 1), a2 + hstepA, voffA);
;             PG8_WAIT_V(8); PG8_WAIT_L(0); PG8_BAR; PG8_MMA(0, 0, At, B0); PG8_MMA(0, 1, At, B1); PG8_BAR; PG8_SCHED;
	s_setprio 1
	s_waitcnt lgkmcnt(0)
	v_mfma_f32_16x16x32_bf16 v[62:65], v[140:143], v[210:213], v[62:65]
	v_mfma_f32_16x16x32_bf16 v[58:61], v[180:183], v[210:213], v[58:61]
	v_mfma_f32_16x16x32_bf16 v[54:57], v[140:143], v[218:221], v[54:57]
	v_mfma_f32_16x16x32_bf16 v[46:49], v[180:183], v[218:221], v[46:49]
	v_mfma_f32_16x16x32_bf16 v[30:33], v[140:143], v[226:229], v[30:33]
	v_mfma_f32_16x16x32_bf16 v[26:29], v[180:183], v[226:229], v[26:29]
	v_mfma_f32_16x16x32_bf16 v[22:25], v[140:143], v[234:237], v[22:25]
	v_mfma_f32_16x16x32_bf16 v[14:17], v[180:183], v[234:237], v[14:17]
	v_mfma_f32_16x16x32_bf16 v[62:65], v[176:179], v[214:217], v[62:65]
	v_mfma_f32_16x16x32_bf16 v[58:61], v[184:187], v[214:217], v[58:61]
	v_mfma_f32_16x16x32_bf16 v[54:57], v[176:179], v[222:225], v[54:57]
	v_mfma_f32_16x16x32_bf16 v[46:49], v[184:187], v[222:225], v[46:49]
	v_mfma_f32_16x16x32_bf16 v[30:33], v[176:179], v[230:233], v[30:33]
	v_mfma_f32_16x16x32_bf16 v[26:29], v[184:187], v[230:233], v[26:29]
	v_mfma_f32_16x16x32_bf16 v[22:25], v[176:179], v[238:241], v[22:25]
	v_mfma_f32_16x16x32_bf16 v[14:17], v[184:187], v[238:241], v[14:17]
	s_setprio 0
	s_setprio 1
	v_mfma_f32_16x16x32_bf16 v[50:53], v[188:191], v[210:213], v[50:53]
	v_mfma_f32_16x16x32_bf16 v[42:45], v[196:199], v[210:213], v[42:45]
	v_mfma_f32_16x16x32_bf16 v[38:41], v[188:191], v[218:221], v[38:41]
	v_mfma_f32_16x16x32_bf16 v[34:37], v[196:199], v[218:221], v[34:37]
	v_mfma_f32_16x16x32_bf16 v[18:21], v[188:191], v[226:229], v[18:21]
	v_mfma_f32_16x16x32_bf16 v[10:13], v[196:199], v[226:229], v[10:13]
	v_mfma_f32_16x16x32_bf16 v[6:9], v[188:191], v[234:237], v[6:9]
	v_mfma_f32_16x16x32_bf16 v[2:5], v[196:199], v[234:237], v[2:5]
	v_mfma_f32_16x16x32_bf16 v[50:53], v[192:195], v[214:217], v[50:53]
	v_mfma_f32_16x16x32_bf16 v[42:45], v[200:203], v[214:217], v[42:45]
	v_mfma_f32_16x16x32_bf16 v[38:41], v[192:195], v[222:225], v[38:41]
	v_mfma_f32_16x16x32_bf16 v[34:37], v[200:203], v[222:225], v[34:37]
	v_mfma_f32_16x16x32_bf16 v[18:21], v[192:195], v[230:233], v[18:21]
	v_mfma_f32_16x16x32_bf16 v[10:13], v[200:203], v[230:233], v[10:13]
	v_mfma_f32_16x16x32_bf16 v[6:9], v[192:195], v[238:241], v[6:9]
	v_mfma_f32_16x16x32_bf16 v[2:5], v[200:203], v[238:241], v[2:5]
	s_setprio 0
	s_barrier
	s_add_i32 s0, 0, 0x18000
	v_add_u32_e32 v175, s0, v171
	s_add_i32 s1, 0, 0x1c000
	ds_read_b128 v[140:143], v175
	ds_read_b128 v[176:179], v175 offset:1024
	ds_read_b128 v[180:183], v175 offset:2048
	ds_read_b128 v[184:187], v175 offset:3072
	v_add_u32_e32 v175, s1, v171
	ds_read_b128 v[188:191], v175
	ds_read_b128 v[192:195], v175 offset:1024
	ds_read_b128 v[196:199], v175 offset:2048
	ds_read_b128 v[200:203], v175 offset:3072
	s_add_u32 s100, s30, 0x40000
	s_addc_u32 s101, s31, 0
	v_lshl_add_u64 v[242:243], s[100:101], 0, v[0:1]
	s_add_i32 m0, s28, 0x14000
	s_nop 0
	global_load_lds_dwordx4 v[242:243], off
	v_lshl_add_u64 v[242:243], s[100:101], 0, v[130:131]
	s_add_i32 m0, s28, 0x16000
	s_nop 0
	global_load_lds_dwordx4 v[242:243], off
	s_add_u32 s2, s68, 0x80000
	s_addc_u32 s3, s69, 0
	s_mov_b32 m0, s73
	v_lshl_add_u64 v[242:243], s[2:3], 0, v[134:135]
	ds_read_b128 v[210:213], v174 offset:32768
	ds_read_b128 v[214:217], v174 offset:33792
	ds_read_b128 v[218:221], v174 offset:34816
	ds_read_b128 v[222:225], v174 offset:35840
	ds_read_b128 v[226:229], v174 offset:36864
	ds_read_b128 v[230:233], v174 offset:37888
	ds_read_b128 v[234:237], v174 offset:38912
	ds_read_b128 v[238:241], v174 offset:39936
	global_load_lds_dwordx4 v[242:243], off
	v_lshl_add_u64 v[242:243], s[2:3], 0, v[132:133]
	s_mov_b32 m0, s74
	s_nop 0
	global_load_lds_dwordx4 v[242:243], off
	s_waitcnt vmcnt(8)
	s_waitcnt lgkmcnt(0)
	s_barrier
	s_setprio 1
	s_waitcnt lgkmcnt(0)
	v_mfma_f32_16x16x32_bf16 v[126:129], v[140:143], v[210:213], v[126:129]
	v_mfma_f32_16x16x32_bf16 v[122:125], v[180:183], v[210:213], v[122:125]
	v_mfma_f32_16x16x32_bf16 v[118:121], v[140:143], v[218:221], v[118:121]
	v_mfma_f32_16x16x32_bf16 v[110:113], v[180:183], v[218:221], v[110:113]
	v_mfma_f32_16x16x32_bf16 v[94:97], v[140:143], v[226:229], v[94:97]
	v_mfma_f32_16x16x32_bf16 v[90:93], v[180:183], v[226:229], v[90:93]
	v_mfma_f32_16x16x32_bf16 v[86:89], v[140:143], v[234:237], v[86:89]
	v_mfma_f32_16x16x32_bf16 v[78:81], v[180:183], v[234:237], v[78:81]
	v_mfma_f32_16x16x32_bf16 v[126:129], v[176:179], v[214:217], v[126:129]
	v_mfma_f32_16x16x32_bf16 v[122:125], v[184:187], v[214:217], v[122:125]
	v_mfma_f32_16x16x32_bf16 v[118:121], v[176:179], v[222:225], v[118:121]
	v_mfma_f32_16x16x32_bf16 v[110:113], v[184:187], v[222:225], v[110:113]
	v_mfma_f32_16x16x32_bf16 v[94:97], v[176:179], v[230:233], v[94:97]
	v_mfma_f32_16x16x32_bf16 v[90:93], v[184:187], v[230:233], v[90:93]
	v_mfma_f32_16x16x32_bf16 v[86:89], v[176:179], v[238:241], v[86:89]
	v_mfma_f32_16x16x32_bf16 v[78:81], v[184:187], v[238:241], v[78:81]
	s_setprio 0
	s_setprio 1
	v_mfma_f32_16x16x32_bf16 v[114:117], v[188:191], v[210:213], v[114:117]
	v_mfma_f32_16x16x32_bf16 v[106:109], v[196:199], v[210:213], v[106:109]
	v_mfma_f32_16x16x32_bf16 v[102:105], v[188:191], v[218:221], v[102:105]
	v_mfma_f32_16x16x32_bf16 v[98:101], v[196:199], v[218:221], v[98:101]
	v_mfma_f32_16x16x32_bf16 v[82:85], v[188:191], v[226:229], v[82:85]
	v_mfma_f32_16x16x32_bf16 v[74:77], v[196:199], v[226:229], v[74:77]
	v_mfma_f32_16x16x32_bf16 v[70:73], v[188:191], v[234:237], v[70:73]
	v_mfma_f32_16x16x32_bf16 v[66:69], v[196:199], v[234:237], v[66:69]
	v_mfma_f32_16x16x32_bf16 v[114:117], v[192:195], v[214:217], v[114:117]
	v_mfma_f32_16x16x32_bf16 v[106:109], v[200:203], v[214:217], v[106:109]
	v_mfma_f32_16x16x32_bf16 v[102:105], v[192:195], v[222:225], v[102:105]
	v_mfma_f32_16x16x32_bf16 v[98:101], v[200:203], v[222:225], v[98:101]
	v_mfma_f32_16x16x32_bf16 v[82:85], v[192:195], v[230:233], v[82:85]
	v_mfma_f32_16x16x32_bf16 v[74:77], v[200:203], v[230:233], v[74:77]
	v_mfma_f32_16x16x32_bf16 v[70:73], v[192:195], v[238:241], v[70:73]
	v_mfma_f32_16x16x32_bf16 v[66:69], v[200:203], v[238:241], v[66:69]
	s_setprio 0
	s_barrier
; #define PG8_STAGE(bufoff, gbase, voff) do { _Pragma("unroll") for (int _i = 0; _i < 2; ++_i) \
;         __builtin_amdgcn_global_load_lds((const unsigned*)((const char*)(gbase) + (voff)[_i]), (LAS unsigned*)(lds + (bufoff) + ldsw + _i * 8192), 16, 0, 0); } while (0)
; #define PG8_LDA(dst, b, h) do { _Pragma("unroll") for (int m = 0; m < 4; ++m) _Pragma("unroll") for (int k = 0; k < 2; ++k) dst[m][k] = *(const LAS bf16x8*)(lds + PG8_SA(b, h) + aoff + m * 2048 + k * 1024); } while (0)
; #define PG8_MMA(ai, bj, At, Bt) do { __builtin_amdgcn_s_setprio(1); _Pragma("unroll") for (int m = 0; m < 4; ++m) _Pragma("unroll") for (int n = 0; n < 2; ++n) _Pragma("unroll") for (int k = 0; k < 2; ++k) \
;         acc[ai][bj][m][n] = __builtin_amdgcn_mfma_f32_16x16x32_bf16(Bt[n][k], At[m][k], acc[ai][bj][m][n], 0, 0, 0); __builtin_amdgcn_s_setprio(0); } while (0)
; #define PG8_WAIT_V(n) asm volatile("s_waitcnt vmcnt(" #n ")" ::: "memory")
; #define PG8_WAIT_L(n) asm volatile("s_waitcnt lgkmcnt(" #n ")" ::: "memory")
; #define PG8_BAR __builtin_amdgcn_s_barrier()
; #define PG8_SCHED __builtin_amdgcn_sched_barrier(0)
; template <class Epi>
; __device__ __forceinline__ void gemm_phase(LAS unsigned char* lds, const int tid, const Gemm g, const StaticOrder& S, const Epi& E) {
;     ...
;             PG8_LDA(At, 1, 1); PG8_STAGE(PG8_SB(1, 0), b3, voffB); PG8_STAGE(PG8_SB(1, 1), b3 + hstepB, voffB); PG8_STAGE(PG8_SA(1, 0), a3, voffA);
;             PG8_WAIT_V(8); PG8_WAIT_L(0); PG8_BAR; PG8_MMA(1, 0, At, B0); PG8_MMA(1, 1, At, B1); PG8_BAR; PG8_SCHED;
;         }
;         if (wr == 0) PG8_BAR;
	s_add_i32 s0, s0, s28
	v_lshl_add_u64 v[144:145], v[144:145], 0, s[36:37]
	s_mov_b32 m0, s0
	ds_read_b128 v[210:213], v174 offset:49152
	ds_read_b128 v[214:217], v174 offset:50176
	ds_read_b128 v[218:221], v174 offset:51200
	ds_read_b128 v[222:225], v174 offset:52224
	ds_read_b128 v[226:229], v174 offset:53248
	ds_read_b128 v[230:233], v174 offset:54272
	ds_read_b128 v[234:237], v174 offset:55296
	ds_read_b128 v[238:241], v174 offset:56320
	global_load_lds_dwordx4 v[144:145], off
	s_add_i32 m0, s0, 0x2000
	s_add_u32 s2, s30, 0x40080
	v_lshl_add_u64 v[144:145], v[162:163], 0, s[36:37]
	s_addc_u32 s3, s31, 0
	s_add_i32 s0, s1, s28
	global_load_lds_dwordx4 v[144:145], off
	v_lshl_add_u64 v[144:145], s[2:3], 0, v[0:1]
	s_mov_b32 m0, s0
	s_nop 0
	global_load_lds_dwordx4 v[144:145], off
	v_lshl_add_u64 v[144:145], s[2:3], 0, v[130:131]
	s_add_i32 m0, s0, 0x2000
	s_nop 0
	global_load_lds_dwordx4 v[144:145], off
	v_lshl_add_u64 v[144:145], v[164:165], 0, s[36:37]
	s_mov_b32 m0, s75
	s_nop 0
	global_load_lds_dwordx4 v[144:145], off
	v_lshl_add_u64 v[144:145], v[206:207], 0, s[36:37]
	s_mov_b32 m0, s76
	s_nop 0
	global_load_lds_dwordx4 v[144:145], off
	s_waitcnt vmcnt(8)
	s_waitcnt lgkmcnt(0)
	s_barrier
	s_setprio 1
	s_waitcnt lgkmcnt(0)
	v_mfma_f32_16x16x32_bf16 v[62:65], v[140:143], v[210:213], v[62:65]
	v_mfma_f32_16x16x32_bf16 v[58:61], v[180:183], v[210:213], v[58:61]
	v_mfma_f32_16x16x32_bf16 v[54:57], v[140:143], v[218:221], v[54:57]
	v_mfma_f32_16x16x32_bf16 v[46:49], v[180:183], v[218:221], v[46:49]
	v_mfma_f32_16x16x32_bf16 v[30:33], v[140:143], v[226:229], v[30:33]
	v_mfma_f32_16x16x32_bf16 v[26:29], v[180:183], v[226:229], v[26:29]
	v_mfma_f32_16x16x32_bf16 v[22:25], v[140:143], v[234:237], v[22:25]
	v_mfma_f32_16x16x32_bf16 v[14:17], v[180:183], v[234:237], v[14:17]
	v_mfma_f32_16x16x32_bf16 v[62:65], v[176:179], v[214:217], v[62:65]
	v_mfma_f32_16x16x32_bf16 v[58:61], v[184:187], v[214:217], v[58:61]
	v_mfma_f32_16x16x32_bf16 v[54:57], v[176:179], v[222:225], v[54:57]
	v_mfma_f32_16x16x32_bf16 v[46:49], v[184:187], v[222:225], v[46:49]
	v_mfma_f32_16x16x32_bf16 v[30:33], v[176:179], v[230:233], v[30:33]
	v_mfma_f32_16x16x32_bf16 v[26:29], v[184:187], v[230:233], v[26:29]
	v_mfma_f32_16x16x32_bf16 v[22:25], v[176:179], v[238:241], v[22:25]
	v_mfma_f32_16x16x32_bf16 v[14:17], v[184:187], v[238:241], v[14:17]
	s_setprio 0
	s_setprio 1
	v_mfma_f32_16x16x32_bf16 v[50:53], v[188:191], v[210:213], v[50:53]
	v_mfma_f32_16x16x32_bf16 v[42:45], v[196:199], v[210:213], v[42:45]
	v_mfma_f32_16x16x32_bf16 v[38:41], v[188:191], v[218:221], v[38:41]
	v_mfma_f32_16x16x32_bf16 v[34:37], v[196:199], v[218:221], v[34:37]
	v_mfma_f32_16x16x32_bf16 v[18:21], v[188:191], v[226:229], v[18:21]
	v_mfma_f32_16x16x32_bf16 v[10:13], v[196:199], v[226:229], v[10:13]
	v_mfma_f32_16x16x32_bf16 v[6:9], v[188:191], v[234:237], v[6:9]
	v_mfma_f32_16x16x32_bf16 v[2:5], v[196:199], v[234:237], v[2:5]
	v_mfma_f32_16x16x32_bf16 v[50:53], v[192:195], v[214:217], v[50:53]
	v_mfma_f32_16x16x32_bf16 v[42:45], v[200:203], v[214:217], v[42:45]
	v_mfma_f32_16x16x32_bf16 v[38:41], v[192:195], v[222:225], v[38:41]
	v_mfma_f32_16x16x32_bf16 v[34:37], v[200:203], v[222:225], v[34:37]
	v_mfma_f32_16x16x32_bf16 v[18:21], v[192:195], v[230:233], v[18:21]
	v_mfma_f32_16x16x32_bf16 v[10:13], v[200:203], v[230:233], v[10:13]
	v_mfma_f32_16x16x32_bf16 v[6:9], v[192:195], v[238:241], v[6:9]
	v_mfma_f32_16x16x32_bf16 v[2:5], v[200:203], v[238:241], v[2:5]
	s_setprio 0
	s_barrier
	s_add_i32 vcc_lo, vcc_lo, 2
	s_add_u32 s66, s66, 0x100
	s_addc_u32 s67, s67, 0
	s_add_u32 s92, s92, 0x100
	s_addc_u32 s93, s93, 0
	s_cmp_gt_u32 vcc_lo, 13
	s_cbranch_scc0 .LBB0_1284
	s_and_b64 vcc, exec, s[6:7]
	s_mov_b32 s92, 0x2c000
	s_mov_b32 s93, 0x2e000
	s_cbranch_vccz .LBB0_1287
	s_barrier

; #define PG8_STAGE(bufoff, gbase, voff) do { _Pragma("unroll") for (int _i = 0; _i < 2; ++_i) \
;         __builtin_amdgcn_global_load_lds((const unsigned*)((const char*)(gbase) + (voff)[_i]), (LAS unsigned*)(lds + (bufoff) + ldsw + _i * 8192), 16, 0, 0); } while (0)
; #define PG8_LDA(dst, b, h) do { _Pragma("unroll") for (int m = 0; m < 4; ++m) _Pragma("unroll") for (int k = 0; k < 2; ++k) dst[m][k] = *(const LAS bf16x8*)(lds + PG8_SA(b, h) + aoff + m * 2048 + k * 1024); } while (0)
; #define PG8_LDB(dst, b, h) do { _Pragma("unroll") for (int n = 0; n < 2; ++n) _Pragma("unroll") for (int k = 0; k < 2; ++k) dst[n][k] = *(const LAS bf16x8*)(lds + PG8_SB(b, h) + boff + n * 2048 + k * 1024); } while (0)
; #define PG8_MMA(ai, bj, At, Bt) do { __builtin_amdgcn_s_setprio(1); _Pragma("unroll") for (int m = 0; m < 4; ++m) _Pragma("unroll") for (int n = 0; n < 2; ++n) _Pragma("unroll") for (int k = 0; k < 2; ++k) \
;         acc[ai][bj][m][n] = __builtin_amdgcn_mfma_f32_16x16x32_bf16(Bt[n][k], At[m][k], acc[ai][bj][m][n], 0, 0, 0); __builtin_amdgcn_s_setprio(0); } while (0)
; #define PG8_WAIT_V(n) asm volatile("s_waitcnt vmcnt(" #n ")" ::: "memory")
; #define PG8_WAIT_L(n) asm volatile("s_waitcnt lgkmcnt(" #n ")" ::: "memory")
; #define PG8_BAR __builtin_amdgcn_s_barrier()
; #define PG8_SCHED __builtin_amdgcn_sched_barrier(0)
; template <class Epi>
; __device__ __forceinline__ void gemm_phase(LAS unsigned char* lds, const int tid, const Gemm g, const StaticOrder& S, const Epi& E) {
;     ...
;             const bool last = (t == nt - 2);
;             const char* a1 = cA + (size_t)(t + 1) * kstep;
;             const char* a2 = last ? nA : cA + (size_t)(t + 2) * kstep; const char* b2 = last ? nB : cB + (size_t)(t + 2) * kstep;
;             const char* a3 = a2 + kstep; const char* b3 = b2 + kstep;
;             PG8_LDB(B0, 0, 0); PG8_LDB(B1, 0, 1); PG8_SCHED; PG8_LDA(At, 0, 0); PG8_STAGE(PG8_SA(1, 1), a1 + hstepA, voffA);
;             PG8_WAIT_V(8); PG8_WAIT_L(0); PG8_BAR; PG8_MMA(0, 0, At, B0); PG8_MMA(0, 1, At, B1); PG8_BAR; PG8_SCHED;
;             PG8_LDA(At, 0, 1); PG8_STAGE(PG8_SB(0, 0), b2, voffB); PG8_STAGE(PG8_SB(0, 1), b2 + hstepB, voffB); PG8_STAGE(PG8_SA(0, 0), a2, voffA);
;             PG8_WAIT_V(8); PG8_WAIT_L(0); PG8_BAR; PG8_MMA(1, 0, At, B0); PG8_MMA(1, 1, At, B1); PG8_BAR; PG8_SCHED;
.LBB0_1333:
	s_add_u32 s0, s66, 0xfff80080
	s_addc_u32 s1, s67, -1
	s_add_i32 s2, 0, 0x10000
	s_cmp_eq_u32 vcc_lo, 12
	s_cselect_b32 s69, s11, s1
	s_cselect_b32 s68, s88, s0
	s_cselect_b32 s31, s9, s93
	s_cselect_b32 s30, s89, s92
	s_add_i32 s0, 0, 0x14000
	v_add_u32_e32 v142, s2, v189
	v_add_u32_e32 v162, s0, v189
	ds_read_b128 v[130:133], v142
	ds_read_b128 v[134:137], v142 offset:1024
	ds_read_b128 v[138:141], v142 offset:2048
	ds_read_b128 v[142:145], v142 offset:3072
	ds_read_b128 v[158:161], v162
	ds_read_b128 v[192:195], v162 offset:1024
	ds_read_b128 v[196:199], v162 offset:2048
	ds_read_b128 v[200:203], v162 offset:3072
	v_lshl_add_u64 v[162:163], s[66:67], 0, v[154:155]
	s_add_i32 m0, s71, 0xc000
	ds_read_b128 v[210:213], v191
	ds_read_b128 v[214:217], v191 offset:1024
	ds_read_b128 v[218:221], v191 offset:2048
	ds_read_b128 v[222:225], v191 offset:3072
	ds_read_b128 v[226:229], v191 offset:4096
	ds_read_b128 v[230:233], v191 offset:5120
	ds_read_b128 v[234:237], v191 offset:6144
	ds_read_b128 v[238:241], v191 offset:7168
	global_load_lds_dwordx4 v[162:163], off
	v_lshl_add_u64 v[162:163], s[66:67], 0, v[156:157]
	s_add_i32 m0, s71, 0xe000
	s_nop 0
	global_load_lds_dwordx4 v[162:163], off
	s_waitcnt vmcnt(8)
	s_waitcnt lgkmcnt(0)
	s_barrier
	s_setprio 1
	s_waitcnt lgkmcnt(0)
	v_mfma_f32_16x16x32_bf16 v[126:129], v[130:133], v[210:213], v[126:129]
	v_mfma_f32_16x16x32_bf16 v[122:125], v[138:141], v[210:213], v[122:125]
	v_mfma_f32_16x16x32_bf16 v[110:113], v[130:133], v[218:221], v[110:113]
	v_mfma_f32_16x16x32_bf16 v[106:109], v[138:141], v[218:221], v[106:109]
	v_mfma_f32_16x16x32_bf16 v[94:97], v[130:133], v[226:229], v[94:97]
	v_mfma_f32_16x16x32_bf16 v[90:93], v[138:141], v[226:229], v[90:93]
	v_mfma_f32_16x16x32_bf16 v[78:81], v[130:133], v[234:237], v[78:81]
	v_mfma_f32_16x16x32_bf16 v[74:77], v[138:141], v[234:237], v[74:77]
	v_mfma_f32_16x16x32_bf16 v[126:129], v[134:137], v[214:217], v[126:129]
	v_mfma_f32_16x16x32_bf16 v[122:125], v[142:145], v[214:217], v[122:125]
	v_mfma_f32_16x16x32_bf16 v[110:113], v[134:137], v[222:225], v[110:113]
	v_mfma_f32_16x16x32_bf16 v[106:109], v[142:145], v[222:225], v[106:109]
	v_mfma_f32_16x16x32_bf16 v[94:97], v[134:137], v[230:233], v[94:97]
	v_mfma_f32_16x16x32_bf16 v[90:93], v[142:145], v[230:233], v[90:93]
	v_mfma_f32_16x16x32_bf16 v[78:81], v[134:137], v[238:241], v[78:81]
	v_mfma_f32_16x16x32_bf16 v[74:77], v[142:145], v[238:241], v[74:77]
	s_setprio 0
	s_setprio 1
	v_mfma_f32_16x16x32_bf16 v[118:121], v[158:161], v[210:213], v[118:121]
	v_mfma_f32_16x16x32_bf16 v[114:117], v[196:199], v[210:213], v[114:117]
	v_mfma_f32_16x16x32_bf16 v[102:105], v[158:161], v[218:221], v[102:105]
	v_mfma_f32_16x16x32_bf16 v[98:101], v[196:199], v[218:221], v[98:101]
	v_mfma_f32_16x16x32_bf16 v[86:89], v[158:161], v[226:229], v[86:89]
	v_mfma_f32_16x16x32_bf16 v[82:85], v[196:199], v[226:229], v[82:85]
	v_mfma_f32_16x16x32_bf16 v[70:73], v[158:161], v[234:237], v[70:73]
	v_mfma_f32_16x16x32_bf16 v[66:69], v[196:199], v[234:237], v[66:69]
	v_mfma_f32_16x16x32_bf16 v[118:121], v[192:195], v[214:217], v[118:121]
	v_mfma_f32_16x16x32_bf16 v[114:117], v[200:203], v[214:217], v[114:117]
	v_mfma_f32_16x16x32_bf16 v[102:105], v[192:195], v[222:225], v[102:105]
	v_mfma_f32_16x16x32_bf16 v[98:101], v[200:203], v[222:225], v[98:101]
	v_mfma_f32_16x16x32_bf16 v[86:89], v[192:195], v[230:233], v[86:89]
	v_mfma_f32_16x16x32_bf16 v[82:85], v[200:203], v[230:233], v[82:85]
	v_mfma_f32_16x16x32_bf16 v[70:73], v[192:195], v[238:241], v[70:73]
	v_mfma_f32_16x16x32_bf16 v[66:69], v[200:203], v[238:241], v[66:69]
	s_setprio 0
	s_barrier
	s_add_i32 s1, s2, s28
	v_lshl_add_u64 v[162:163], s[30:31], 0, v[0:1]
	s_mov_b32 m0, s1
	ds_read_b128 v[210:213], v191 offset:16384
	ds_read_b128 v[214:217], v191 offset:17408
	ds_read_b128 v[218:221], v191 offset:18432
	ds_read_b128 v[222:225], v191 offset:19456
	ds_read_b128 v[226:229], v191 offset:20480
	ds_read_b128 v[230:233], v191 offset:21504
	ds_read_b128 v[234:237], v191 offset:22528
	ds_read_b128 v[238:241], v191 offset:23552
	global_load_lds_dwordx4 v[162:163], off
	s_add_i32 m0, s1, 0x2000
	s_add_u32 s2, s30, 0x40000
	v_lshl_add_u64 v[164:165], s[30:31], 0, v[148:149]
	s_addc_u32 s3, s31, 0
	s_add_i32 s0, s0, s28
	global_load_lds_dwordx4 v[164:165], off
	v_lshl_add_u64 v[170:171], s[2:3], 0, v[0:1]
	s_mov_b32 m0, s0
	v_lshl_add_u64 v[206:207], s[68:69], 0, v[150:151]
	v_lshl_add_u64 v[170:171], s[2:3], 0, v[148:149]
	s_add_i32 m0, s0, 0x2000
	s_nop 0
	v_lshl_add_u64 v[170:171], s[68:69], 0, v[152:153]
	s_mov_b32 m0, s71
	s_nop 0
	global_load_lds_dwordx4 v[170:171], off
	s_mov_b32 m0, s72
	s_nop 0
	global_load_lds_dwordx4 v[206:207], off
	s_waitcnt vmcnt(6)
	s_waitcnt lgkmcnt(0)
	s_barrier
; #define PG8_STAGE(bufoff, gbase, voff) do { _Pragma("unroll") for (int _i = 0; _i < 2; ++_i) \
;         __builtin_amdgcn_global_load_lds((const unsigned*)((const char*)(gbase) + (voff)[_i]), (LAS unsigned*)(lds + (bufoff) + ldsw + _i * 8192), 16, 0, 0); } while (0)
; #define PG8_LDA(dst, b, h) do { _Pragma("unroll") for (int m = 0; m < 4; ++m) _Pragma("unroll") for (int k = 0; k < 2; ++k) dst[m][k] = *(const LAS bf16x8*)(lds + PG8_SA(b, h) + aoff + m * 2048 + k * 1024); } while (0)
; #define PG8_LDB(dst, b, h) do { _Pragma("unroll") for (int n = 0; n < 2; ++n) _Pragma("unroll") for (int k = 0; k < 2; ++k) dst[n][k] = *(const LAS bf16x8*)(lds + PG8_SB(b, h) + boff + n * 2048 + k * 1024); } while (0)
; #define PG8_MMA(ai, bj, At, Bt) do { __builtin_amdgcn_s_setprio(1); _Pragma("unroll") for (int m = 0; m < 4; ++m) _Pragma("unroll") for (int n = 0; n < 2; ++n) _Pragma("unroll") for (int k = 0; k < 2; ++k) \
;         acc[ai][bj][m][n] = __builtin_amdgcn_mfma_f32_16x16x32_bf16(Bt[n][k], At[m][k], acc[ai][bj][m][n], 0, 0, 0); __builtin_amdgcn_s_setprio(0); } while (0)
; #define PG8_WAIT_V(n) asm volatile("s_waitcnt vmcnt(" #n ")" ::: "memory")
; #define PG8_WAIT_L(n) asm volatile("s_waitcnt lgkmcnt(" #n ")" ::: "memory")
; #define PG8_BAR __builtin_amdgcn_s_barrier()
; #define PG8_SCHED __builtin_amdgcn_sched_barrier(0)
; template <class Epi>
; __device__ __forceinline__ void gemm_phase(LAS unsigned char* lds, const int tid, const Gemm g, const StaticOrder& S, const Epi& E) {
;     ...
;             PG8_WAIT_V(8); PG8_WAIT_L(0); PG8_BAR; PG8_MMA(1, 0, At, B0); PG8_MMA(1, 1, At, B1); PG8_BAR; PG8_SCHED;
;             PG8_LDB(B0, 1, 0); PG8_LDB(B1, 1, 1); PG8_SCHED; PG8_LDA(At, 1, 0); PG8_STAGE(PG8_SA(0, 1), a2 + hstepA, voffA);
;             PG8_WAIT_V(8); PG8_WAIT_L(0); PG8_BAR; PG8_MMA(0, 0, At, B0); PG8_MMA(0, 1, At, B1); PG8_BAR; PG8_SCHED;
	s_setprio 1
	s_waitcnt lgkmcnt(0)
	v_mfma_f32_16x16x32_bf16 v[62:65], v[130:133], v[210:213], v[62:65]
	v_mfma_f32_16x16x32_bf16 v[58:61], v[138:141], v[210:213], v[58:61]
	v_mfma_f32_16x16x32_bf16 v[46:49], v[130:133], v[218:221], v[46:49]
	v_mfma_f32_16x16x32_bf16 v[42:45], v[138:141], v[218:221], v[42:45]
	v_mfma_f32_16x16x32_bf16 v[30:33], v[130:133], v[226:229], v[30:33]
	v_mfma_f32_16x16x32_bf16 v[26:29], v[138:141], v[226:229], v[26:29]
	v_mfma_f32_16x16x32_bf16 v[14:17], v[130:133], v[234:237], v[14:17]
	v_mfma_f32_16x16x32_bf16 v[10:13], v[138:141], v[234:237], v[10:13]
	v_mfma_f32_16x16x32_bf16 v[62:65], v[134:137], v[214:217], v[62:65]
	v_mfma_f32_16x16x32_bf16 v[58:61], v[142:145], v[214:217], v[58:61]
	v_mfma_f32_16x16x32_bf16 v[46:49], v[134:137], v[222:225], v[46:49]
	v_mfma_f32_16x16x32_bf16 v[42:45], v[142:145], v[222:225], v[42:45]
	v_mfma_f32_16x16x32_bf16 v[30:33], v[134:137], v[230:233], v[30:33]
	v_mfma_f32_16x16x32_bf16 v[26:29], v[142:145], v[230:233], v[26:29]
	v_mfma_f32_16x16x32_bf16 v[14:17], v[134:137], v[238:241], v[14:17]
	v_mfma_f32_16x16x32_bf16 v[10:13], v[142:145], v[238:241], v[10:13]
	s_setprio 0
	s_setprio 1
	v_mfma_f32_16x16x32_bf16 v[54:57], v[158:161], v[210:213], v[54:57]
	v_mfma_f32_16x16x32_bf16 v[50:53], v[196:199], v[210:213], v[50:53]
	v_mfma_f32_16x16x32_bf16 v[38:41], v[158:161], v[218:221], v[38:41]
	v_mfma_f32_16x16x32_bf16 v[34:37], v[196:199], v[218:221], v[34:37]
	v_mfma_f32_16x16x32_bf16 v[22:25], v[158:161], v[226:229], v[22:25]
	v_mfma_f32_16x16x32_bf16 v[18:21], v[196:199], v[226:229], v[18:21]
	v_mfma_f32_16x16x32_bf16 v[6:9], v[158:161], v[234:237], v[6:9]
	v_mfma_f32_16x16x32_bf16 v[2:5], v[196:199], v[234:237], v[2:5]
	v_mfma_f32_16x16x32_bf16 v[54:57], v[192:195], v[214:217], v[54:57]
	v_mfma_f32_16x16x32_bf16 v[50:53], v[200:203], v[214:217], v[50:53]
	v_mfma_f32_16x16x32_bf16 v[38:41], v[192:195], v[222:225], v[38:41]
	v_mfma_f32_16x16x32_bf16 v[34:37], v[200:203], v[222:225], v[34:37]
	v_mfma_f32_16x16x32_bf16 v[22:25], v[192:195], v[230:233], v[22:25]
	v_mfma_f32_16x16x32_bf16 v[18:21], v[200:203], v[230:233], v[18:21]
	v_mfma_f32_16x16x32_bf16 v[6:9], v[192:195], v[238:241], v[6:9]
	v_mfma_f32_16x16x32_bf16 v[2:5], v[200:203], v[238:241], v[2:5]
	s_setprio 0
	s_barrier
	s_add_i32 s0, 0, 0x18000
	s_add_i32 s1, 0, 0x1c000
	v_add_u32_e32 v142, s0, v189
	v_add_u32_e32 v200, s1, v189
	ds_read_b128 v[130:133], v142
	ds_read_b128 v[134:137], v142 offset:1024
	ds_read_b128 v[138:141], v142 offset:2048
	ds_read_b128 v[142:145], v142 offset:3072
	ds_read_b128 v[158:161], v200
	ds_read_b128 v[192:195], v200 offset:1024
	ds_read_b128 v[196:199], v200 offset:2048
	ds_read_b128 v[200:203], v200 offset:3072
	s_add_u32 s100, s30, 0x40000
	s_addc_u32 s101, s31, 0
	v_lshl_add_u64 v[242:243], s[100:101], 0, v[0:1]
	s_add_i32 m0, s28, 0x14000
	s_nop 0
	global_load_lds_dwordx4 v[242:243], off
	v_lshl_add_u64 v[242:243], s[100:101], 0, v[148:149]
	s_add_i32 m0, s28, 0x16000
	s_nop 0
	global_load_lds_dwordx4 v[242:243], off
	s_add_u32 s2, s68, 0x80000
	s_addc_u32 s3, s69, 0
	s_mov_b32 m0, s73
	v_lshl_add_u64 v[242:243], s[2:3], 0, v[152:153]
	ds_read_b128 v[210:213], v191 offset:32768
	ds_read_b128 v[214:217], v191 offset:33792
	ds_read_b128 v[218:221], v191 offset:34816
	ds_read_b128 v[222:225], v191 offset:35840
	ds_read_b128 v[226:229], v191 offset:36864
	ds_read_b128 v[230:233], v191 offset:37888
	ds_read_b128 v[234:237], v191 offset:38912
	ds_read_b128 v[238:241], v191 offset:39936
	global_load_lds_dwordx4 v[242:243], off
	v_lshl_add_u64 v[242:243], s[2:3], 0, v[150:151]
	s_mov_b32 m0, s74
	s_nop 0
	global_load_lds_dwordx4 v[242:243], off
	s_waitcnt vmcnt(8)
	s_waitcnt lgkmcnt(0)
	s_barrier
	s_setprio 1
	s_waitcnt lgkmcnt(0)
	v_mfma_f32_16x16x32_bf16 v[126:129], v[130:133], v[210:213], v[126:129]
	v_mfma_f32_16x16x32_bf16 v[122:125], v[138:141], v[210:213], v[122:125]
	v_mfma_f32_16x16x32_bf16 v[110:113], v[130:133], v[218:221], v[110:113]
	v_mfma_f32_16x16x32_bf16 v[106:109], v[138:141], v[218:221], v[106:109]
	v_mfma_f32_16x16x32_bf16 v[94:97], v[130:133], v[226:229], v[94:97]
	v_mfma_f32_16x16x32_bf16 v[90:93], v[138:141], v[226:229], v[90:93]
	v_mfma_f32_16x16x32_bf16 v[78:81], v[130:133], v[234:237], v[78:81]
	v_mfma_f32_16x16x32_bf16 v[74:77], v[138:141], v[234:237], v[74:77]
	v_mfma_f32_16x16x32_bf16 v[126:129], v[134:137], v[214:217], v[126:129]
	v_mfma_f32_16x16x32_bf16 v[122:125], v[142:145], v[214:217], v[122:125]
	v_mfma_f32_16x16x32_bf16 v[110:113], v[134:137], v[222:225], v[110:113]
	v_mfma_f32_16x16x32_bf16 v[106:109], v[142:145], v[222:225], v[106:109]
	v_mfma_f32_16x16x32_bf16 v[94:97], v[134:137], v[230:233], v[94:97]
	v_mfma_f32_16x16x32_bf16 v[90:93], v[142:145], v[230:233], v[90:93]
	v_mfma_f32_16x16x32_bf16 v[78:81], v[134:137], v[238:241], v[78:81]
	v_mfma_f32_16x16x32_bf16 v[74:77], v[142:145], v[238:241], v[74:77]
	s_setprio 0
	s_setprio 1
	v_mfma_f32_16x16x32_bf16 v[118:121], v[158:161], v[210:213], v[118:121]
	v_mfma_f32_16x16x32_bf16 v[114:117], v[196:199], v[210:213], v[114:117]
	v_mfma_f32_16x16x32_bf16 v[102:105], v[158:161], v[218:221], v[102:105]
	v_mfma_f32_16x16x32_bf16 v[98:101], v[196:199], v[218:221], v[98:101]
	v_mfma_f32_16x16x32_bf16 v[86:89], v[158:161], v[226:229], v[86:89]
	v_mfma_f32_16x16x32_bf16 v[82:85], v[196:199], v[226:229], v[82:85]
	v_mfma_f32_16x16x32_bf16 v[70:73], v[158:161], v[234:237], v[70:73]
	v_mfma_f32_16x16x32_bf16 v[66:69], v[196:199], v[234:237], v[66:69]
	v_mfma_f32_16x16x32_bf16 v[118:121], v[192:195], v[214:217], v[118:121]
	v_mfma_f32_16x16x32_bf16 v[114:117], v[200:203], v[214:217], v[114:117]
	v_mfma_f32_16x16x32_bf16 v[102:105], v[192:195], v[222:225], v[102:105]
	v_mfma_f32_16x16x32_bf16 v[98:101], v[200:203], v[222:225], v[98:101]
	v_mfma_f32_16x16x32_bf16 v[86:89], v[192:195], v[230:233], v[86:89]
	v_mfma_f32_16x16x32_bf16 v[82:85], v[200:203], v[230:233], v[82:85]
	v_mfma_f32_16x16x32_bf16 v[70:73], v[192:195], v[238:241], v[70:73]
	v_mfma_f32_16x16x32_bf16 v[66:69], v[200:203], v[238:241], v[66:69]
	s_setprio 0
	s_barrier
; #define PG8_STAGE(bufoff, gbase, voff) do { _Pragma("unroll") for (int _i = 0; _i < 2; ++_i) \
;         __builtin_amdgcn_global_load_lds((const unsigned*)((const char*)(gbase) + (voff)[_i]), (LAS unsigned*)(lds + (bufoff) + ldsw + _i * 8192), 16, 0, 0); } while (0)
; #define PG8_LDA(dst, b, h) do { _Pragma("unroll") for (int m = 0; m < 4; ++m) _Pragma("unroll") for (int k = 0; k < 2; ++k) dst[m][k] = *(const LAS bf16x8*)(lds + PG8_SA(b, h) + aoff + m * 2048 + k * 1024); } while (0)
; #define PG8_MMA(ai, bj, At, Bt) do { __builtin_amdgcn_s_setprio(1); _Pragma("unroll") for (int m = 0; m < 4; ++m) _Pragma("unroll") for (int n = 0; n < 2; ++n) _Pragma("unroll") for (int k = 0; k < 2; ++k) \
;         acc[ai][bj][m][n] = __builtin_amdgcn_mfma_f32_16x16x32_bf16(Bt[n][k], At[m][k], acc[ai][bj][m][n], 0, 0, 0); __builtin_amdgcn_s_setprio(0); } while (0)
; #define PG8_WAIT_V(n) asm volatile("s_waitcnt vmcnt(" #n ")" ::: "memory")
; #define PG8_WAIT_L(n) asm volatile("s_waitcnt lgkmcnt(" #n ")" ::: "memory")
; #define PG8_BAR __builtin_amdgcn_s_barrier()
; #define PG8_SCHED __builtin_amdgcn_sched_barrier(0)
; template <class Epi>
; __device__ __forceinline__ void gemm_phase(LAS unsigned char* lds, const int tid, const Gemm g, const StaticOrder& S, const Epi& E) {
;     ...
;             PG8_LDA(At, 1, 1); PG8_STAGE(PG8_SB(1, 0), b3, voffB); PG8_STAGE(PG8_SB(1, 1), b3 + hstepB, voffB); PG8_STAGE(PG8_SA(1, 0), a3, voffA);
;             PG8_WAIT_V(8); PG8_WAIT_L(0); PG8_BAR; PG8_MMA(1, 0, At, B0); PG8_MMA(1, 1, At, B1); PG8_BAR; PG8_SCHED;
;         }
;         if (wr == 0) PG8_BAR;
	s_add_i32 s0, s0, s28
	v_lshl_add_u64 v[162:163], v[162:163], 0, s[36:37]
	s_mov_b32 m0, s0
	ds_read_b128 v[210:213], v191 offset:49152
	ds_read_b128 v[214:217], v191 offset:50176
	ds_read_b128 v[218:221], v191 offset:51200
	ds_read_b128 v[222:225], v191 offset:52224
	ds_read_b128 v[226:229], v191 offset:53248
	ds_read_b128 v[230:233], v191 offset:54272
	ds_read_b128 v[234:237], v191 offset:55296
	ds_read_b128 v[238:241], v191 offset:56320
	global_load_lds_dwordx4 v[162:163], off
	s_add_i32 m0, s0, 0x2000
	s_add_u32 s2, s30, 0x40080
	v_lshl_add_u64 v[162:163], v[164:165], 0, s[36:37]
	s_addc_u32 s3, s31, 0
	s_add_i32 s0, s1, s28
	global_load_lds_dwordx4 v[162:163], off
	v_lshl_add_u64 v[162:163], s[2:3], 0, v[0:1]
	s_mov_b32 m0, s0
	s_nop 0
	global_load_lds_dwordx4 v[162:163], off
	v_lshl_add_u64 v[162:163], s[2:3], 0, v[148:149]
	s_add_i32 m0, s0, 0x2000
	s_nop 0
	global_load_lds_dwordx4 v[162:163], off
	v_lshl_add_u64 v[162:163], v[170:171], 0, s[36:37]
	s_mov_b32 m0, s75
	s_nop 0
	global_load_lds_dwordx4 v[162:163], off
	v_lshl_add_u64 v[162:163], v[206:207], 0, s[36:37]
	s_mov_b32 m0, s76
	s_nop 0
	global_load_lds_dwordx4 v[162:163], off
	s_waitcnt vmcnt(8)
	s_waitcnt lgkmcnt(0)
	s_barrier
	s_setprio 1
	s_waitcnt lgkmcnt(0)
	v_mfma_f32_16x16x32_bf16 v[62:65], v[130:133], v[210:213], v[62:65]
	v_mfma_f32_16x16x32_bf16 v[58:61], v[138:141], v[210:213], v[58:61]
	v_mfma_f32_16x16x32_bf16 v[46:49], v[130:133], v[218:221], v[46:49]
	v_mfma_f32_16x16x32_bf16 v[42:45], v[138:141], v[218:221], v[42:45]
	v_mfma_f32_16x16x32_bf16 v[30:33], v[130:133], v[226:229], v[30:33]
	v_mfma_f32_16x16x32_bf16 v[26:29], v[138:141], v[226:229], v[26:29]
	v_mfma_f32_16x16x32_bf16 v[14:17], v[130:133], v[234:237], v[14:17]
	v_mfma_f32_16x16x32_bf16 v[10:13], v[138:141], v[234:237], v[10:13]
	v_mfma_f32_16x16x32_bf16 v[62:65], v[134:137], v[214:217], v[62:65]
	v_mfma_f32_16x16x32_bf16 v[58:61], v[142:145], v[214:217], v[58:61]
	v_mfma_f32_16x16x32_bf16 v[46:49], v[134:137], v[222:225], v[46:49]
	v_mfma_f32_16x16x32_bf16 v[42:45], v[142:145], v[222:225], v[42:45]
	v_mfma_f32_16x16x32_bf16 v[30:33], v[134:137], v[230:233], v[30:33]
	v_mfma_f32_16x16x32_bf16 v[26:29], v[142:145], v[230:233], v[26:29]
	v_mfma_f32_16x16x32_bf16 v[14:17], v[134:137], v[238:241], v[14:17]
	v_mfma_f32_16x16x32_bf16 v[10:13], v[142:145], v[238:241], v[10:13]
	s_setprio 0
	s_setprio 1
	v_mfma_f32_16x16x32_bf16 v[54:57], v[158:161], v[210:213], v[54:57]
	v_mfma_f32_16x16x32_bf16 v[50:53], v[196:199], v[210:213], v[50:53]
	v_mfma_f32_16x16x32_bf16 v[38:41], v[158:161], v[218:221], v[38:41]
	v_mfma_f32_16x16x32_bf16 v[34:37], v[196:199], v[218:221], v[34:37]
	v_mfma_f32_16x16x32_bf16 v[22:25], v[158:161], v[226:229], v[22:25]
	v_mfma_f32_16x16x32_bf16 v[18:21], v[196:199], v[226:229], v[18:21]
	v_mfma_f32_16x16x32_bf16 v[6:9], v[158:161], v[234:237], v[6:9]
	v_mfma_f32_16x16x32_bf16 v[2:5], v[196:199], v[234:237], v[2:5]
	v_mfma_f32_16x16x32_bf16 v[54:57], v[192:195], v[214:217], v[54:57]
	v_mfma_f32_16x16x32_bf16 v[50:53], v[200:203], v[214:217], v[50:53]
	v_mfma_f32_16x16x32_bf16 v[38:41], v[192:195], v[222:225], v[38:41]
	v_mfma_f32_16x16x32_bf16 v[34:37], v[200:203], v[222:225], v[34:37]
	v_mfma_f32_16x16x32_bf16 v[22:25], v[192:195], v[230:233], v[22:25]
	v_mfma_f32_16x16x32_bf16 v[18:21], v[200:203], v[230:233], v[18:21]
	v_mfma_f32_16x16x32_bf16 v[6:9], v[192:195], v[238:241], v[6:9]
	v_mfma_f32_16x16x32_bf16 v[2:5], v[200:203], v[238:241], v[2:5]
	s_setprio 0
	s_barrier
	s_add_i32 vcc_lo, vcc_lo, 2
	s_add_u32 s66, s66, 0x100
	s_addc_u32 s67, s67, 0
	s_add_u32 s92, s92, 0x100
	s_addc_u32 s93, s93, 0
	s_cmp_gt_u32 vcc_lo, 13
	s_cbranch_scc0 .LBB0_1333
	s_and_b64 vcc, exec, s[6:7]
	s_cbranch_vccz .LBB0_1336
	s_barrier

; #define PG8_STAGE(bufoff, gbase, voff) do { _Pragma("unroll") for (int _i = 0; _i < 2; ++_i) \
;         __builtin_amdgcn_global_load_lds((const unsigned*)((const char*)(gbase) + (voff)[_i]), (LAS unsigned*)(lds + (bufoff) + ldsw + _i * 8192), 16, 0, 0); } while (0)
; #define PG8_LDA(dst, b, h) do { _Pragma("unroll") for (int m = 0; m < 4; ++m) _Pragma("unroll") for (int k = 0; k < 2; ++k) dst[m][k] = *(const LAS bf16x8*)(lds + PG8_SA(b, h) + aoff + m * 2048 + k * 1024); } while (0)
; #define PG8_LDB(dst, b, h) do { _Pragma("unroll") for (int n = 0; n < 2; ++n) _Pragma("unroll") for (int k = 0; k < 2; ++k) dst[n][k] = *(const LAS bf16x8*)(lds + PG8_SB(b, h) + boff + n * 2048 + k * 1024); } while (0)
; #define PG8_MMA(ai, bj, At, Bt) do { __builtin_amdgcn_s_setprio(1); _Pragma("unroll") for (int m = 0; m < 4; ++m) _Pragma("unroll") for (int n = 0; n < 2; ++n) _Pragma("unroll") for (int k = 0; k < 2; ++k) \
;         acc[ai][bj][m][n] = __builtin_amdgcn_mfma_f32_16x16x32_bf16(Bt[n][k], At[m][k], acc[ai][bj][m][n], 0, 0, 0); __builtin_amdgcn_s_setprio(0); } while (0)
; #define PG8_WAIT_V(n) asm volatile("s_waitcnt vmcnt(" #n ")" ::: "memory")
; #define PG8_WAIT_L(n) asm volatile("s_waitcnt lgkmcnt(" #n ")" ::: "memory")
; #define PG8_BAR __builtin_amdgcn_s_barrier()
; #define PG8_SCHED __builtin_amdgcn_sched_barrier(0)
; template <class Epi>
; __device__ __forceinline__ void gemm_phase(LAS unsigned char* lds, const int tid, const Gemm g, const StaticOrder& S, const Epi& E) {
;     ...
;             const bool last = (t == nt - 2);
;             const char* a1 = cA + (size_t)(t + 1) * kstep;
;             const char* a2 = last ? nA : cA + (size_t)(t + 2) * kstep; const char* b2 = last ? nB : cB + (size_t)(t + 2) * kstep;
;             const char* a3 = a2 + kstep; const char* b3 = b2 + kstep;
;             PG8_LDB(B0, 0, 0); PG8_LDB(B1, 0, 1); PG8_SCHED; PG8_LDA(At, 0, 0); PG8_STAGE(PG8_SA(1, 1), a1 + hstepA, voffA);
;             PG8_WAIT_V(8); PG8_WAIT_L(0); PG8_BAR; PG8_MMA(0, 0, At, B0); PG8_MMA(0, 1, At, B1); PG8_BAR; PG8_SCHED;
;             PG8_LDA(At, 0, 1); PG8_STAGE(PG8_SB(0, 0), b2, voffB); PG8_STAGE(PG8_SB(0, 1), b2 + hstepB, voffB); PG8_STAGE(PG8_SA(0, 0), a2, voffA);
;             PG8_WAIT_V(8); PG8_WAIT_L(0); PG8_BAR; PG8_MMA(1, 0, At, B0); PG8_MMA(1, 1, At, B1); PG8_BAR; PG8_SCHED;
.LBB0_1487:
	s_add_u32 s27, s68, 0xfffc0080
	s_addc_u32 s30, s69, -1
	s_add_i32 s62, 0, 0x10000
	s_cmp_eq_u32 s26, 12
	s_cselect_b32 vcc_hi, s28, s30
	s_cselect_b32 vcc_lo, s71, s27
	s_cselect_b32 s31, s5, s83
	s_cselect_b32 s30, s73, s75
	s_add_i32 s27, 0, 0x14000
	v_add_u32_e32 v142, s62, v216
	v_add_u32_e32 v158, s27, v216
	ds_read_b128 v[130:133], v142
	ds_read_b128 v[134:137], v142 offset:1024
	ds_read_b128 v[138:141], v142 offset:2048
	ds_read_b128 v[142:145], v142 offset:3072
	ds_read_b128 v[146:149], v158
	ds_read_b128 v[150:153], v158 offset:1024
	ds_read_b128 v[154:157], v158 offset:2048
	ds_read_b128 v[158:161], v158 offset:3072
	v_lshl_add_u64 v[162:163], s[68:69], 0, v[176:177]
	s_add_i32 m0, s1, 0xc000
	ds_read_b128 v[180:183], v218
	ds_read_b128 v[184:187], v218 offset:1024
	ds_read_b128 v[220:223], v218 offset:2048
	ds_read_b128 v[224:227], v218 offset:3072
	ds_read_b128 v[228:231], v218 offset:4096
	ds_read_b128 v[232:235], v218 offset:5120
	ds_read_b128 v[236:239], v218 offset:6144
	ds_read_b128 v[240:243], v218 offset:7168
	global_load_lds_dwordx4 v[162:163], off
	v_lshl_add_u64 v[162:163], s[68:69], 0, v[178:179]
	s_add_i32 m0, s1, 0xe000
	s_nop 0
	global_load_lds_dwordx4 v[162:163], off
	s_waitcnt vmcnt(8)
	s_waitcnt lgkmcnt(0)
	s_barrier
	s_setprio 1
	s_waitcnt lgkmcnt(0)
	v_mfma_f32_16x16x32_bf16 v[126:129], v[130:133], v[180:183], v[126:129]
	v_mfma_f32_16x16x32_bf16 v[122:125], v[138:141], v[180:183], v[122:125]
	v_mfma_f32_16x16x32_bf16 v[110:113], v[130:133], v[220:223], v[110:113]
	v_mfma_f32_16x16x32_bf16 v[106:109], v[138:141], v[220:223], v[106:109]
	v_mfma_f32_16x16x32_bf16 v[94:97], v[130:133], v[228:231], v[94:97]
	v_mfma_f32_16x16x32_bf16 v[90:93], v[138:141], v[228:231], v[90:93]
	v_mfma_f32_16x16x32_bf16 v[78:81], v[130:133], v[236:239], v[78:81]
	v_mfma_f32_16x16x32_bf16 v[74:77], v[138:141], v[236:239], v[74:77]
	v_mfma_f32_16x16x32_bf16 v[126:129], v[134:137], v[184:187], v[126:129]
	v_mfma_f32_16x16x32_bf16 v[122:125], v[142:145], v[184:187], v[122:125]
	v_mfma_f32_16x16x32_bf16 v[110:113], v[134:137], v[224:227], v[110:113]
	v_mfma_f32_16x16x32_bf16 v[106:109], v[142:145], v[224:227], v[106:109]
	v_mfma_f32_16x16x32_bf16 v[94:97], v[134:137], v[232:235], v[94:97]
	v_mfma_f32_16x16x32_bf16 v[90:93], v[142:145], v[232:235], v[90:93]
	v_mfma_f32_16x16x32_bf16 v[78:81], v[134:137], v[240:243], v[78:81]
	v_mfma_f32_16x16x32_bf16 v[74:77], v[142:145], v[240:243], v[74:77]
	s_setprio 0
	s_setprio 1
	v_mfma_f32_16x16x32_bf16 v[118:121], v[146:149], v[180:183], v[118:121]
	v_mfma_f32_16x16x32_bf16 v[114:117], v[154:157], v[180:183], v[114:117]
	v_mfma_f32_16x16x32_bf16 v[102:105], v[146:149], v[220:223], v[102:105]
	v_mfma_f32_16x16x32_bf16 v[98:101], v[154:157], v[220:223], v[98:101]
	v_mfma_f32_16x16x32_bf16 v[86:89], v[146:149], v[228:231], v[86:89]
	v_mfma_f32_16x16x32_bf16 v[82:85], v[154:157], v[228:231], v[82:85]
	v_mfma_f32_16x16x32_bf16 v[70:73], v[146:149], v[236:239], v[70:73]
	v_mfma_f32_16x16x32_bf16 v[66:69], v[154:157], v[236:239], v[66:69]
	v_mfma_f32_16x16x32_bf16 v[118:121], v[150:153], v[184:187], v[118:121]
	v_mfma_f32_16x16x32_bf16 v[114:117], v[158:161], v[184:187], v[114:117]
	v_mfma_f32_16x16x32_bf16 v[102:105], v[150:153], v[224:227], v[102:105]
	v_mfma_f32_16x16x32_bf16 v[98:101], v[158:161], v[224:227], v[98:101]
	v_mfma_f32_16x16x32_bf16 v[86:89], v[150:153], v[232:235], v[86:89]
	v_mfma_f32_16x16x32_bf16 v[82:85], v[158:161], v[232:235], v[82:85]
	v_mfma_f32_16x16x32_bf16 v[70:73], v[150:153], v[240:243], v[70:73]
	v_mfma_f32_16x16x32_bf16 v[66:69], v[158:161], v[240:243], v[66:69]
	s_setprio 0
	s_barrier
	s_add_i32 s62, s62, s0
	v_lshl_add_u64 v[162:163], s[30:31], 0, v[0:1]
	s_mov_b32 m0, s62
	ds_read_b128 v[180:183], v218 offset:16384
	ds_read_b128 v[184:187], v218 offset:17408
	ds_read_b128 v[220:223], v218 offset:18432
	ds_read_b128 v[224:227], v218 offset:19456
	ds_read_b128 v[228:231], v218 offset:20480
	ds_read_b128 v[232:235], v218 offset:21504
	ds_read_b128 v[236:239], v218 offset:22528
	ds_read_b128 v[240:243], v218 offset:23552
	global_load_lds_dwordx4 v[162:163], off
	s_add_i32 m0, s62, 0x2000
	s_add_u32 s62, s30, 0x40000
	v_lshl_add_u64 v[164:165], s[30:31], 0, v[170:171]
	s_addc_u32 s63, s31, 0
	s_add_i32 s27, s27, s0
	global_load_lds_dwordx4 v[164:165], off
	v_lshl_add_u64 v[206:207], s[62:63], 0, v[0:1]
	s_mov_b32 m0, s27
	v_lshl_add_u64 v[244:245], vcc, 0, v[174:175]
	v_lshl_add_u64 v[206:207], s[62:63], 0, v[170:171]
	s_add_i32 m0, s27, 0x2000
	s_nop 0
	v_lshl_add_u64 v[206:207], vcc, 0, v[172:173]
	s_mov_b32 m0, s1
	s_nop 0
	global_load_lds_dwordx4 v[206:207], off
	s_mov_b32 m0, s2
	s_nop 0
	global_load_lds_dwordx4 v[244:245], off
	s_waitcnt vmcnt(6)
	s_waitcnt lgkmcnt(0)
	s_barrier
; #define PG8_STAGE(bufoff, gbase, voff) do { _Pragma("unroll") for (int _i = 0; _i < 2; ++_i) \
;         __builtin_amdgcn_global_load_lds((const unsigned*)((const char*)(gbase) + (voff)[_i]), (LAS unsigned*)(lds + (bufoff) + ldsw + _i * 8192), 16, 0, 0); } while (0)
; #define PG8_LDA(dst, b, h) do { _Pragma("unroll") for (int m = 0; m < 4; ++m) _Pragma("unroll") for (int k = 0; k < 2; ++k) dst[m][k] = *(const LAS bf16x8*)(lds + PG8_SA(b, h) + aoff + m * 2048 + k * 1024); } while (0)
; #define PG8_LDB(dst, b, h) do { _Pragma("unroll") for (int n = 0; n < 2; ++n) _Pragma("unroll") for (int k = 0; k < 2; ++k) dst[n][k] = *(const LAS bf16x8*)(lds + PG8_SB(b, h) + boff + n * 2048 + k * 1024); } while (0)
; #define PG8_MMA(ai, bj, At, Bt) do { __builtin_amdgcn_s_setprio(1); _Pragma("unroll") for (int m = 0; m < 4; ++m) _Pragma("unroll") for (int n = 0; n < 2; ++n) _Pragma("unroll") for (int k = 0; k < 2; ++k) \
;         acc[ai][bj][m][n] = __builtin_amdgcn_mfma_f32_16x16x32_bf16(Bt[n][k], At[m][k], acc[ai][bj][m][n], 0, 0, 0); __builtin_amdgcn_s_setprio(0); } while (0)
; #define PG8_WAIT_V(n) asm volatile("s_waitcnt vmcnt(" #n ")" ::: "memory")
; #define PG8_WAIT_L(n) asm volatile("s_waitcnt lgkmcnt(" #n ")" ::: "memory")
; #define PG8_BAR __builtin_amdgcn_s_barrier()
; #define PG8_SCHED __builtin_amdgcn_sched_barrier(0)
; template <class Epi>
; __device__ __forceinline__ void gemm_phase(LAS unsigned char* lds, const int tid, const Gemm g, const StaticOrder& S, const Epi& E) {
;     ...
;             PG8_WAIT_V(8); PG8_WAIT_L(0); PG8_BAR; PG8_MMA(1, 0, At, B0); PG8_MMA(1, 1, At, B1); PG8_BAR; PG8_SCHED;
;             PG8_LDB(B0, 1, 0); PG8_LDB(B1, 1, 1); PG8_SCHED; PG8_LDA(At, 1, 0); PG8_STAGE(PG8_SA(0, 1), a2 + hstepA, voffA);
;             PG8_WAIT_V(8); PG8_WAIT_L(0); PG8_BAR; PG8_MMA(0, 0, At, B0); PG8_MMA(0, 1, At, B1); PG8_BAR; PG8_SCHED;
	s_setprio 1
	s_waitcnt lgkmcnt(0)
	v_mfma_f32_16x16x32_bf16 v[62:65], v[130:133], v[180:183], v[62:65]
	v_mfma_f32_16x16x32_bf16 v[58:61], v[138:141], v[180:183], v[58:61]
	v_mfma_f32_16x16x32_bf16 v[46:49], v[130:133], v[220:223], v[46:49]
	v_mfma_f32_16x16x32_bf16 v[42:45], v[138:141], v[220:223], v[42:45]
	v_mfma_f32_16x16x32_bf16 v[30:33], v[130:133], v[228:231], v[30:33]
	v_mfma_f32_16x16x32_bf16 v[26:29], v[138:141], v[228:231], v[26:29]
	v_mfma_f32_16x16x32_bf16 v[14:17], v[130:133], v[236:239], v[14:17]
	v_mfma_f32_16x16x32_bf16 v[10:13], v[138:141], v[236:239], v[10:13]
	v_mfma_f32_16x16x32_bf16 v[62:65], v[134:137], v[184:187], v[62:65]
	v_mfma_f32_16x16x32_bf16 v[58:61], v[142:145], v[184:187], v[58:61]
	v_mfma_f32_16x16x32_bf16 v[46:49], v[134:137], v[224:227], v[46:49]
	v_mfma_f32_16x16x32_bf16 v[42:45], v[142:145], v[224:227], v[42:45]
	v_mfma_f32_16x16x32_bf16 v[30:33], v[134:137], v[232:235], v[30:33]
	v_mfma_f32_16x16x32_bf16 v[26:29], v[142:145], v[232:235], v[26:29]
	v_mfma_f32_16x16x32_bf16 v[14:17], v[134:137], v[240:243], v[14:17]
	v_mfma_f32_16x16x32_bf16 v[10:13], v[142:145], v[240:243], v[10:13]
	s_setprio 0
	s_setprio 1
	v_mfma_f32_16x16x32_bf16 v[54:57], v[146:149], v[180:183], v[54:57]
	v_mfma_f32_16x16x32_bf16 v[50:53], v[154:157], v[180:183], v[50:53]
	v_mfma_f32_16x16x32_bf16 v[38:41], v[146:149], v[220:223], v[38:41]
	v_mfma_f32_16x16x32_bf16 v[34:37], v[154:157], v[220:223], v[34:37]
	v_mfma_f32_16x16x32_bf16 v[22:25], v[146:149], v[228:231], v[22:25]
	v_mfma_f32_16x16x32_bf16 v[18:21], v[154:157], v[228:231], v[18:21]
	v_mfma_f32_16x16x32_bf16 v[6:9], v[146:149], v[236:239], v[6:9]
	v_mfma_f32_16x16x32_bf16 v[2:5], v[154:157], v[236:239], v[2:5]
	v_mfma_f32_16x16x32_bf16 v[54:57], v[150:153], v[184:187], v[54:57]
	v_mfma_f32_16x16x32_bf16 v[50:53], v[158:161], v[184:187], v[50:53]
	v_mfma_f32_16x16x32_bf16 v[38:41], v[150:153], v[224:227], v[38:41]
	v_mfma_f32_16x16x32_bf16 v[34:37], v[158:161], v[224:227], v[34:37]
	v_mfma_f32_16x16x32_bf16 v[22:25], v[150:153], v[232:235], v[22:25]
	v_mfma_f32_16x16x32_bf16 v[18:21], v[158:161], v[232:235], v[18:21]
	v_mfma_f32_16x16x32_bf16 v[6:9], v[150:153], v[240:243], v[6:9]
	v_mfma_f32_16x16x32_bf16 v[2:5], v[158:161], v[240:243], v[2:5]
	s_setprio 0
	s_barrier
	s_add_i32 s27, 0, 0x18000
	s_add_i32 s17, 0, 0x1c000
	v_add_u32_e32 v142, s27, v216
	v_add_u32_e32 v158, s17, v216
	ds_read_b128 v[130:133], v142
	ds_read_b128 v[134:137], v142 offset:1024
	ds_read_b128 v[138:141], v142 offset:2048
	ds_read_b128 v[142:145], v142 offset:3072
	ds_read_b128 v[146:149], v158
	ds_read_b128 v[150:153], v158 offset:1024
	ds_read_b128 v[154:157], v158 offset:2048
	ds_read_b128 v[158:161], v158 offset:3072
	s_add_u32 s100, s30, 0x40000
	s_addc_u32 s101, s31, 0
	v_lshl_add_u64 v[246:247], s[100:101], 0, v[0:1]
	s_add_i32 m0, s0, 0x14000
	s_nop 0
	global_load_lds_dwordx4 v[246:247], off
	v_lshl_add_u64 v[246:247], s[100:101], 0, v[170:171]
	s_add_i32 m0, s0, 0x16000
	s_nop 0
	global_load_lds_dwordx4 v[246:247], off
	s_add_u32 s62, vcc_lo, 0x40000
	s_addc_u32 s63, vcc_hi, 0
	s_mov_b32 m0, s3
	v_lshl_add_u64 v[246:247], s[62:63], 0, v[172:173]
	ds_read_b128 v[180:183], v218 offset:32768
	ds_read_b128 v[184:187], v218 offset:33792
	ds_read_b128 v[220:223], v218 offset:34816
	ds_read_b128 v[224:227], v218 offset:35840
	ds_read_b128 v[228:231], v218 offset:36864
	ds_read_b128 v[232:235], v218 offset:37888
	ds_read_b128 v[236:239], v218 offset:38912
	ds_read_b128 v[240:243], v218 offset:39936
	global_load_lds_dwordx4 v[246:247], off
	v_lshl_add_u64 v[246:247], s[62:63], 0, v[174:175]
	s_mov_b32 m0, s16
	s_nop 0
	global_load_lds_dwordx4 v[246:247], off
	s_waitcnt vmcnt(8)
	s_waitcnt lgkmcnt(0)
	s_barrier
	s_setprio 1
	s_waitcnt lgkmcnt(0)
	v_mfma_f32_16x16x32_bf16 v[126:129], v[130:133], v[180:183], v[126:129]
	v_mfma_f32_16x16x32_bf16 v[122:125], v[138:141], v[180:183], v[122:125]
	v_mfma_f32_16x16x32_bf16 v[110:113], v[130:133], v[220:223], v[110:113]
	v_mfma_f32_16x16x32_bf16 v[106:109], v[138:141], v[220:223], v[106:109]
	v_mfma_f32_16x16x32_bf16 v[94:97], v[130:133], v[228:231], v[94:97]
	v_mfma_f32_16x16x32_bf16 v[90:93], v[138:141], v[228:231], v[90:93]
	v_mfma_f32_16x16x32_bf16 v[78:81], v[130:133], v[236:239], v[78:81]
	v_mfma_f32_16x16x32_bf16 v[74:77], v[138:141], v[236:239], v[74:77]
	v_mfma_f32_16x16x32_bf16 v[126:129], v[134:137], v[184:187], v[126:129]
	v_mfma_f32_16x16x32_bf16 v[122:125], v[142:145], v[184:187], v[122:125]
	v_mfma_f32_16x16x32_bf16 v[110:113], v[134:137], v[224:227], v[110:113]
	v_mfma_f32_16x16x32_bf16 v[106:109], v[142:145], v[224:227], v[106:109]
	v_mfma_f32_16x16x32_bf16 v[94:97], v[134:137], v[232:235], v[94:97]
	v_mfma_f32_16x16x32_bf16 v[90:93], v[142:145], v[232:235], v[90:93]
	v_mfma_f32_16x16x32_bf16 v[78:81], v[134:137], v[240:243], v[78:81]
	v_mfma_f32_16x16x32_bf16 v[74:77], v[142:145], v[240:243], v[74:77]
	s_setprio 0
	s_setprio 1
	v_mfma_f32_16x16x32_bf16 v[118:121], v[146:149], v[180:183], v[118:121]
	v_mfma_f32_16x16x32_bf16 v[114:117], v[154:157], v[180:183], v[114:117]
	v_mfma_f32_16x16x32_bf16 v[102:105], v[146:149], v[220:223], v[102:105]
	v_mfma_f32_16x16x32_bf16 v[98:101], v[154:157], v[220:223], v[98:101]
	v_mfma_f32_16x16x32_bf16 v[86:89], v[146:149], v[228:231], v[86:89]
	v_mfma_f32_16x16x32_bf16 v[82:85], v[154:157], v[228:231], v[82:85]
	v_mfma_f32_16x16x32_bf16 v[70:73], v[146:149], v[236:239], v[70:73]
	v_mfma_f32_16x16x32_bf16 v[66:69], v[154:157], v[236:239], v[66:69]
	v_mfma_f32_16x16x32_bf16 v[118:121], v[150:153], v[184:187], v[118:121]
	v_mfma_f32_16x16x32_bf16 v[114:117], v[158:161], v[184:187], v[114:117]
	v_mfma_f32_16x16x32_bf16 v[102:105], v[150:153], v[224:227], v[102:105]
	v_mfma_f32_16x16x32_bf16 v[98:101], v[158:161], v[224:227], v[98:101]
	v_mfma_f32_16x16x32_bf16 v[86:89], v[150:153], v[232:235], v[86:89]
	v_mfma_f32_16x16x32_bf16 v[82:85], v[158:161], v[232:235], v[82:85]
	v_mfma_f32_16x16x32_bf16 v[70:73], v[150:153], v[240:243], v[70:73]
	v_mfma_f32_16x16x32_bf16 v[66:69], v[158:161], v[240:243], v[66:69]
	s_setprio 0
	s_barrier
; #define PG8_STAGE(bufoff, gbase, voff) do { _Pragma("unroll") for (int _i = 0; _i < 2; ++_i) \
;         __builtin_amdgcn_global_load_lds((const unsigned*)((const char*)(gbase) + (voff)[_i]), (LAS unsigned*)(lds + (bufoff) + ldsw + _i * 8192), 16, 0, 0); } while (0)
; #define PG8_LDA(dst, b, h) do { _Pragma("unroll") for (int m = 0; m < 4; ++m) _Pragma("unroll") for (int k = 0; k < 2; ++k) dst[m][k] = *(const LAS bf16x8*)(lds + PG8_SA(b, h) + aoff + m * 2048 + k * 1024); } while (0)
; #define PG8_MMA(ai, bj, At, Bt) do { __builtin_amdgcn_s_setprio(1); _Pragma("unroll") for (int m = 0; m < 4; ++m) _Pragma("unroll") for (int n = 0; n < 2; ++n) _Pragma("unroll") for (int k = 0; k < 2; ++k) \
;         acc[ai][bj][m][n] = __builtin_amdgcn_mfma_f32_16x16x32_bf16(Bt[n][k], At[m][k], acc[ai][bj][m][n], 0, 0, 0); __builtin_amdgcn_s_setprio(0); } while (0)
; #define PG8_WAIT_V(n) asm volatile("s_waitcnt vmcnt(" #n ")" ::: "memory")
; #define PG8_WAIT_L(n) asm volatile("s_waitcnt lgkmcnt(" #n ")" ::: "memory")
; #define PG8_BAR __builtin_amdgcn_s_barrier()
; #define PG8_SCHED __builtin_amdgcn_sched_barrier(0)
; template <class Epi>
; __device__ __forceinline__ void gemm_phase(LAS unsigned char* lds, const int tid, const Gemm g, const StaticOrder& S, const Epi& E) {
;     ...
;             PG8_LDA(At, 1, 1); PG8_STAGE(PG8_SB(1, 0), b3, voffB); PG8_STAGE(PG8_SB(1, 1), b3 + hstepB, voffB); PG8_STAGE(PG8_SA(1, 0), a3, voffA);
;             PG8_WAIT_V(8); PG8_WAIT_L(0); PG8_BAR; PG8_MMA(1, 0, At, B0); PG8_MMA(1, 1, At, B1); PG8_BAR; PG8_SCHED;
;         }
;         if (wr == 0) PG8_BAR;
	s_add_i32 s27, s27, s0
	v_lshl_add_u64 v[162:163], v[162:163], 0, s[36:37]
	s_mov_b32 m0, s27
	ds_read_b128 v[180:183], v218 offset:49152
	ds_read_b128 v[184:187], v218 offset:50176
	ds_read_b128 v[220:223], v218 offset:51200
	ds_read_b128 v[224:227], v218 offset:52224
	ds_read_b128 v[228:231], v218 offset:53248
	ds_read_b128 v[232:235], v218 offset:54272
	ds_read_b128 v[236:239], v218 offset:55296
	ds_read_b128 v[240:243], v218 offset:56320
	global_load_lds_dwordx4 v[162:163], off
	s_add_i32 m0, s27, 0x2000
	s_add_u32 s30, s30, 0x40080
	v_lshl_add_u64 v[162:163], v[164:165], 0, s[36:37]
	s_addc_u32 s31, s31, 0
	s_add_i32 s17, s17, s0
	global_load_lds_dwordx4 v[162:163], off
	v_lshl_add_u64 v[162:163], s[30:31], 0, v[0:1]
	s_mov_b32 m0, s17
	s_nop 0
	global_load_lds_dwordx4 v[162:163], off
	v_lshl_add_u64 v[162:163], s[30:31], 0, v[170:171]
	s_add_i32 m0, s17, 0x2000
	s_nop 0
	global_load_lds_dwordx4 v[162:163], off
	v_lshl_add_u64 v[162:163], v[206:207], 0, s[36:37]
	s_mov_b32 m0, s10
	s_nop 0
	global_load_lds_dwordx4 v[162:163], off
	v_lshl_add_u64 v[162:163], v[244:245], 0, s[36:37]
	s_mov_b32 m0, s11
	s_nop 0
	global_load_lds_dwordx4 v[162:163], off
	s_waitcnt vmcnt(8)
	s_waitcnt lgkmcnt(0)
	s_barrier
	s_setprio 1
	s_waitcnt lgkmcnt(0)
	v_mfma_f32_16x16x32_bf16 v[62:65], v[130:133], v[180:183], v[62:65]
	v_mfma_f32_16x16x32_bf16 v[58:61], v[138:141], v[180:183], v[58:61]
	v_mfma_f32_16x16x32_bf16 v[46:49], v[130:133], v[220:223], v[46:49]
	v_mfma_f32_16x16x32_bf16 v[42:45], v[138:141], v[220:223], v[42:45]
	v_mfma_f32_16x16x32_bf16 v[30:33], v[130:133], v[228:231], v[30:33]
	v_mfma_f32_16x16x32_bf16 v[26:29], v[138:141], v[228:231], v[26:29]
	v_mfma_f32_16x16x32_bf16 v[14:17], v[130:133], v[236:239], v[14:17]
	v_mfma_f32_16x16x32_bf16 v[10:13], v[138:141], v[236:239], v[10:13]
	v_mfma_f32_16x16x32_bf16 v[62:65], v[134:137], v[184:187], v[62:65]
	v_mfma_f32_16x16x32_bf16 v[58:61], v[142:145], v[184:187], v[58:61]
	v_mfma_f32_16x16x32_bf16 v[46:49], v[134:137], v[224:227], v[46:49]
	v_mfma_f32_16x16x32_bf16 v[42:45], v[142:145], v[224:227], v[42:45]
	v_mfma_f32_16x16x32_bf16 v[30:33], v[134:137], v[232:235], v[30:33]
	v_mfma_f32_16x16x32_bf16 v[26:29], v[142:145], v[232:235], v[26:29]
	v_mfma_f32_16x16x32_bf16 v[14:17], v[134:137], v[240:243], v[14:17]
	v_mfma_f32_16x16x32_bf16 v[10:13], v[142:145], v[240:243], v[10:13]
	s_setprio 0
	s_setprio 1
	v_mfma_f32_16x16x32_bf16 v[54:57], v[146:149], v[180:183], v[54:57]
	v_mfma_f32_16x16x32_bf16 v[50:53], v[154:157], v[180:183], v[50:53]
	v_mfma_f32_16x16x32_bf16 v[38:41], v[146:149], v[220:223], v[38:41]
	v_mfma_f32_16x16x32_bf16 v[34:37], v[154:157], v[220:223], v[34:37]
	v_mfma_f32_16x16x32_bf16 v[22:25], v[146:149], v[228:231], v[22:25]
	v_mfma_f32_16x16x32_bf16 v[18:21], v[154:157], v[228:231], v[18:21]
	v_mfma_f32_16x16x32_bf16 v[6:9], v[146:149], v[236:239], v[6:9]
	v_mfma_f32_16x16x32_bf16 v[2:5], v[154:157], v[236:239], v[2:5]
	v_mfma_f32_16x16x32_bf16 v[54:57], v[150:153], v[184:187], v[54:57]
	v_mfma_f32_16x16x32_bf16 v[50:53], v[158:161], v[184:187], v[50:53]
	v_mfma_f32_16x16x32_bf16 v[38:41], v[150:153], v[224:227], v[38:41]
	v_mfma_f32_16x16x32_bf16 v[34:37], v[158:161], v[224:227], v[34:37]
	v_mfma_f32_16x16x32_bf16 v[22:25], v[150:153], v[232:235], v[22:25]
	v_mfma_f32_16x16x32_bf16 v[18:21], v[158:161], v[232:235], v[18:21]
	v_mfma_f32_16x16x32_bf16 v[6:9], v[150:153], v[240:243], v[6:9]
	v_mfma_f32_16x16x32_bf16 v[2:5], v[158:161], v[240:243], v[2:5]
	s_setprio 0
	s_barrier
	s_add_i32 s26, s26, 2
	s_add_u32 s68, s68, 0x100
	s_addc_u32 s69, s69, 0
	s_add_u32 s75, s75, 0x100
	s_addc_u32 s83, s83, 0
	s_cmp_gt_u32 s26, 13
	s_cbranch_scc0 .LBB0_1487
	v_readlane_b32 s26, v255, 55
	v_readlane_b32 s27, v255, 56
	s_and_b64 vcc, exec, s[26:27]
	s_cbranch_vccz .LBB0_1490
	s_barrier

; #define PG8_STAGE(bufoff, gbase, voff) do { _Pragma("unroll") for (int _i = 0; _i < 2; ++_i) \
;         __builtin_amdgcn_global_load_lds((const unsigned*)((const char*)(gbase) + (voff)[_i]), (LAS unsigned*)(lds + (bufoff) + ldsw + _i * 8192), 16, 0, 0); } while (0)
; #define PG8_LDA(dst, b, h) do { _Pragma("unroll") for (int m = 0; m < 4; ++m) _Pragma("unroll") for (int k = 0; k < 2; ++k) dst[m][k] = *(const LAS bf16x8*)(lds + PG8_SA(b, h) + aoff + m * 2048 + k * 1024); } while (0)
; #define PG8_LDB(dst, b, h) do { _Pragma("unroll") for (int n = 0; n < 2; ++n) _Pragma("unroll") for (int k = 0; k < 2; ++k) dst[n][k] = *(const LAS bf16x8*)(lds + PG8_SB(b, h) + boff + n * 2048 + k * 1024); } while (0)
; #define PG8_MMA(ai, bj, At, Bt) do { __builtin_amdgcn_s_setprio(1); _Pragma("unroll") for (int m = 0; m < 4; ++m) _Pragma("unroll") for (int n = 0; n < 2; ++n) _Pragma("unroll") for (int k = 0; k < 2; ++k) \
;         acc[ai][bj][m][n] = __builtin_amdgcn_mfma_f32_16x16x32_bf16(Bt[n][k], At[m][k], acc[ai][bj][m][n], 0, 0, 0); __builtin_amdgcn_s_setprio(0); } while (0)
; #define PG8_WAIT_V(n) asm volatile("s_waitcnt vmcnt(" #n ")" ::: "memory")
; #define PG8_WAIT_L(n) asm volatile("s_waitcnt lgkmcnt(" #n ")" ::: "memory")
; #define PG8_BAR __builtin_amdgcn_s_barrier()
; #define PG8_SCHED __builtin_amdgcn_sched_barrier(0)
; template <class Epi>
; __device__ __forceinline__ void gemm_phase(LAS unsigned char* lds, const int tid, const Gemm g, const StaticOrder& S, const Epi& E) {
;     ...
;             const bool last = (t == nt - 2);
;             const char* a1 = cA + (size_t)(t + 1) * kstep;
;             const char* a2 = last ? nA : cA + (size_t)(t + 2) * kstep; const char* b2 = last ? nB : cB + (size_t)(t + 2) * kstep;
;             const char* a3 = a2 + kstep; const char* b3 = b2 + kstep;
;             PG8_LDB(B0, 0, 0); PG8_LDB(B1, 0, 1); PG8_SCHED; PG8_LDA(At, 0, 0); PG8_STAGE(PG8_SA(1, 1), a1 + hstepA, voffA);
;             PG8_WAIT_V(8); PG8_WAIT_L(0); PG8_BAR; PG8_MMA(0, 0, At, B0); PG8_MMA(0, 1, At, B1); PG8_BAR; PG8_SCHED;
;             PG8_LDA(At, 0, 1); PG8_STAGE(PG8_SB(0, 0), b2, voffB); PG8_STAGE(PG8_SB(0, 1), b2 + hstepB, voffB); PG8_STAGE(PG8_SA(0, 0), a2, voffA);
;             PG8_WAIT_V(8); PG8_WAIT_L(0); PG8_BAR; PG8_MMA(1, 0, At, B0); PG8_MMA(1, 1, At, B1); PG8_BAR; PG8_SCHED;
.LBB0_1912:
	s_add_u32 s30, s82, 0xfffc0080
	s_addc_u32 s31, s83, -1
	s_add_i32 s92, 0, 0x10000
	s_cmp_eq_u32 s17, 12
	s_cselect_b32 s89, s7, s31
	s_cselect_b32 s88, s65, s30
	s_cselect_b32 s31, s5, s27
	s_cselect_b32 s30, vcc_lo, vcc_hi
	s_add_i32 s11, 0, 0x14000
	v_add_u32_e32 v110, s92, v158
	v_add_u32_e32 v162, s11, v158
	ds_read_b128 v[98:101], v110
	ds_read_b128 v[102:105], v110 offset:1024
	ds_read_b128 v[106:109], v110 offset:2048
	ds_read_b128 v[110:113], v110 offset:3072
	ds_read_b128 v[174:177], v162
	ds_read_b128 v[178:181], v162 offset:1024
	ds_read_b128 v[182:185], v162 offset:2048
	ds_read_b128 v[186:189], v162 offset:3072
	v_lshl_add_u64 v[162:163], s[82:83], 0, v[152:153]
	s_add_i32 m0, s66, 0xc000
	ds_read_b128 v[190:193], v172
	ds_read_b128 v[194:197], v172 offset:1024
	ds_read_b128 v[198:201], v172 offset:2048
	ds_read_b128 v[210:213], v172 offset:3072
	ds_read_b128 v[214:217], v172 offset:4096
	ds_read_b128 v[218:221], v172 offset:5120
	ds_read_b128 v[222:225], v172 offset:6144
	ds_read_b128 v[226:229], v172 offset:7168
	global_load_lds_dwordx4 v[162:163], off
	v_lshl_add_u64 v[162:163], s[82:83], 0, v[154:155]
	s_add_i32 m0, s66, 0xe000
	s_nop 0
	global_load_lds_dwordx4 v[162:163], off
	s_waitcnt vmcnt(8)
	s_waitcnt lgkmcnt(0)
	s_barrier
	s_setprio 1
	s_waitcnt lgkmcnt(0)
	v_mfma_f32_16x16x32_bf16 v[142:145], v[98:101], v[190:193], v[142:145]
	v_mfma_f32_16x16x32_bf16 v[138:141], v[106:109], v[190:193], v[138:141]
	v_mfma_f32_16x16x32_bf16 v[134:137], v[98:101], v[198:201], v[134:137]
	v_mfma_f32_16x16x32_bf16 v[130:133], v[106:109], v[198:201], v[130:133]
	v_mfma_f32_16x16x32_bf16 v[94:97], v[98:101], v[214:217], v[94:97]
	v_mfma_f32_16x16x32_bf16 v[90:93], v[106:109], v[214:217], v[90:93]
	v_mfma_f32_16x16x32_bf16 v[78:81], v[98:101], v[222:225], v[78:81]
	v_mfma_f32_16x16x32_bf16 v[74:77], v[106:109], v[222:225], v[74:77]
	v_mfma_f32_16x16x32_bf16 v[142:145], v[102:105], v[194:197], v[142:145]
	v_mfma_f32_16x16x32_bf16 v[138:141], v[110:113], v[194:197], v[138:141]
	v_mfma_f32_16x16x32_bf16 v[134:137], v[102:105], v[210:213], v[134:137]
	v_mfma_f32_16x16x32_bf16 v[130:133], v[110:113], v[210:213], v[130:133]
	v_mfma_f32_16x16x32_bf16 v[94:97], v[102:105], v[218:221], v[94:97]
	v_mfma_f32_16x16x32_bf16 v[90:93], v[110:113], v[218:221], v[90:93]
	v_mfma_f32_16x16x32_bf16 v[78:81], v[102:105], v[226:229], v[78:81]
	v_mfma_f32_16x16x32_bf16 v[74:77], v[110:113], v[226:229], v[74:77]
	s_setprio 0
	s_setprio 1
	v_mfma_f32_16x16x32_bf16 v[126:129], v[174:177], v[190:193], v[126:129]
	v_mfma_f32_16x16x32_bf16 v[122:125], v[182:185], v[190:193], v[122:125]
	v_mfma_f32_16x16x32_bf16 v[118:121], v[174:177], v[198:201], v[118:121]
	v_mfma_f32_16x16x32_bf16 v[114:117], v[182:185], v[198:201], v[114:117]
	v_mfma_f32_16x16x32_bf16 v[86:89], v[174:177], v[214:217], v[86:89]
	v_mfma_f32_16x16x32_bf16 v[82:85], v[182:185], v[214:217], v[82:85]
	v_mfma_f32_16x16x32_bf16 v[70:73], v[174:177], v[222:225], v[70:73]
	v_mfma_f32_16x16x32_bf16 v[66:69], v[182:185], v[222:225], v[66:69]
	v_mfma_f32_16x16x32_bf16 v[126:129], v[178:181], v[194:197], v[126:129]
	v_mfma_f32_16x16x32_bf16 v[122:125], v[186:189], v[194:197], v[122:125]
	v_mfma_f32_16x16x32_bf16 v[118:121], v[178:181], v[210:213], v[118:121]
	v_mfma_f32_16x16x32_bf16 v[114:117], v[186:189], v[210:213], v[114:117]
	v_mfma_f32_16x16x32_bf16 v[86:89], v[178:181], v[218:221], v[86:89]
	v_mfma_f32_16x16x32_bf16 v[82:85], v[186:189], v[218:221], v[82:85]
	v_mfma_f32_16x16x32_bf16 v[70:73], v[178:181], v[226:229], v[70:73]
	v_mfma_f32_16x16x32_bf16 v[66:69], v[186:189], v[226:229], v[66:69]
	s_setprio 0
	s_barrier
	s_add_i32 s92, s92, s28
	v_lshl_add_u64 v[162:163], s[30:31], 0, v[0:1]
	s_mov_b32 m0, s92
	ds_read_b128 v[190:193], v172 offset:16384
	ds_read_b128 v[194:197], v172 offset:17408
	ds_read_b128 v[198:201], v172 offset:18432
	ds_read_b128 v[210:213], v172 offset:19456
	ds_read_b128 v[214:217], v172 offset:20480
	ds_read_b128 v[218:221], v172 offset:21504
	ds_read_b128 v[222:225], v172 offset:22528
	ds_read_b128 v[226:229], v172 offset:23552
	global_load_lds_dwordx4 v[162:163], off
	s_add_i32 m0, s92, 0x2000
	s_add_u32 s92, s30, 0x40000
	v_lshl_add_u64 v[164:165], s[30:31], 0, v[146:147]
	s_addc_u32 s93, s31, 0
	s_add_i32 s11, s11, s28
	global_load_lds_dwordx4 v[164:165], off
	v_lshl_add_u64 v[202:203], s[92:93], 0, v[0:1]
	s_mov_b32 m0, s11
	v_lshl_add_u64 v[206:207], s[88:89], 0, v[148:149]
	v_lshl_add_u64 v[202:203], s[92:93], 0, v[146:147]
	s_add_i32 m0, s11, 0x2000
	s_nop 0
	v_lshl_add_u64 v[202:203], s[88:89], 0, v[150:151]
	s_mov_b32 m0, s66
	s_nop 0
	global_load_lds_dwordx4 v[202:203], off
	s_mov_b32 m0, s67
	s_nop 0
	global_load_lds_dwordx4 v[206:207], off
	s_waitcnt vmcnt(6)
	s_waitcnt lgkmcnt(0)
	s_barrier
; #define PG8_STAGE(bufoff, gbase, voff) do { _Pragma("unroll") for (int _i = 0; _i < 2; ++_i) \
;         __builtin_amdgcn_global_load_lds((const unsigned*)((const char*)(gbase) + (voff)[_i]), (LAS unsigned*)(lds + (bufoff) + ldsw + _i * 8192), 16, 0, 0); } while (0)
; #define PG8_LDA(dst, b, h) do { _Pragma("unroll") for (int m = 0; m < 4; ++m) _Pragma("unroll") for (int k = 0; k < 2; ++k) dst[m][k] = *(const LAS bf16x8*)(lds + PG8_SA(b, h) + aoff + m * 2048 + k * 1024); } while (0)
; #define PG8_LDB(dst, b, h) do { _Pragma("unroll") for (int n = 0; n < 2; ++n) _Pragma("unroll") for (int k = 0; k < 2; ++k) dst[n][k] = *(const LAS bf16x8*)(lds + PG8_SB(b, h) + boff + n * 2048 + k * 1024); } while (0)
; #define PG8_MMA(ai, bj, At, Bt) do { __builtin_amdgcn_s_setprio(1); _Pragma("unroll") for (int m = 0; m < 4; ++m) _Pragma("unroll") for (int n = 0; n < 2; ++n) _Pragma("unroll") for (int k = 0; k < 2; ++k) \
;         acc[ai][bj][m][n] = __builtin_amdgcn_mfma_f32_16x16x32_bf16(Bt[n][k], At[m][k], acc[ai][bj][m][n], 0, 0, 0); __builtin_amdgcn_s_setprio(0); } while (0)
; #define PG8_WAIT_V(n) asm volatile("s_waitcnt vmcnt(" #n ")" ::: "memory")
; #define PG8_WAIT_L(n) asm volatile("s_waitcnt lgkmcnt(" #n ")" ::: "memory")
; #define PG8_BAR __builtin_amdgcn_s_barrier()
; #define PG8_SCHED __builtin_amdgcn_sched_barrier(0)
; template <class Epi>
; __device__ __forceinline__ void gemm_phase(LAS unsigned char* lds, const int tid, const Gemm g, const StaticOrder& S, const Epi& E) {
;     ...
;             PG8_WAIT_V(8); PG8_WAIT_L(0); PG8_BAR; PG8_MMA(1, 0, At, B0); PG8_MMA(1, 1, At, B1); PG8_BAR; PG8_SCHED;
;             PG8_LDB(B0, 1, 0); PG8_LDB(B1, 1, 1); PG8_SCHED; PG8_LDA(At, 1, 0); PG8_STAGE(PG8_SA(0, 1), a2 + hstepA, voffA);
;             PG8_WAIT_V(8); PG8_WAIT_L(0); PG8_BAR; PG8_MMA(0, 0, At, B0); PG8_MMA(0, 1, At, B1); PG8_BAR; PG8_SCHED;
	s_setprio 1
	s_waitcnt lgkmcnt(0)
	v_mfma_f32_16x16x32_bf16 v[62:65], v[98:101], v[190:193], v[62:65]
	v_mfma_f32_16x16x32_bf16 v[58:61], v[106:109], v[190:193], v[58:61]
	v_mfma_f32_16x16x32_bf16 v[54:57], v[98:101], v[198:201], v[54:57]
	v_mfma_f32_16x16x32_bf16 v[46:49], v[106:109], v[198:201], v[46:49]
	v_mfma_f32_16x16x32_bf16 v[30:33], v[98:101], v[214:217], v[30:33]
	v_mfma_f32_16x16x32_bf16 v[26:29], v[106:109], v[214:217], v[26:29]
	v_mfma_f32_16x16x32_bf16 v[22:25], v[98:101], v[222:225], v[22:25]
	v_mfma_f32_16x16x32_bf16 v[14:17], v[106:109], v[222:225], v[14:17]
	v_mfma_f32_16x16x32_bf16 v[62:65], v[102:105], v[194:197], v[62:65]
	v_mfma_f32_16x16x32_bf16 v[58:61], v[110:113], v[194:197], v[58:61]
	v_mfma_f32_16x16x32_bf16 v[54:57], v[102:105], v[210:213], v[54:57]
	v_mfma_f32_16x16x32_bf16 v[46:49], v[110:113], v[210:213], v[46:49]
	v_mfma_f32_16x16x32_bf16 v[30:33], v[102:105], v[218:221], v[30:33]
	v_mfma_f32_16x16x32_bf16 v[26:29], v[110:113], v[218:221], v[26:29]
	v_mfma_f32_16x16x32_bf16 v[22:25], v[102:105], v[226:229], v[22:25]
	v_mfma_f32_16x16x32_bf16 v[14:17], v[110:113], v[226:229], v[14:17]
	s_setprio 0
	s_setprio 1
	v_mfma_f32_16x16x32_bf16 v[50:53], v[174:177], v[190:193], v[50:53]
	v_mfma_f32_16x16x32_bf16 v[42:45], v[182:185], v[190:193], v[42:45]
	v_mfma_f32_16x16x32_bf16 v[38:41], v[174:177], v[198:201], v[38:41]
	v_mfma_f32_16x16x32_bf16 v[34:37], v[182:185], v[198:201], v[34:37]
	v_mfma_f32_16x16x32_bf16 v[18:21], v[174:177], v[214:217], v[18:21]
	v_mfma_f32_16x16x32_bf16 v[10:13], v[182:185], v[214:217], v[10:13]
	v_mfma_f32_16x16x32_bf16 v[6:9], v[174:177], v[222:225], v[6:9]
	v_mfma_f32_16x16x32_bf16 v[2:5], v[182:185], v[222:225], v[2:5]
	v_mfma_f32_16x16x32_bf16 v[50:53], v[178:181], v[194:197], v[50:53]
	v_mfma_f32_16x16x32_bf16 v[42:45], v[186:189], v[194:197], v[42:45]
	v_mfma_f32_16x16x32_bf16 v[38:41], v[178:181], v[210:213], v[38:41]
	v_mfma_f32_16x16x32_bf16 v[34:37], v[186:189], v[210:213], v[34:37]
	v_mfma_f32_16x16x32_bf16 v[18:21], v[178:181], v[218:221], v[18:21]
	v_mfma_f32_16x16x32_bf16 v[10:13], v[186:189], v[218:221], v[10:13]
	v_mfma_f32_16x16x32_bf16 v[6:9], v[178:181], v[226:229], v[6:9]
	v_mfma_f32_16x16x32_bf16 v[2:5], v[186:189], v[226:229], v[2:5]
	s_setprio 0
	s_barrier
	s_add_i32 s11, 0, 0x18000
	s_add_i32 s92, 0, 0x1c000
	v_add_u32_e32 v110, s11, v158
	v_add_u32_e32 v173, s92, v158
	ds_read_b128 v[98:101], v110
	ds_read_b128 v[102:105], v110 offset:1024
	ds_read_b128 v[106:109], v110 offset:2048
	ds_read_b128 v[110:113], v110 offset:3072
	ds_read_b128 v[174:177], v173
	ds_read_b128 v[178:181], v173 offset:1024
	ds_read_b128 v[182:185], v173 offset:2048
	ds_read_b128 v[186:189], v173 offset:3072
	s_add_u32 s100, s30, 0x40000
	s_addc_u32 s101, s31, 0
	v_lshl_add_u64 v[230:231], s[100:101], 0, v[0:1]
	s_add_i32 m0, s28, 0x14000
	s_nop 0
	global_load_lds_dwordx4 v[230:231], off
	v_lshl_add_u64 v[230:231], s[100:101], 0, v[146:147]
	s_add_i32 m0, s28, 0x16000
	s_nop 0
	global_load_lds_dwordx4 v[230:231], off
	s_add_u32 s88, s88, 0x40000
	s_addc_u32 s89, s89, 0
	s_mov_b32 m0, s70
	v_lshl_add_u64 v[230:231], s[88:89], 0, v[150:151]
	ds_read_b128 v[190:193], v172 offset:32768
	ds_read_b128 v[194:197], v172 offset:33792
	ds_read_b128 v[198:201], v172 offset:34816
	ds_read_b128 v[210:213], v172 offset:35840
	ds_read_b128 v[214:217], v172 offset:36864
	ds_read_b128 v[218:221], v172 offset:37888
	ds_read_b128 v[222:225], v172 offset:38912
	ds_read_b128 v[226:229], v172 offset:39936
	global_load_lds_dwordx4 v[230:231], off
	v_lshl_add_u64 v[230:231], s[88:89], 0, v[148:149]
	s_mov_b32 m0, s71
	s_nop 0
	global_load_lds_dwordx4 v[230:231], off
	s_waitcnt vmcnt(8)
	s_waitcnt lgkmcnt(0)
	s_barrier
	s_setprio 1
	s_waitcnt lgkmcnt(0)
	v_mfma_f32_16x16x32_bf16 v[142:145], v[98:101], v[190:193], v[142:145]
	v_mfma_f32_16x16x32_bf16 v[138:141], v[106:109], v[190:193], v[138:141]
	v_mfma_f32_16x16x32_bf16 v[134:137], v[98:101], v[198:201], v[134:137]
	v_mfma_f32_16x16x32_bf16 v[130:133], v[106:109], v[198:201], v[130:133]
	v_mfma_f32_16x16x32_bf16 v[94:97], v[98:101], v[214:217], v[94:97]
	v_mfma_f32_16x16x32_bf16 v[90:93], v[106:109], v[214:217], v[90:93]
	v_mfma_f32_16x16x32_bf16 v[78:81], v[98:101], v[222:225], v[78:81]
	v_mfma_f32_16x16x32_bf16 v[74:77], v[106:109], v[222:225], v[74:77]
	v_mfma_f32_16x16x32_bf16 v[142:145], v[102:105], v[194:197], v[142:145]
	v_mfma_f32_16x16x32_bf16 v[138:141], v[110:113], v[194:197], v[138:141]
	v_mfma_f32_16x16x32_bf16 v[134:137], v[102:105], v[210:213], v[134:137]
	v_mfma_f32_16x16x32_bf16 v[130:133], v[110:113], v[210:213], v[130:133]
	v_mfma_f32_16x16x32_bf16 v[94:97], v[102:105], v[218:221], v[94:97]
	v_mfma_f32_16x16x32_bf16 v[90:93], v[110:113], v[218:221], v[90:93]
	v_mfma_f32_16x16x32_bf16 v[78:81], v[102:105], v[226:229], v[78:81]
	v_mfma_f32_16x16x32_bf16 v[74:77], v[110:113], v[226:229], v[74:77]
	s_setprio 0
	s_setprio 1
	v_mfma_f32_16x16x32_bf16 v[126:129], v[174:177], v[190:193], v[126:129]
	v_mfma_f32_16x16x32_bf16 v[122:125], v[182:185], v[190:193], v[122:125]
	v_mfma_f32_16x16x32_bf16 v[118:121], v[174:177], v[198:201], v[118:121]
	v_mfma_f32_16x16x32_bf16 v[114:117], v[182:185], v[198:201], v[114:117]
	v_mfma_f32_16x16x32_bf16 v[86:89], v[174:177], v[214:217], v[86:89]
	v_mfma_f32_16x16x32_bf16 v[82:85], v[182:185], v[214:217], v[82:85]
	v_mfma_f32_16x16x32_bf16 v[70:73], v[174:177], v[222:225], v[70:73]
	v_mfma_f32_16x16x32_bf16 v[66:69], v[182:185], v[222:225], v[66:69]
	v_mfma_f32_16x16x32_bf16 v[126:129], v[178:181], v[194:197], v[126:129]
	v_mfma_f32_16x16x32_bf16 v[122:125], v[186:189], v[194:197], v[122:125]
	v_mfma_f32_16x16x32_bf16 v[118:121], v[178:181], v[210:213], v[118:121]
	v_mfma_f32_16x16x32_bf16 v[114:117], v[186:189], v[210:213], v[114:117]
	v_mfma_f32_16x16x32_bf16 v[86:89], v[178:181], v[218:221], v[86:89]
	v_mfma_f32_16x16x32_bf16 v[82:85], v[186:189], v[218:221], v[82:85]
	v_mfma_f32_16x16x32_bf16 v[70:73], v[178:181], v[226:229], v[70:73]
	v_mfma_f32_16x16x32_bf16 v[66:69], v[186:189], v[226:229], v[66:69]
	s_setprio 0
	s_barrier
; #define PG8_STAGE(bufoff, gbase, voff) do { _Pragma("unroll") for (int _i = 0; _i < 2; ++_i) \
;         __builtin_amdgcn_global_load_lds((const unsigned*)((const char*)(gbase) + (voff)[_i]), (LAS unsigned*)(lds + (bufoff) + ldsw + _i * 8192), 16, 0, 0); } while (0)
; #define PG8_LDA(dst, b, h) do { _Pragma("unroll") for (int m = 0; m < 4; ++m) _Pragma("unroll") for (int k = 0; k < 2; ++k) dst[m][k] = *(const LAS bf16x8*)(lds + PG8_SA(b, h) + aoff + m * 2048 + k * 1024); } while (0)
; #define PG8_MMA(ai, bj, At, Bt) do { __builtin_amdgcn_s_setprio(1); _Pragma("unroll") for (int m = 0; m < 4; ++m) _Pragma("unroll") for (int n = 0; n < 2; ++n) _Pragma("unroll") for (int k = 0; k < 2; ++k) \
;         acc[ai][bj][m][n] = __builtin_amdgcn_mfma_f32_16x16x32_bf16(Bt[n][k], At[m][k], acc[ai][bj][m][n], 0, 0, 0); __builtin_amdgcn_s_setprio(0); } while (0)
; #define PG8_WAIT_V(n) asm volatile("s_waitcnt vmcnt(" #n ")" ::: "memory")
; #define PG8_WAIT_L(n) asm volatile("s_waitcnt lgkmcnt(" #n ")" ::: "memory")
; #define PG8_BAR __builtin_amdgcn_s_barrier()
; #define PG8_SCHED __builtin_amdgcn_sched_barrier(0)
; template <class Epi>
; __device__ __forceinline__ void gemm_phase(LAS unsigned char* lds, const int tid, const Gemm g, const StaticOrder& S, const Epi& E) {
;     ...
;             PG8_LDA(At, 1, 1); PG8_STAGE(PG8_SB(1, 0), b3, voffB); PG8_STAGE(PG8_SB(1, 1), b3 + hstepB, voffB); PG8_STAGE(PG8_SA(1, 0), a3, voffA);
;             PG8_WAIT_V(8); PG8_WAIT_L(0); PG8_BAR; PG8_MMA(1, 0, At, B0); PG8_MMA(1, 1, At, B1); PG8_BAR; PG8_SCHED;
;         }
;         if (wr == 0) PG8_BAR;
	s_add_i32 s11, s11, s28
	v_lshl_add_u64 v[162:163], v[162:163], 0, s[36:37]
	s_mov_b32 m0, s11
	ds_read_b128 v[190:193], v172 offset:49152
	ds_read_b128 v[194:197], v172 offset:50176
	ds_read_b128 v[198:201], v172 offset:51200
	ds_read_b128 v[210:213], v172 offset:52224
	ds_read_b128 v[214:217], v172 offset:53248
	ds_read_b128 v[218:221], v172 offset:54272
	ds_read_b128 v[222:225], v172 offset:55296
	ds_read_b128 v[226:229], v172 offset:56320
	global_load_lds_dwordx4 v[162:163], off
	s_add_i32 m0, s11, 0x2000
	s_add_u32 s30, s30, 0x40080
	v_lshl_add_u64 v[162:163], v[164:165], 0, s[36:37]
	s_addc_u32 s31, s31, 0
	s_add_i32 s11, s92, s28
	global_load_lds_dwordx4 v[162:163], off
	v_lshl_add_u64 v[162:163], s[30:31], 0, v[0:1]
	s_mov_b32 m0, s11
	s_nop 0
	global_load_lds_dwordx4 v[162:163], off
	v_lshl_add_u64 v[162:163], s[30:31], 0, v[146:147]
	s_add_i32 m0, s11, 0x2000
	s_nop 0
	global_load_lds_dwordx4 v[162:163], off
	v_lshl_add_u64 v[162:163], v[202:203], 0, s[36:37]
	s_mov_b32 m0, s72
	s_nop 0
	global_load_lds_dwordx4 v[162:163], off
	v_lshl_add_u64 v[162:163], v[206:207], 0, s[36:37]
	s_mov_b32 m0, s73
	s_nop 0
	global_load_lds_dwordx4 v[162:163], off
	s_waitcnt vmcnt(8)
	s_waitcnt lgkmcnt(0)
	s_barrier
	s_setprio 1
	s_waitcnt lgkmcnt(0)
	v_mfma_f32_16x16x32_bf16 v[62:65], v[98:101], v[190:193], v[62:65]
	v_mfma_f32_16x16x32_bf16 v[58:61], v[106:109], v[190:193], v[58:61]
	v_mfma_f32_16x16x32_bf16 v[54:57], v[98:101], v[198:201], v[54:57]
	v_mfma_f32_16x16x32_bf16 v[46:49], v[106:109], v[198:201], v[46:49]
	v_mfma_f32_16x16x32_bf16 v[30:33], v[98:101], v[214:217], v[30:33]
	v_mfma_f32_16x16x32_bf16 v[26:29], v[106:109], v[214:217], v[26:29]
	v_mfma_f32_16x16x32_bf16 v[22:25], v[98:101], v[222:225], v[22:25]
	v_mfma_f32_16x16x32_bf16 v[14:17], v[106:109], v[222:225], v[14:17]
	v_mfma_f32_16x16x32_bf16 v[62:65], v[102:105], v[194:197], v[62:65]
	v_mfma_f32_16x16x32_bf16 v[58:61], v[110:113], v[194:197], v[58:61]
	v_mfma_f32_16x16x32_bf16 v[54:57], v[102:105], v[210:213], v[54:57]
	v_mfma_f32_16x16x32_bf16 v[46:49], v[110:113], v[210:213], v[46:49]
	v_mfma_f32_16x16x32_bf16 v[30:33], v[102:105], v[218:221], v[30:33]
	v_mfma_f32_16x16x32_bf16 v[26:29], v[110:113], v[218:221], v[26:29]
	v_mfma_f32_16x16x32_bf16 v[22:25], v[102:105], v[226:229], v[22:25]
	v_mfma_f32_16x16x32_bf16 v[14:17], v[110:113], v[226:229], v[14:17]
	s_setprio 0
	s_setprio 1
	v_mfma_f32_16x16x32_bf16 v[50:53], v[174:177], v[190:193], v[50:53]
	v_mfma_f32_16x16x32_bf16 v[42:45], v[182:185], v[190:193], v[42:45]
	v_mfma_f32_16x16x32_bf16 v[38:41], v[174:177], v[198:201], v[38:41]
	v_mfma_f32_16x16x32_bf16 v[34:37], v[182:185], v[198:201], v[34:37]
	v_mfma_f32_16x16x32_bf16 v[18:21], v[174:177], v[214:217], v[18:21]
	v_mfma_f32_16x16x32_bf16 v[10:13], v[182:185], v[214:217], v[10:13]
	v_mfma_f32_16x16x32_bf16 v[6:9], v[174:177], v[222:225], v[6:9]
	v_mfma_f32_16x16x32_bf16 v[2:5], v[182:185], v[222:225], v[2:5]
	v_mfma_f32_16x16x32_bf16 v[50:53], v[178:181], v[194:197], v[50:53]
	v_mfma_f32_16x16x32_bf16 v[42:45], v[186:189], v[194:197], v[42:45]
	v_mfma_f32_16x16x32_bf16 v[38:41], v[178:181], v[210:213], v[38:41]
	v_mfma_f32_16x16x32_bf16 v[34:37], v[186:189], v[210:213], v[34:37]
	v_mfma_f32_16x16x32_bf16 v[18:21], v[178:181], v[218:221], v[18:21]
	v_mfma_f32_16x16x32_bf16 v[10:13], v[186:189], v[218:221], v[10:13]
	v_mfma_f32_16x16x32_bf16 v[6:9], v[178:181], v[226:229], v[6:9]
	v_mfma_f32_16x16x32_bf16 v[2:5], v[186:189], v[226:229], v[2:5]
	s_setprio 0
	s_barrier
	s_add_i32 s17, s17, 2
	s_add_u32 s82, s82, 0x100
	s_addc_u32 s83, s83, 0
	s_add_u32 vcc_hi, vcc_hi, 0x100
	s_addc_u32 s27, s27, 0
	s_cmp_gt_u32 s17, 13
	s_cbranch_scc0 .LBB0_1912
	s_and_b64 vcc, exec, s[2:3]
	s_cbranch_vccz .LBB0_1915
	s_barrier

; #define PG8_STAGE(bufoff, gbase, voff) do { _Pragma("unroll") for (int _i = 0; _i < 2; ++_i) \
;         __builtin_amdgcn_global_load_lds((const unsigned*)((const char*)(gbase) + (voff)[_i]), (LAS unsigned*)(lds + (bufoff) + ldsw + _i * 8192), 16, 0, 0); } while (0)
; #define PG8_LDA(dst, b, h) do { _Pragma("unroll") for (int m = 0; m < 4; ++m) _Pragma("unroll") for (int k = 0; k < 2; ++k) dst[m][k] = *(const LAS bf16x8*)(lds + PG8_SA(b, h) + aoff + m * 2048 + k * 1024); } while (0)
; #define PG8_LDB(dst, b, h) do { _Pragma("unroll") for (int n = 0; n < 2; ++n) _Pragma("unroll") for (int k = 0; k < 2; ++k) dst[n][k] = *(const LAS bf16x8*)(lds + PG8_SB(b, h) + boff + n * 2048 + k * 1024); } while (0)
; #define PG8_MMA(ai, bj, At, Bt) do { __builtin_amdgcn_s_setprio(1); _Pragma("unroll") for (int m = 0; m < 4; ++m) _Pragma("unroll") for (int n = 0; n < 2; ++n) _Pragma("unroll") for (int k = 0; k < 2; ++k) \
;         acc[ai][bj][m][n] = __builtin_amdgcn_mfma_f32_16x16x32_bf16(Bt[n][k], At[m][k], acc[ai][bj][m][n], 0, 0, 0); __builtin_amdgcn_s_setprio(0); } while (0)
; #define PG8_WAIT_V(n) asm volatile("s_waitcnt vmcnt(" #n ")" ::: "memory")
; #define PG8_WAIT_L(n) asm volatile("s_waitcnt lgkmcnt(" #n ")" ::: "memory")
; #define PG8_BAR __builtin_amdgcn_s_barrier()
; #define PG8_SCHED __builtin_amdgcn_sched_barrier(0)
; template <class Epi>
; __device__ __forceinline__ void gemm_phase(LAS unsigned char* lds, const int tid, const Gemm g, const StaticOrder& S, const Epi& E) {
;     ...
;             const bool last = (t == nt - 2);
;             const char* a1 = cA + (size_t)(t + 1) * kstep;
;             const char* a2 = last ? nA : cA + (size_t)(t + 2) * kstep; const char* b2 = last ? nB : cB + (size_t)(t + 2) * kstep;
;             const char* a3 = a2 + kstep; const char* b3 = b2 + kstep;
;             PG8_LDB(B0, 0, 0); PG8_LDB(B1, 0, 1); PG8_SCHED; PG8_LDA(At, 0, 0); PG8_STAGE(PG8_SA(1, 1), a1 + hstepA, voffA);
;             PG8_WAIT_V(8); PG8_WAIT_L(0); PG8_BAR; PG8_MMA(0, 0, At, B0); PG8_MMA(0, 1, At, B1); PG8_BAR; PG8_SCHED;
;             PG8_LDA(At, 0, 1); PG8_STAGE(PG8_SB(0, 0), b2, voffB); PG8_STAGE(PG8_SB(0, 1), b2 + hstepB, voffB); PG8_STAGE(PG8_SA(0, 0), a2, voffA);
;             PG8_WAIT_V(8); PG8_WAIT_L(0); PG8_BAR; PG8_MMA(1, 0, At, B0); PG8_MMA(1, 1, At, B1); PG8_BAR; PG8_SCHED;
.LBB0_2193:
	s_add_u32 s70, s30, 0x100
	s_addc_u32 s71, s31, 0
	s_add_i32 s76, 0, 0x10000
	s_cmp_eq_u32 vcc_hi, 40
	s_cselect_b32 s75, s1, s71
	s_cselect_b32 s74, s0, s70
	s_cselect_b32 s73, s69, vcc_lo
	s_cselect_b32 s72, s68, s28
	s_add_i32 s2, 0, 0x14000
	v_add_u32_e32 v154, s76, v179
	v_add_u32_e32 v162, s2, v179
	ds_read_b128 v[130:133], v154
	ds_read_b128 v[134:137], v154 offset:1024
	ds_read_b128 v[138:141], v154 offset:2048
	ds_read_b128 v[154:157], v154 offset:3072
	ds_read_b128 v[158:161], v162
	ds_read_b128 v[170:173], v162 offset:1024
	ds_read_b128 v[174:177], v162 offset:2048
	ds_read_b128 v[184:187], v162 offset:3072
	v_lshl_add_u64 v[162:163], s[30:31], 0, v[150:151]
	s_add_i32 m0, s5, 0xc000
	ds_read_b128 v[188:191], v181
	ds_read_b128 v[192:195], v181 offset:1024
	ds_read_b128 v[196:199], v181 offset:2048
	ds_read_b128 v[200:203], v181 offset:3072
	ds_read_b128 v[212:215], v181 offset:4096
	ds_read_b128 v[216:219], v181 offset:5120
	ds_read_b128 v[220:223], v181 offset:6144
	ds_read_b128 v[224:227], v181 offset:7168
	global_load_lds_dwordx4 v[162:163], off
	v_lshl_add_u64 v[162:163], s[30:31], 0, v[152:153]
	s_add_i32 m0, s5, 0xe000
	s_nop 0
	global_load_lds_dwordx4 v[162:163], off
	s_waitcnt vmcnt(8)
	s_waitcnt lgkmcnt(0)
	s_barrier
	s_setprio 1
	s_waitcnt lgkmcnt(0)
	v_mfma_f32_16x16x32_bf16 v[126:129], v[130:133], v[188:191], v[126:129]
	v_mfma_f32_16x16x32_bf16 v[122:125], v[138:141], v[188:191], v[122:125]
	v_mfma_f32_16x16x32_bf16 v[110:113], v[130:133], v[196:199], v[110:113]
	v_mfma_f32_16x16x32_bf16 v[106:109], v[138:141], v[196:199], v[106:109]
	v_mfma_f32_16x16x32_bf16 v[94:97], v[130:133], v[212:215], v[94:97]
	v_mfma_f32_16x16x32_bf16 v[90:93], v[138:141], v[212:215], v[90:93]
	v_mfma_f32_16x16x32_bf16 v[78:81], v[130:133], v[220:223], v[78:81]
	v_mfma_f32_16x16x32_bf16 v[74:77], v[138:141], v[220:223], v[74:77]
	v_mfma_f32_16x16x32_bf16 v[126:129], v[134:137], v[192:195], v[126:129]
	v_mfma_f32_16x16x32_bf16 v[122:125], v[154:157], v[192:195], v[122:125]
	v_mfma_f32_16x16x32_bf16 v[110:113], v[134:137], v[200:203], v[110:113]
	v_mfma_f32_16x16x32_bf16 v[106:109], v[154:157], v[200:203], v[106:109]
	v_mfma_f32_16x16x32_bf16 v[94:97], v[134:137], v[216:219], v[94:97]
	v_mfma_f32_16x16x32_bf16 v[90:93], v[154:157], v[216:219], v[90:93]
	v_mfma_f32_16x16x32_bf16 v[78:81], v[134:137], v[224:227], v[78:81]
	v_mfma_f32_16x16x32_bf16 v[74:77], v[154:157], v[224:227], v[74:77]
	s_setprio 0
	s_setprio 1
	v_mfma_f32_16x16x32_bf16 v[118:121], v[158:161], v[188:191], v[118:121]
	v_mfma_f32_16x16x32_bf16 v[114:117], v[174:177], v[188:191], v[114:117]
	v_mfma_f32_16x16x32_bf16 v[102:105], v[158:161], v[196:199], v[102:105]
	v_mfma_f32_16x16x32_bf16 v[98:101], v[174:177], v[196:199], v[98:101]
	v_mfma_f32_16x16x32_bf16 v[86:89], v[158:161], v[212:215], v[86:89]
	v_mfma_f32_16x16x32_bf16 v[82:85], v[174:177], v[212:215], v[82:85]
	v_mfma_f32_16x16x32_bf16 v[70:73], v[158:161], v[220:223], v[70:73]
	v_mfma_f32_16x16x32_bf16 v[66:69], v[174:177], v[220:223], v[66:69]
	v_mfma_f32_16x16x32_bf16 v[118:121], v[170:173], v[192:195], v[118:121]
	v_mfma_f32_16x16x32_bf16 v[114:117], v[184:187], v[192:195], v[114:117]
	v_mfma_f32_16x16x32_bf16 v[102:105], v[170:173], v[200:203], v[102:105]
	v_mfma_f32_16x16x32_bf16 v[98:101], v[184:187], v[200:203], v[98:101]
	v_mfma_f32_16x16x32_bf16 v[86:89], v[170:173], v[216:219], v[86:89]
	v_mfma_f32_16x16x32_bf16 v[82:85], v[184:187], v[216:219], v[82:85]
	v_mfma_f32_16x16x32_bf16 v[70:73], v[170:173], v[224:227], v[70:73]
	v_mfma_f32_16x16x32_bf16 v[66:69], v[184:187], v[224:227], v[66:69]
	s_setprio 0
	s_barrier
	s_add_i32 s3, s76, s4
	v_lshl_add_u64 v[162:163], s[72:73], 0, v[0:1]
	s_mov_b32 m0, s3
	ds_read_b128 v[188:191], v181 offset:16384
	ds_read_b128 v[192:195], v181 offset:17408
	ds_read_b128 v[196:199], v181 offset:18432
	ds_read_b128 v[200:203], v181 offset:19456
	ds_read_b128 v[212:215], v181 offset:20480
	ds_read_b128 v[216:219], v181 offset:21504
	ds_read_b128 v[220:223], v181 offset:22528
	ds_read_b128 v[224:227], v181 offset:23552
	global_load_lds_dwordx4 v[162:163], off
	s_add_i32 m0, s3, 0x2000
	s_add_u32 s30, s72, 0xb0000
	v_lshl_add_u64 v[164:165], s[72:73], 0, v[148:149]
	s_addc_u32 s31, s73, 0
	s_add_i32 s2, s2, s4
	global_load_lds_dwordx4 v[164:165], off
	v_lshl_add_u64 v[206:207], s[30:31], 0, v[0:1]
	s_mov_b32 m0, s2
	v_lshl_add_u64 v[228:229], s[74:75], 0, v[144:145]
	v_lshl_add_u64 v[206:207], s[30:31], 0, v[148:149]
	s_add_i32 m0, s2, 0x2000
	s_nop 0
	v_lshl_add_u64 v[206:207], s[74:75], 0, v[142:143]
	s_mov_b32 m0, s5
	s_nop 0
	global_load_lds_dwordx4 v[206:207], off
	s_mov_b32 m0, s6
	s_nop 0
	global_load_lds_dwordx4 v[228:229], off
	s_waitcnt vmcnt(6)
	s_waitcnt lgkmcnt(0)
	s_barrier
; #define PG8_STAGE(bufoff, gbase, voff) do { _Pragma("unroll") for (int _i = 0; _i < 2; ++_i) \
;         __builtin_amdgcn_global_load_lds((const unsigned*)((const char*)(gbase) + (voff)[_i]), (LAS unsigned*)(lds + (bufoff) + ldsw + _i * 8192), 16, 0, 0); } while (0)
; #define PG8_LDA(dst, b, h) do { _Pragma("unroll") for (int m = 0; m < 4; ++m) _Pragma("unroll") for (int k = 0; k < 2; ++k) dst[m][k] = *(const LAS bf16x8*)(lds + PG8_SA(b, h) + aoff + m * 2048 + k * 1024); } while (0)
; #define PG8_LDB(dst, b, h) do { _Pragma("unroll") for (int n = 0; n < 2; ++n) _Pragma("unroll") for (int k = 0; k < 2; ++k) dst[n][k] = *(const LAS bf16x8*)(lds + PG8_SB(b, h) + boff + n * 2048 + k * 1024); } while (0)
; #define PG8_MMA(ai, bj, At, Bt) do { __builtin_amdgcn_s_setprio(1); _Pragma("unroll") for (int m = 0; m < 4; ++m) _Pragma("unroll") for (int n = 0; n < 2; ++n) _Pragma("unroll") for (int k = 0; k < 2; ++k) \
;         acc[ai][bj][m][n] = __builtin_amdgcn_mfma_f32_16x16x32_bf16(Bt[n][k], At[m][k], acc[ai][bj][m][n], 0, 0, 0); __builtin_amdgcn_s_setprio(0); } while (0)
; #define PG8_WAIT_V(n) asm volatile("s_waitcnt vmcnt(" #n ")" ::: "memory")
; #define PG8_WAIT_L(n) asm volatile("s_waitcnt lgkmcnt(" #n ")" ::: "memory")
; #define PG8_BAR __builtin_amdgcn_s_barrier()
; #define PG8_SCHED __builtin_amdgcn_sched_barrier(0)
; template <class Epi>
; __device__ __forceinline__ void gemm_phase(LAS unsigned char* lds, const int tid, const Gemm g, const StaticOrder& S, const Epi& E) {
;     ...
;             PG8_WAIT_V(8); PG8_WAIT_L(0); PG8_BAR; PG8_MMA(1, 0, At, B0); PG8_MMA(1, 1, At, B1); PG8_BAR; PG8_SCHED;
;             PG8_LDB(B0, 1, 0); PG8_LDB(B1, 1, 1); PG8_SCHED; PG8_LDA(At, 1, 0); PG8_STAGE(PG8_SA(0, 1), a2 + hstepA, voffA);
;             PG8_WAIT_V(8); PG8_WAIT_L(0); PG8_BAR; PG8_MMA(0, 0, At, B0); PG8_MMA(0, 1, At, B1); PG8_BAR; PG8_SCHED;
	s_setprio 1
	s_waitcnt lgkmcnt(0)
	v_mfma_f32_16x16x32_bf16 v[62:65], v[130:133], v[188:191], v[62:65]
	v_mfma_f32_16x16x32_bf16 v[58:61], v[138:141], v[188:191], v[58:61]
	v_mfma_f32_16x16x32_bf16 v[46:49], v[130:133], v[196:199], v[46:49]
	v_mfma_f32_16x16x32_bf16 v[42:45], v[138:141], v[196:199], v[42:45]
	v_mfma_f32_16x16x32_bf16 v[30:33], v[130:133], v[212:215], v[30:33]
	v_mfma_f32_16x16x32_bf16 v[26:29], v[138:141], v[212:215], v[26:29]
	v_mfma_f32_16x16x32_bf16 v[14:17], v[130:133], v[220:223], v[14:17]
	v_mfma_f32_16x16x32_bf16 v[10:13], v[138:141], v[220:223], v[10:13]
	v_mfma_f32_16x16x32_bf16 v[62:65], v[134:137], v[192:195], v[62:65]
	v_mfma_f32_16x16x32_bf16 v[58:61], v[154:157], v[192:195], v[58:61]
	v_mfma_f32_16x16x32_bf16 v[46:49], v[134:137], v[200:203], v[46:49]
	v_mfma_f32_16x16x32_bf16 v[42:45], v[154:157], v[200:203], v[42:45]
	v_mfma_f32_16x16x32_bf16 v[30:33], v[134:137], v[216:219], v[30:33]
	v_mfma_f32_16x16x32_bf16 v[26:29], v[154:157], v[216:219], v[26:29]
	v_mfma_f32_16x16x32_bf16 v[14:17], v[134:137], v[224:227], v[14:17]
	v_mfma_f32_16x16x32_bf16 v[10:13], v[154:157], v[224:227], v[10:13]
	s_setprio 0
	s_setprio 1
	v_mfma_f32_16x16x32_bf16 v[54:57], v[158:161], v[188:191], v[54:57]
	v_mfma_f32_16x16x32_bf16 v[50:53], v[174:177], v[188:191], v[50:53]
	v_mfma_f32_16x16x32_bf16 v[38:41], v[158:161], v[196:199], v[38:41]
	v_mfma_f32_16x16x32_bf16 v[34:37], v[174:177], v[196:199], v[34:37]
	v_mfma_f32_16x16x32_bf16 v[22:25], v[158:161], v[212:215], v[22:25]
	v_mfma_f32_16x16x32_bf16 v[18:21], v[174:177], v[212:215], v[18:21]
	v_mfma_f32_16x16x32_bf16 v[6:9], v[158:161], v[220:223], v[6:9]
	v_mfma_f32_16x16x32_bf16 v[2:5], v[174:177], v[220:223], v[2:5]
	v_mfma_f32_16x16x32_bf16 v[54:57], v[170:173], v[192:195], v[54:57]
	v_mfma_f32_16x16x32_bf16 v[50:53], v[184:187], v[192:195], v[50:53]
	v_mfma_f32_16x16x32_bf16 v[38:41], v[170:173], v[200:203], v[38:41]
	v_mfma_f32_16x16x32_bf16 v[34:37], v[184:187], v[200:203], v[34:37]
	v_mfma_f32_16x16x32_bf16 v[22:25], v[170:173], v[216:219], v[22:25]
	v_mfma_f32_16x16x32_bf16 v[18:21], v[184:187], v[216:219], v[18:21]
	v_mfma_f32_16x16x32_bf16 v[6:9], v[170:173], v[224:227], v[6:9]
	v_mfma_f32_16x16x32_bf16 v[2:5], v[184:187], v[224:227], v[2:5]
	s_setprio 0
	s_barrier
	s_add_i32 s2, 0, 0x18000
	s_add_i32 s3, 0, 0x1c000
	v_add_u32_e32 v154, s2, v179
	v_add_u32_e32 v183, s3, v179
	ds_read_b128 v[130:133], v154
	ds_read_b128 v[134:137], v154 offset:1024
	ds_read_b128 v[138:141], v154 offset:2048
	ds_read_b128 v[154:157], v154 offset:3072
	ds_read_b128 v[158:161], v183
	ds_read_b128 v[170:173], v183 offset:1024
	ds_read_b128 v[174:177], v183 offset:2048
	ds_read_b128 v[184:187], v183 offset:3072
	s_add_u32 s100, s72, 0xb0000
	s_addc_u32 s101, s73, 0
	v_lshl_add_u64 v[230:231], s[100:101], 0, v[0:1]
	s_add_i32 m0, s4, 0x14000
	s_nop 0
	global_load_lds_dwordx4 v[230:231], off
	v_lshl_add_u64 v[230:231], s[100:101], 0, v[148:149]
	s_add_i32 m0, s4, 0x16000
	s_nop 0
	global_load_lds_dwordx4 v[230:231], off
	s_add_u32 s30, s74, 0x160000
	s_addc_u32 s31, s75, 0
	s_mov_b32 m0, s7
	v_lshl_add_u64 v[230:231], s[30:31], 0, v[142:143]
	ds_read_b128 v[188:191], v181 offset:32768
	ds_read_b128 v[192:195], v181 offset:33792
	ds_read_b128 v[196:199], v181 offset:34816
	ds_read_b128 v[200:203], v181 offset:35840
	ds_read_b128 v[212:215], v181 offset:36864
	ds_read_b128 v[216:219], v181 offset:37888
	ds_read_b128 v[220:223], v181 offset:38912
	ds_read_b128 v[224:227], v181 offset:39936
	global_load_lds_dwordx4 v[230:231], off
	v_lshl_add_u64 v[230:231], s[30:31], 0, v[144:145]
	s_mov_b32 m0, s77
	s_nop 0
	global_load_lds_dwordx4 v[230:231], off
	s_waitcnt vmcnt(8)
	s_waitcnt lgkmcnt(0)
	s_barrier
	s_setprio 1
	s_waitcnt lgkmcnt(0)
	v_mfma_f32_16x16x32_bf16 v[126:129], v[130:133], v[188:191], v[126:129]
	v_mfma_f32_16x16x32_bf16 v[122:125], v[138:141], v[188:191], v[122:125]
	v_mfma_f32_16x16x32_bf16 v[110:113], v[130:133], v[196:199], v[110:113]
	v_mfma_f32_16x16x32_bf16 v[106:109], v[138:141], v[196:199], v[106:109]
	v_mfma_f32_16x16x32_bf16 v[94:97], v[130:133], v[212:215], v[94:97]
	v_mfma_f32_16x16x32_bf16 v[90:93], v[138:141], v[212:215], v[90:93]
	v_mfma_f32_16x16x32_bf16 v[78:81], v[130:133], v[220:223], v[78:81]
	v_mfma_f32_16x16x32_bf16 v[74:77], v[138:141], v[220:223], v[74:77]
	v_mfma_f32_16x16x32_bf16 v[126:129], v[134:137], v[192:195], v[126:129]
	v_mfma_f32_16x16x32_bf16 v[122:125], v[154:157], v[192:195], v[122:125]
	v_mfma_f32_16x16x32_bf16 v[110:113], v[134:137], v[200:203], v[110:113]
	v_mfma_f32_16x16x32_bf16 v[106:109], v[154:157], v[200:203], v[106:109]
	v_mfma_f32_16x16x32_bf16 v[94:97], v[134:137], v[216:219], v[94:97]
	v_mfma_f32_16x16x32_bf16 v[90:93], v[154:157], v[216:219], v[90:93]
	v_mfma_f32_16x16x32_bf16 v[78:81], v[134:137], v[224:227], v[78:81]
	v_mfma_f32_16x16x32_bf16 v[74:77], v[154:157], v[224:227], v[74:77]
	s_setprio 0
	s_setprio 1
	v_mfma_f32_16x16x32_bf16 v[118:121], v[158:161], v[188:191], v[118:121]
	v_mfma_f32_16x16x32_bf16 v[114:117], v[174:177], v[188:191], v[114:117]
	v_mfma_f32_16x16x32_bf16 v[102:105], v[158:161], v[196:199], v[102:105]
	v_mfma_f32_16x16x32_bf16 v[98:101], v[174:177], v[196:199], v[98:101]
	v_mfma_f32_16x16x32_bf16 v[86:89], v[158:161], v[212:215], v[86:89]
	v_mfma_f32_16x16x32_bf16 v[82:85], v[174:177], v[212:215], v[82:85]
	v_mfma_f32_16x16x32_bf16 v[70:73], v[158:161], v[220:223], v[70:73]
	v_mfma_f32_16x16x32_bf16 v[66:69], v[174:177], v[220:223], v[66:69]
	v_mfma_f32_16x16x32_bf16 v[118:121], v[170:173], v[192:195], v[118:121]
	v_mfma_f32_16x16x32_bf16 v[114:117], v[184:187], v[192:195], v[114:117]
	v_mfma_f32_16x16x32_bf16 v[102:105], v[170:173], v[200:203], v[102:105]
	v_mfma_f32_16x16x32_bf16 v[98:101], v[184:187], v[200:203], v[98:101]
	v_mfma_f32_16x16x32_bf16 v[86:89], v[170:173], v[216:219], v[86:89]
	v_mfma_f32_16x16x32_bf16 v[82:85], v[184:187], v[216:219], v[82:85]
	v_mfma_f32_16x16x32_bf16 v[70:73], v[170:173], v[224:227], v[70:73]
	v_mfma_f32_16x16x32_bf16 v[66:69], v[184:187], v[224:227], v[66:69]
	s_setprio 0
	s_barrier
; #define PG8_STAGE(bufoff, gbase, voff) do { _Pragma("unroll") for (int _i = 0; _i < 2; ++_i) \
;         __builtin_amdgcn_global_load_lds((const unsigned*)((const char*)(gbase) + (voff)[_i]), (LAS unsigned*)(lds + (bufoff) + ldsw + _i * 8192), 16, 0, 0); } while (0)
; #define PG8_LDA(dst, b, h) do { _Pragma("unroll") for (int m = 0; m < 4; ++m) _Pragma("unroll") for (int k = 0; k < 2; ++k) dst[m][k] = *(const LAS bf16x8*)(lds + PG8_SA(b, h) + aoff + m * 2048 + k * 1024); } while (0)
; #define PG8_MMA(ai, bj, At, Bt) do { __builtin_amdgcn_s_setprio(1); _Pragma("unroll") for (int m = 0; m < 4; ++m) _Pragma("unroll") for (int n = 0; n < 2; ++n) _Pragma("unroll") for (int k = 0; k < 2; ++k) \
;         acc[ai][bj][m][n] = __builtin_amdgcn_mfma_f32_16x16x32_bf16(Bt[n][k], At[m][k], acc[ai][bj][m][n], 0, 0, 0); __builtin_amdgcn_s_setprio(0); } while (0)
; #define PG8_WAIT_V(n) asm volatile("s_waitcnt vmcnt(" #n ")" ::: "memory")
; #define PG8_WAIT_L(n) asm volatile("s_waitcnt lgkmcnt(" #n ")" ::: "memory")
; #define PG8_BAR __builtin_amdgcn_s_barrier()
; #define PG8_SCHED __builtin_amdgcn_sched_barrier(0)
; template <class Epi>
; __device__ __forceinline__ void gemm_phase(LAS unsigned char* lds, const int tid, const Gemm g, const StaticOrder& S, const Epi& E) {
;     ...
;             PG8_LDA(At, 1, 1); PG8_STAGE(PG8_SB(1, 0), b3, voffB); PG8_STAGE(PG8_SB(1, 1), b3 + hstepB, voffB); PG8_STAGE(PG8_SA(1, 0), a3, voffA);
;             PG8_WAIT_V(8); PG8_WAIT_L(0); PG8_BAR; PG8_MMA(1, 0, At, B0); PG8_MMA(1, 1, At, B1); PG8_BAR; PG8_SCHED;
;         }
;         if (wr == 0) PG8_BAR;
	s_add_i32 s2, s2, s4
	v_lshl_add_u64 v[162:163], v[162:163], 0, s[36:37]
	s_mov_b32 m0, s2
	ds_read_b128 v[188:191], v181 offset:49152
	ds_read_b128 v[192:195], v181 offset:50176
	ds_read_b128 v[196:199], v181 offset:51200
	ds_read_b128 v[200:203], v181 offset:52224
	ds_read_b128 v[212:215], v181 offset:53248
	ds_read_b128 v[216:219], v181 offset:54272
	ds_read_b128 v[220:223], v181 offset:55296
	ds_read_b128 v[224:227], v181 offset:56320
	global_load_lds_dwordx4 v[162:163], off
	s_add_i32 m0, s2, 0x2000
	s_add_u32 s30, s72, 0xb0080
	v_lshl_add_u64 v[162:163], v[164:165], 0, s[36:37]
	s_addc_u32 s31, s73, 0
	s_add_i32 s2, s3, s4
	global_load_lds_dwordx4 v[162:163], off
	v_lshl_add_u64 v[162:163], s[30:31], 0, v[0:1]
	s_mov_b32 m0, s2
	s_nop 0
	global_load_lds_dwordx4 v[162:163], off
	v_lshl_add_u64 v[162:163], s[30:31], 0, v[148:149]
	s_add_i32 m0, s2, 0x2000
	s_nop 0
	global_load_lds_dwordx4 v[162:163], off
	v_lshl_add_u64 v[162:163], v[206:207], 0, s[36:37]
	s_mov_b32 m0, s83
	s_nop 0
	global_load_lds_dwordx4 v[162:163], off
	v_lshl_add_u64 v[162:163], v[228:229], 0, s[36:37]
	s_mov_b32 m0, s88
	s_nop 0
	global_load_lds_dwordx4 v[162:163], off
	s_waitcnt vmcnt(8)
	s_waitcnt lgkmcnt(0)
	s_barrier
	s_setprio 1
	s_waitcnt lgkmcnt(0)
	v_mfma_f32_16x16x32_bf16 v[62:65], v[130:133], v[188:191], v[62:65]
	v_mfma_f32_16x16x32_bf16 v[58:61], v[138:141], v[188:191], v[58:61]
	v_mfma_f32_16x16x32_bf16 v[46:49], v[130:133], v[196:199], v[46:49]
	v_mfma_f32_16x16x32_bf16 v[42:45], v[138:141], v[196:199], v[42:45]
	v_mfma_f32_16x16x32_bf16 v[30:33], v[130:133], v[212:215], v[30:33]
	v_mfma_f32_16x16x32_bf16 v[26:29], v[138:141], v[212:215], v[26:29]
	v_mfma_f32_16x16x32_bf16 v[14:17], v[130:133], v[220:223], v[14:17]
	v_mfma_f32_16x16x32_bf16 v[10:13], v[138:141], v[220:223], v[10:13]
	v_mfma_f32_16x16x32_bf16 v[62:65], v[134:137], v[192:195], v[62:65]
	v_mfma_f32_16x16x32_bf16 v[58:61], v[154:157], v[192:195], v[58:61]
	v_mfma_f32_16x16x32_bf16 v[46:49], v[134:137], v[200:203], v[46:49]
	v_mfma_f32_16x16x32_bf16 v[42:45], v[154:157], v[200:203], v[42:45]
	v_mfma_f32_16x16x32_bf16 v[30:33], v[134:137], v[216:219], v[30:33]
	v_mfma_f32_16x16x32_bf16 v[26:29], v[154:157], v[216:219], v[26:29]
	v_mfma_f32_16x16x32_bf16 v[14:17], v[134:137], v[224:227], v[14:17]
	v_mfma_f32_16x16x32_bf16 v[10:13], v[154:157], v[224:227], v[10:13]
	s_setprio 0
	s_setprio 1
	v_mfma_f32_16x16x32_bf16 v[54:57], v[158:161], v[188:191], v[54:57]
	v_mfma_f32_16x16x32_bf16 v[50:53], v[174:177], v[188:191], v[50:53]
	v_mfma_f32_16x16x32_bf16 v[38:41], v[158:161], v[196:199], v[38:41]
	v_mfma_f32_16x16x32_bf16 v[34:37], v[174:177], v[196:199], v[34:37]
	v_mfma_f32_16x16x32_bf16 v[22:25], v[158:161], v[212:215], v[22:25]
	v_mfma_f32_16x16x32_bf16 v[18:21], v[174:177], v[212:215], v[18:21]
	v_mfma_f32_16x16x32_bf16 v[6:9], v[158:161], v[220:223], v[6:9]
	v_mfma_f32_16x16x32_bf16 v[2:5], v[174:177], v[220:223], v[2:5]
	v_mfma_f32_16x16x32_bf16 v[54:57], v[170:173], v[192:195], v[54:57]
	v_mfma_f32_16x16x32_bf16 v[50:53], v[184:187], v[192:195], v[50:53]
	v_mfma_f32_16x16x32_bf16 v[38:41], v[170:173], v[200:203], v[38:41]
	v_mfma_f32_16x16x32_bf16 v[34:37], v[184:187], v[200:203], v[34:37]
	v_mfma_f32_16x16x32_bf16 v[22:25], v[170:173], v[216:219], v[22:25]
	v_mfma_f32_16x16x32_bf16 v[18:21], v[184:187], v[216:219], v[18:21]
	v_mfma_f32_16x16x32_bf16 v[6:9], v[170:173], v[224:227], v[6:9]
	v_mfma_f32_16x16x32_bf16 v[2:5], v[184:187], v[224:227], v[2:5]
	s_setprio 0
	s_barrier
	s_add_i32 vcc_hi, vcc_hi, 2
	s_add_u32 s28, s28, 0x100
	s_addc_u32 vcc_lo, vcc_lo, 0
	s_cmp_gt_u32 vcc_hi, 41
	s_mov_b64 s[30:31], s[70:71]
	s_cbranch_scc0 .LBB0_2193
	s_and_b64 vcc, exec, s[26:27]
	s_cbranch_vccz .LBB0_2196
	s_barrier

; #define PG8_STAGE(bufoff, gbase, voff) do { _Pragma("unroll") for (int _i = 0; _i < 2; ++_i) \
;         __builtin_amdgcn_global_load_lds((const unsigned*)((const char*)(gbase) + (voff)[_i]), (LAS unsigned*)(lds + (bufoff) + ldsw + _i * 8192), 16, 0, 0); } while (0)
; #define PG8_LDA(dst, b, h) do { _Pragma("unroll") for (int m = 0; m < 4; ++m) _Pragma("unroll") for (int k = 0; k < 2; ++k) dst[m][k] = *(const LAS bf16x8*)(lds + PG8_SA(b, h) + aoff + m * 2048 + k * 1024); } while (0)
; #define PG8_LDB(dst, b, h) do { _Pragma("unroll") for (int n = 0; n < 2; ++n) _Pragma("unroll") for (int k = 0; k < 2; ++k) dst[n][k] = *(const LAS bf16x8*)(lds + PG8_SB(b, h) + boff + n * 2048 + k * 1024); } while (0)
; #define PG8_MMA(ai, bj, At, Bt) do { __builtin_amdgcn_s_setprio(1); _Pragma("unroll") for (int m = 0; m < 4; ++m) _Pragma("unroll") for (int n = 0; n < 2; ++n) _Pragma("unroll") for (int k = 0; k < 2; ++k) \
;         acc[ai][bj][m][n] = __builtin_amdgcn_mfma_f32_16x16x32_bf16(Bt[n][k], At[m][k], acc[ai][bj][m][n], 0, 0, 0); __builtin_amdgcn_s_setprio(0); } while (0)
; #define PG8_WAIT_V(n) asm volatile("s_waitcnt vmcnt(" #n ")" ::: "memory")
; #define PG8_WAIT_L(n) asm volatile("s_waitcnt lgkmcnt(" #n ")" ::: "memory")
; #define PG8_BAR __builtin_amdgcn_s_barrier()
; #define PG8_SCHED __builtin_amdgcn_sched_barrier(0)
; template <class Epi>
; __device__ __forceinline__ void gemm_phase(LAS unsigned char* lds, const int tid, const Gemm g, const StaticOrder& S, const Epi& E) {
;     ...
;             const bool last = (t == nt - 2);
;             const char* a1 = cA + (size_t)(t + 1) * kstep;
;             const char* a2 = last ? nA : cA + (size_t)(t + 2) * kstep; const char* b2 = last ? nB : cB + (size_t)(t + 2) * kstep;
;             const char* a3 = a2 + kstep; const char* b3 = b2 + kstep;
;             PG8_LDB(B0, 0, 0); PG8_LDB(B1, 0, 1); PG8_SCHED; PG8_LDA(At, 0, 0); PG8_STAGE(PG8_SA(1, 1), a1 + hstepA, voffA);
;             PG8_WAIT_V(8); PG8_WAIT_L(0); PG8_BAR; PG8_MMA(0, 0, At, B0); PG8_MMA(0, 1, At, B1); PG8_BAR; PG8_SCHED;
;             PG8_LDA(At, 0, 1); PG8_STAGE(PG8_SB(0, 0), b2, voffB); PG8_STAGE(PG8_SB(0, 1), b2 + hstepB, voffB); PG8_STAGE(PG8_SA(0, 0), a2, voffA);
;             PG8_WAIT_V(8); PG8_WAIT_L(0); PG8_BAR; PG8_MMA(1, 0, At, B0); PG8_MMA(1, 1, At, B1); PG8_BAR; PG8_SCHED;
.LBB0_2303:
	s_add_u32 s68, s66, 0x100
	s_addc_u32 s69, s67, 0
	s_add_i32 s76, 0, 0x10000
	s_cmp_eq_u32 s93, 40
	s_cselect_b32 s73, s1, s69
	s_cselect_b32 s72, s0, s68
	s_cselect_b32 s71, s31, s28
	s_cselect_b32 s70, s30, s11
	s_add_i32 vcc_lo, 0, 0x14000
	v_add_u32_e32 v70, s76, v212
	v_add_u32_e32 v162, vcc_lo, v212
	ds_read_b128 v[42:45], v70
	ds_read_b128 v[46:49], v70 offset:1024
	ds_read_b128 v[66:69], v70 offset:2048
	ds_read_b128 v[70:73], v70 offset:3072
	ds_read_b128 v[158:161], v162
	ds_read_b128 v[170:173], v162 offset:1024
	ds_read_b128 v[174:177], v162 offset:2048
	ds_read_b128 v[178:181], v162 offset:3072
	v_lshl_add_u64 v[162:163], s[66:67], 0, v[154:155]
	s_add_i32 m0, s5, 0xc000
	ds_read_b128 v[182:185], v214
	ds_read_b128 v[186:189], v214 offset:1024
	ds_read_b128 v[190:193], v214 offset:2048
	ds_read_b128 v[194:197], v214 offset:3072
	ds_read_b128 v[198:201], v214 offset:4096
	ds_read_b128 v[216:219], v214 offset:5120
	ds_read_b128 v[220:223], v214 offset:6144
	ds_read_b128 v[224:227], v214 offset:7168
	global_load_lds_dwordx4 v[162:163], off
	v_lshl_add_u64 v[162:163], s[66:67], 0, v[156:157]
	s_add_i32 m0, s5, 0xe000
	s_nop 0
	global_load_lds_dwordx4 v[162:163], off
	s_waitcnt vmcnt(8)
	s_waitcnt lgkmcnt(0)
	s_barrier
	s_setprio 1
	s_waitcnt lgkmcnt(0)
	v_mfma_f32_16x16x32_bf16 v[142:145], v[42:45], v[182:185], v[142:145]
	v_mfma_f32_16x16x32_bf16 v[138:141], v[66:69], v[182:185], v[138:141]
	v_mfma_f32_16x16x32_bf16 v[126:129], v[42:45], v[190:193], v[126:129]
	v_mfma_f32_16x16x32_bf16 v[122:125], v[66:69], v[190:193], v[122:125]
	v_mfma_f32_16x16x32_bf16 v[110:113], v[42:45], v[198:201], v[110:113]
	v_mfma_f32_16x16x32_bf16 v[106:109], v[66:69], v[198:201], v[106:109]
	v_mfma_f32_16x16x32_bf16 v[94:97], v[42:45], v[220:223], v[94:97]
	v_mfma_f32_16x16x32_bf16 v[90:93], v[66:69], v[220:223], v[90:93]
	v_mfma_f32_16x16x32_bf16 v[142:145], v[46:49], v[186:189], v[142:145]
	v_mfma_f32_16x16x32_bf16 v[138:141], v[70:73], v[186:189], v[138:141]
	v_mfma_f32_16x16x32_bf16 v[126:129], v[46:49], v[194:197], v[126:129]
	v_mfma_f32_16x16x32_bf16 v[122:125], v[70:73], v[194:197], v[122:125]
	v_mfma_f32_16x16x32_bf16 v[110:113], v[46:49], v[216:219], v[110:113]
	v_mfma_f32_16x16x32_bf16 v[106:109], v[70:73], v[216:219], v[106:109]
	v_mfma_f32_16x16x32_bf16 v[94:97], v[46:49], v[224:227], v[94:97]
	v_mfma_f32_16x16x32_bf16 v[90:93], v[70:73], v[224:227], v[90:93]
	s_setprio 0
	s_setprio 1
	v_mfma_f32_16x16x32_bf16 v[134:137], v[158:161], v[182:185], v[134:137]
	v_mfma_f32_16x16x32_bf16 v[130:133], v[174:177], v[182:185], v[130:133]
	v_mfma_f32_16x16x32_bf16 v[118:121], v[158:161], v[190:193], v[118:121]
	v_mfma_f32_16x16x32_bf16 v[114:117], v[174:177], v[190:193], v[114:117]
	v_mfma_f32_16x16x32_bf16 v[102:105], v[158:161], v[198:201], v[102:105]
	v_mfma_f32_16x16x32_bf16 v[98:101], v[174:177], v[198:201], v[98:101]
	v_mfma_f32_16x16x32_bf16 v[86:89], v[158:161], v[220:223], v[86:89]
	v_mfma_f32_16x16x32_bf16 v[82:85], v[174:177], v[220:223], v[82:85]
	v_mfma_f32_16x16x32_bf16 v[134:137], v[170:173], v[186:189], v[134:137]
	v_mfma_f32_16x16x32_bf16 v[130:133], v[178:181], v[186:189], v[130:133]
	v_mfma_f32_16x16x32_bf16 v[118:121], v[170:173], v[194:197], v[118:121]
	v_mfma_f32_16x16x32_bf16 v[114:117], v[178:181], v[194:197], v[114:117]
	v_mfma_f32_16x16x32_bf16 v[102:105], v[170:173], v[216:219], v[102:105]
	v_mfma_f32_16x16x32_bf16 v[98:101], v[178:181], v[216:219], v[98:101]
	v_mfma_f32_16x16x32_bf16 v[86:89], v[170:173], v[224:227], v[86:89]
	v_mfma_f32_16x16x32_bf16 v[82:85], v[178:181], v[224:227], v[82:85]
	s_setprio 0
	s_barrier
	s_add_i32 s66, s76, s4
	v_lshl_add_u64 v[162:163], s[70:71], 0, v[0:1]
	s_mov_b32 m0, s66
	ds_read_b128 v[182:185], v214 offset:16384
	ds_read_b128 v[186:189], v214 offset:17408
	ds_read_b128 v[190:193], v214 offset:18432
	ds_read_b128 v[194:197], v214 offset:19456
	ds_read_b128 v[198:201], v214 offset:20480
	ds_read_b128 v[216:219], v214 offset:21504
	ds_read_b128 v[220:223], v214 offset:22528
	ds_read_b128 v[224:227], v214 offset:23552
	global_load_lds_dwordx4 v[162:163], off
	s_add_i32 m0, s66, 0x2000
	s_add_u32 s66, s70, 0xb0000
	v_lshl_add_u64 v[164:165], s[70:71], 0, v[152:153]
	s_addc_u32 s67, s71, 0
	s_add_i32 s76, vcc_lo, s4
	global_load_lds_dwordx4 v[164:165], off
	v_lshl_add_u64 v[202:203], s[66:67], 0, v[0:1]
	s_mov_b32 m0, s76
	v_lshl_add_u64 v[206:207], s[72:73], 0, v[150:151]
	v_lshl_add_u64 v[202:203], s[66:67], 0, v[152:153]
	s_add_i32 m0, s76, 0x2000
	s_nop 0
	v_lshl_add_u64 v[202:203], s[72:73], 0, v[148:149]
	s_mov_b32 m0, s5
	s_nop 0
	global_load_lds_dwordx4 v[202:203], off
	s_mov_b32 m0, s6
	s_nop 0
	global_load_lds_dwordx4 v[206:207], off
	s_waitcnt vmcnt(6)
	s_waitcnt lgkmcnt(0)
	s_barrier
; #define PG8_STAGE(bufoff, gbase, voff) do { _Pragma("unroll") for (int _i = 0; _i < 2; ++_i) \
;         __builtin_amdgcn_global_load_lds((const unsigned*)((const char*)(gbase) + (voff)[_i]), (LAS unsigned*)(lds + (bufoff) + ldsw + _i * 8192), 16, 0, 0); } while (0)
; #define PG8_LDA(dst, b, h) do { _Pragma("unroll") for (int m = 0; m < 4; ++m) _Pragma("unroll") for (int k = 0; k < 2; ++k) dst[m][k] = *(const LAS bf16x8*)(lds + PG8_SA(b, h) + aoff + m * 2048 + k * 1024); } while (0)
; #define PG8_LDB(dst, b, h) do { _Pragma("unroll") for (int n = 0; n < 2; ++n) _Pragma("unroll") for (int k = 0; k < 2; ++k) dst[n][k] = *(const LAS bf16x8*)(lds + PG8_SB(b, h) + boff + n * 2048 + k * 1024); } while (0)
; #define PG8_MMA(ai, bj, At, Bt) do { __builtin_amdgcn_s_setprio(1); _Pragma("unroll") for (int m = 0; m < 4; ++m) _Pragma("unroll") for (int n = 0; n < 2; ++n) _Pragma("unroll") for (int k = 0; k < 2; ++k) \
;         acc[ai][bj][m][n] = __builtin_amdgcn_mfma_f32_16x16x32_bf16(Bt[n][k], At[m][k], acc[ai][bj][m][n], 0, 0, 0); __builtin_amdgcn_s_setprio(0); } while (0)
; #define PG8_WAIT_V(n) asm volatile("s_waitcnt vmcnt(" #n ")" ::: "memory")
; #define PG8_WAIT_L(n) asm volatile("s_waitcnt lgkmcnt(" #n ")" ::: "memory")
; #define PG8_BAR __builtin_amdgcn_s_barrier()
; #define PG8_SCHED __builtin_amdgcn_sched_barrier(0)
; template <class Epi>
; __device__ __forceinline__ void gemm_phase(LAS unsigned char* lds, const int tid, const Gemm g, const StaticOrder& S, const Epi& E) {
;     ...
;             PG8_WAIT_V(8); PG8_WAIT_L(0); PG8_BAR; PG8_MMA(1, 0, At, B0); PG8_MMA(1, 1, At, B1); PG8_BAR; PG8_SCHED;
;             PG8_LDB(B0, 1, 0); PG8_LDB(B1, 1, 1); PG8_SCHED; PG8_LDA(At, 1, 0); PG8_STAGE(PG8_SA(0, 1), a2 + hstepA, voffA);
;             PG8_WAIT_V(8); PG8_WAIT_L(0); PG8_BAR; PG8_MMA(0, 0, At, B0); PG8_MMA(0, 1, At, B1); PG8_BAR; PG8_SCHED;
	s_setprio 1
	s_waitcnt lgkmcnt(0)
	v_mfma_f32_16x16x32_bf16 v[78:81], v[42:45], v[182:185], v[78:81]
	v_mfma_f32_16x16x32_bf16 v[74:77], v[66:69], v[182:185], v[74:77]
	v_mfma_f32_16x16x32_bf16 v[54:57], v[42:45], v[190:193], v[54:57]
	v_mfma_f32_16x16x32_bf16 v[50:53], v[66:69], v[190:193], v[50:53]
	v_mfma_f32_16x16x32_bf16 v[30:33], v[42:45], v[198:201], v[30:33]
	v_mfma_f32_16x16x32_bf16 v[26:29], v[66:69], v[198:201], v[26:29]
	v_mfma_f32_16x16x32_bf16 v[14:17], v[42:45], v[220:223], v[14:17]
	v_mfma_f32_16x16x32_bf16 v[10:13], v[66:69], v[220:223], v[10:13]
	v_mfma_f32_16x16x32_bf16 v[78:81], v[46:49], v[186:189], v[78:81]
	v_mfma_f32_16x16x32_bf16 v[74:77], v[70:73], v[186:189], v[74:77]
	v_mfma_f32_16x16x32_bf16 v[54:57], v[46:49], v[194:197], v[54:57]
	v_mfma_f32_16x16x32_bf16 v[50:53], v[70:73], v[194:197], v[50:53]
	v_mfma_f32_16x16x32_bf16 v[30:33], v[46:49], v[216:219], v[30:33]
	v_mfma_f32_16x16x32_bf16 v[26:29], v[70:73], v[216:219], v[26:29]
	v_mfma_f32_16x16x32_bf16 v[14:17], v[46:49], v[224:227], v[14:17]
	v_mfma_f32_16x16x32_bf16 v[10:13], v[70:73], v[224:227], v[10:13]
	s_setprio 0
	s_setprio 1
	v_mfma_f32_16x16x32_bf16 v[38:41], v[158:161], v[190:193], v[38:41]
	v_mfma_f32_16x16x32_bf16 v[34:37], v[174:177], v[190:193], v[34:37]
	v_mfma_f32_16x16x32_bf16 v[22:25], v[158:161], v[198:201], v[22:25]
	v_mfma_f32_16x16x32_bf16 v[18:21], v[174:177], v[198:201], v[18:21]
	v_mfma_f32_16x16x32_bf16 v[6:9], v[158:161], v[220:223], v[6:9]
	v_mfma_f32_16x16x32_bf16 v[2:5], v[174:177], v[220:223], v[2:5]
	v_mfma_f32_16x16x32_bf16 v[42:45], v[158:161], v[182:185], v[62:65]
	v_mfma_f32_16x16x32_bf16 v[46:49], v[174:177], v[182:185], v[58:61]
	v_mfma_f32_16x16x32_bf16 v[38:41], v[170:173], v[194:197], v[38:41]
	v_mfma_f32_16x16x32_bf16 v[34:37], v[178:181], v[194:197], v[34:37]
	v_mfma_f32_16x16x32_bf16 v[22:25], v[170:173], v[216:219], v[22:25]
	v_mfma_f32_16x16x32_bf16 v[18:21], v[178:181], v[216:219], v[18:21]
	v_mfma_f32_16x16x32_bf16 v[6:9], v[170:173], v[224:227], v[6:9]
	v_mfma_f32_16x16x32_bf16 v[2:5], v[178:181], v[224:227], v[2:5]
	v_mfma_f32_16x16x32_bf16 v[42:45], v[170:173], v[186:189], v[42:45]
	v_mfma_f32_16x16x32_bf16 v[46:49], v[178:181], v[186:189], v[46:49]
	s_setprio 0
	s_barrier
	s_add_i32 s76, 0, 0x18000
	s_add_i32 vcc_lo, 0, 0x1c000
	v_add_u32_e32 v70, s76, v212
	v_add_u32_e32 v178, vcc_lo, v212
	ds_read_b128 v[58:61], v70
	ds_read_b128 v[62:65], v70 offset:1024
	ds_read_b128 v[66:69], v70 offset:2048
	ds_read_b128 v[70:73], v70 offset:3072
	ds_read_b128 v[158:161], v178
	ds_read_b128 v[170:173], v178 offset:1024
	ds_read_b128 v[174:177], v178 offset:2048
	ds_read_b128 v[178:181], v178 offset:3072
	s_add_u32 s100, s70, 0xb0000
	s_addc_u32 s101, s71, 0
	v_lshl_add_u64 v[228:229], s[100:101], 0, v[0:1]
	s_add_i32 m0, s4, 0x14000
	s_nop 0
	global_load_lds_dwordx4 v[228:229], off
	v_lshl_add_u64 v[228:229], s[100:101], 0, v[152:153]
	s_add_i32 m0, s4, 0x16000
	s_nop 0
	global_load_lds_dwordx4 v[228:229], off
	s_add_u32 s66, s72, 0x160000
	s_addc_u32 s67, s73, 0
	s_mov_b32 m0, s7
	v_lshl_add_u64 v[228:229], s[66:67], 0, v[148:149]
	ds_read_b128 v[182:185], v214 offset:32768
	ds_read_b128 v[186:189], v214 offset:33792
	ds_read_b128 v[190:193], v214 offset:34816
	ds_read_b128 v[194:197], v214 offset:35840
	ds_read_b128 v[198:201], v214 offset:36864
	ds_read_b128 v[216:219], v214 offset:37888
	ds_read_b128 v[220:223], v214 offset:38912
	ds_read_b128 v[224:227], v214 offset:39936
	global_load_lds_dwordx4 v[228:229], off
	v_lshl_add_u64 v[228:229], s[66:67], 0, v[150:151]
	s_mov_b32 m0, s74
	s_nop 0
	global_load_lds_dwordx4 v[228:229], off
	s_waitcnt vmcnt(8)
	s_waitcnt lgkmcnt(0)
	s_barrier
	s_setprio 1
	s_waitcnt lgkmcnt(0)
	v_mfma_f32_16x16x32_bf16 v[142:145], v[58:61], v[182:185], v[142:145]
	v_mfma_f32_16x16x32_bf16 v[138:141], v[66:69], v[182:185], v[138:141]
	v_mfma_f32_16x16x32_bf16 v[126:129], v[58:61], v[190:193], v[126:129]
	v_mfma_f32_16x16x32_bf16 v[122:125], v[66:69], v[190:193], v[122:125]
	v_mfma_f32_16x16x32_bf16 v[110:113], v[58:61], v[198:201], v[110:113]
	v_mfma_f32_16x16x32_bf16 v[106:109], v[66:69], v[198:201], v[106:109]
	v_mfma_f32_16x16x32_bf16 v[94:97], v[58:61], v[220:223], v[94:97]
	v_mfma_f32_16x16x32_bf16 v[90:93], v[66:69], v[220:223], v[90:93]
	v_mfma_f32_16x16x32_bf16 v[142:145], v[62:65], v[186:189], v[142:145]
	v_mfma_f32_16x16x32_bf16 v[138:141], v[70:73], v[186:189], v[138:141]
	v_mfma_f32_16x16x32_bf16 v[126:129], v[62:65], v[194:197], v[126:129]
	v_mfma_f32_16x16x32_bf16 v[122:125], v[70:73], v[194:197], v[122:125]
	v_mfma_f32_16x16x32_bf16 v[110:113], v[62:65], v[216:219], v[110:113]
	v_mfma_f32_16x16x32_bf16 v[106:109], v[70:73], v[216:219], v[106:109]
	v_mfma_f32_16x16x32_bf16 v[94:97], v[62:65], v[224:227], v[94:97]
	v_mfma_f32_16x16x32_bf16 v[90:93], v[70:73], v[224:227], v[90:93]
	s_setprio 0
	s_setprio 1
	v_mfma_f32_16x16x32_bf16 v[134:137], v[158:161], v[182:185], v[134:137]
	v_mfma_f32_16x16x32_bf16 v[130:133], v[174:177], v[182:185], v[130:133]
	v_mfma_f32_16x16x32_bf16 v[118:121], v[158:161], v[190:193], v[118:121]
	v_mfma_f32_16x16x32_bf16 v[114:117], v[174:177], v[190:193], v[114:117]
	v_mfma_f32_16x16x32_bf16 v[102:105], v[158:161], v[198:201], v[102:105]
	v_mfma_f32_16x16x32_bf16 v[98:101], v[174:177], v[198:201], v[98:101]
	v_mfma_f32_16x16x32_bf16 v[86:89], v[158:161], v[220:223], v[86:89]
	v_mfma_f32_16x16x32_bf16 v[82:85], v[174:177], v[220:223], v[82:85]
	v_mfma_f32_16x16x32_bf16 v[134:137], v[170:173], v[186:189], v[134:137]
	v_mfma_f32_16x16x32_bf16 v[130:133], v[178:181], v[186:189], v[130:133]
	v_mfma_f32_16x16x32_bf16 v[118:121], v[170:173], v[194:197], v[118:121]
	v_mfma_f32_16x16x32_bf16 v[114:117], v[178:181], v[194:197], v[114:117]
	v_mfma_f32_16x16x32_bf16 v[102:105], v[170:173], v[216:219], v[102:105]
	v_mfma_f32_16x16x32_bf16 v[98:101], v[178:181], v[216:219], v[98:101]
	v_mfma_f32_16x16x32_bf16 v[86:89], v[170:173], v[224:227], v[86:89]
	v_mfma_f32_16x16x32_bf16 v[82:85], v[178:181], v[224:227], v[82:85]
	s_setprio 0
	s_barrier
; #define PG8_STAGE(bufoff, gbase, voff) do { _Pragma("unroll") for (int _i = 0; _i < 2; ++_i) \
;         __builtin_amdgcn_global_load_lds((const unsigned*)((const char*)(gbase) + (voff)[_i]), (LAS unsigned*)(lds + (bufoff) + ldsw + _i * 8192), 16, 0, 0); } while (0)
; #define PG8_LDA(dst, b, h) do { _Pragma("unroll") for (int m = 0; m < 4; ++m) _Pragma("unroll") for (int k = 0; k < 2; ++k) dst[m][k] = *(const LAS bf16x8*)(lds + PG8_SA(b, h) + aoff + m * 2048 + k * 1024); } while (0)
; #define PG8_MMA(ai, bj, At, Bt) do { __builtin_amdgcn_s_setprio(1); _Pragma("unroll") for (int m = 0; m < 4; ++m) _Pragma("unroll") for (int n = 0; n < 2; ++n) _Pragma("unroll") for (int k = 0; k < 2; ++k) \
;         acc[ai][bj][m][n] = __builtin_amdgcn_mfma_f32_16x16x32_bf16(Bt[n][k], At[m][k], acc[ai][bj][m][n], 0, 0, 0); __builtin_amdgcn_s_setprio(0); } while (0)
; #define PG8_WAIT_V(n) asm volatile("s_waitcnt vmcnt(" #n ")" ::: "memory")
; #define PG8_WAIT_L(n) asm volatile("s_waitcnt lgkmcnt(" #n ")" ::: "memory")
; #define PG8_BAR __builtin_amdgcn_s_barrier()
; #define PG8_SCHED __builtin_amdgcn_sched_barrier(0)
; template <class Epi>
; __device__ __forceinline__ void gemm_phase(LAS unsigned char* lds, const int tid, const Gemm g, const StaticOrder& S, const Epi& E) {
;     ...
;             PG8_LDA(At, 1, 1); PG8_STAGE(PG8_SB(1, 0), b3, voffB); PG8_STAGE(PG8_SB(1, 1), b3 + hstepB, voffB); PG8_STAGE(PG8_SA(1, 0), a3, voffA);
;             PG8_WAIT_V(8); PG8_WAIT_L(0); PG8_BAR; PG8_MMA(1, 0, At, B0); PG8_MMA(1, 1, At, B1); PG8_BAR; PG8_SCHED;
;         }
;         if (wr == 0) PG8_BAR;
	s_add_i32 s66, s76, s4
	v_lshl_add_u64 v[162:163], v[162:163], 0, s[36:37]
	s_mov_b32 m0, s66
	ds_read_b128 v[182:185], v214 offset:49152
	ds_read_b128 v[186:189], v214 offset:50176
	ds_read_b128 v[190:193], v214 offset:51200
	ds_read_b128 v[194:197], v214 offset:52224
	ds_read_b128 v[198:201], v214 offset:53248
	ds_read_b128 v[216:219], v214 offset:54272
	ds_read_b128 v[220:223], v214 offset:55296
	ds_read_b128 v[224:227], v214 offset:56320
	global_load_lds_dwordx4 v[162:163], off
	s_add_i32 m0, s66, 0x2000
	s_add_u32 s66, s70, 0xb0080
	v_lshl_add_u64 v[162:163], v[164:165], 0, s[36:37]
	s_addc_u32 s67, s71, 0
	s_add_i32 s70, vcc_lo, s4
	global_load_lds_dwordx4 v[162:163], off
	v_lshl_add_u64 v[162:163], s[66:67], 0, v[0:1]
	s_mov_b32 m0, s70
	s_nop 0
	global_load_lds_dwordx4 v[162:163], off
	v_lshl_add_u64 v[162:163], s[66:67], 0, v[152:153]
	s_add_i32 m0, s70, 0x2000
	s_nop 0
	global_load_lds_dwordx4 v[162:163], off
	v_lshl_add_u64 v[162:163], v[202:203], 0, s[36:37]
	s_mov_b32 m0, s77
	s_nop 0
	global_load_lds_dwordx4 v[162:163], off
	v_lshl_add_u64 v[162:163], v[206:207], 0, s[36:37]
	s_mov_b32 m0, s79
	s_nop 0
	global_load_lds_dwordx4 v[162:163], off
	s_waitcnt vmcnt(8)
	s_waitcnt lgkmcnt(0)
	s_barrier
	s_setprio 1
	s_waitcnt lgkmcnt(0)
	v_mfma_f32_16x16x32_bf16 v[78:81], v[58:61], v[182:185], v[78:81]
	v_mfma_f32_16x16x32_bf16 v[74:77], v[66:69], v[182:185], v[74:77]
	v_mfma_f32_16x16x32_bf16 v[54:57], v[58:61], v[190:193], v[54:57]
	v_mfma_f32_16x16x32_bf16 v[50:53], v[66:69], v[190:193], v[50:53]
	v_mfma_f32_16x16x32_bf16 v[30:33], v[58:61], v[198:201], v[30:33]
	v_mfma_f32_16x16x32_bf16 v[26:29], v[66:69], v[198:201], v[26:29]
	v_mfma_f32_16x16x32_bf16 v[14:17], v[58:61], v[220:223], v[14:17]
	v_mfma_f32_16x16x32_bf16 v[10:13], v[66:69], v[220:223], v[10:13]
	v_mfma_f32_16x16x32_bf16 v[78:81], v[62:65], v[186:189], v[78:81]
	v_mfma_f32_16x16x32_bf16 v[74:77], v[70:73], v[186:189], v[74:77]
	v_mfma_f32_16x16x32_bf16 v[54:57], v[62:65], v[194:197], v[54:57]
	v_mfma_f32_16x16x32_bf16 v[50:53], v[70:73], v[194:197], v[50:53]
	v_mfma_f32_16x16x32_bf16 v[30:33], v[62:65], v[216:219], v[30:33]
	v_mfma_f32_16x16x32_bf16 v[26:29], v[70:73], v[216:219], v[26:29]
	v_mfma_f32_16x16x32_bf16 v[14:17], v[62:65], v[224:227], v[14:17]
	v_mfma_f32_16x16x32_bf16 v[10:13], v[70:73], v[224:227], v[10:13]
	s_setprio 0
	s_setprio 1
	v_mfma_f32_16x16x32_bf16 v[42:45], v[158:161], v[182:185], v[42:45]
	v_mfma_f32_16x16x32_bf16 v[62:65], v[170:173], v[186:189], v[42:45]
	v_mfma_f32_16x16x32_bf16 v[42:45], v[174:177], v[182:185], v[46:49]
	v_mfma_f32_16x16x32_bf16 v[38:41], v[158:161], v[190:193], v[38:41]
	v_mfma_f32_16x16x32_bf16 v[34:37], v[174:177], v[190:193], v[34:37]
	v_mfma_f32_16x16x32_bf16 v[22:25], v[158:161], v[198:201], v[22:25]
	v_mfma_f32_16x16x32_bf16 v[18:21], v[174:177], v[198:201], v[18:21]
	v_mfma_f32_16x16x32_bf16 v[6:9], v[158:161], v[220:223], v[6:9]
	v_mfma_f32_16x16x32_bf16 v[2:5], v[174:177], v[220:223], v[2:5]
	v_mfma_f32_16x16x32_bf16 v[58:61], v[178:181], v[186:189], v[42:45]
	v_mfma_f32_16x16x32_bf16 v[38:41], v[170:173], v[194:197], v[38:41]
	v_mfma_f32_16x16x32_bf16 v[34:37], v[178:181], v[194:197], v[34:37]
	v_mfma_f32_16x16x32_bf16 v[22:25], v[170:173], v[216:219], v[22:25]
	v_mfma_f32_16x16x32_bf16 v[18:21], v[178:181], v[216:219], v[18:21]
	v_mfma_f32_16x16x32_bf16 v[6:9], v[170:173], v[224:227], v[6:9]
	v_mfma_f32_16x16x32_bf16 v[2:5], v[178:181], v[224:227], v[2:5]
	s_setprio 0
	s_barrier
	s_add_i32 s93, s93, 2
	s_add_u32 s11, s11, 0x100
	s_addc_u32 s28, s28, 0
	s_cmp_gt_u32 s93, 41
	s_mov_b64 s[66:67], s[68:69]
	s_cbranch_scc0 .LBB0_2303
	s_and_b64 vcc, exec, s[26:27]
	s_cbranch_vccz .LBB0_2306
	s_barrier
